# v38 + sc1 (write-through, not retained in L2) on the mLSTM phase's 16-byte h stores
# baseline (speedup 1.0000x reference)
.LBB0_289:
	s_min_u32 s18, s20, 1
	s_lshl_b32 s26, s18, 7
	s_and_b32 s18, s20, 1
	s_mov_b32 s19, s20
	s_mul_i32 s20, s18, 0x5000
	s_add_i32 s25, s20, 0
	s_lshl_b32 s20, s18, 11
	s_add_i32 s20, s20, 0
	s_add_i32 s36, s20, 0x25a00
	s_lshl_b32 s20, s18, 4
	s_add_i32 s20, s20, 0
	s_add_i32 s25, s25, 0x12000
	s_add_i32 s37, s20, 0x26a00
	s_add_i32 s20, s19, 1
	s_mul_i32 s27, s18, 0x9000
	s_cmp_lt_u32 s20, s79
	s_cselect_b32 s38, s20, s19
	s_add_i32 s19, s27, 0
	v_lshlrev_b32_e32 v136, 1, v80
	s_waitcnt vmcnt(4)
	v_mov_b64_e32 v[56:57], v[16:17]
	s_waitcnt vmcnt(3)
	v_mov_b64_e32 v[60:61], v[20:21]
	s_waitcnt vmcnt(2)
	v_mov_b64_e32 v[110:111], v[24:25]
	v_mov_b32_e32 v2, s36
	v_lshl_add_u32 v3, v92, 2, s36
	v_add_u32_e32 v62, s19, v136
	v_mov_b64_e32 v[54:55], v[14:15]
	v_mov_b64_e32 v[58:59], v[18:19]
	v_mov_b64_e32 v[108:109], v[22:23]
	s_waitcnt lgkmcnt(0)
	s_barrier
	ds_read2st64_b32 v[86:87], v3 offset0:3 offset1:5
	v_mov_b32_e32 v3, s37
	v_add_u32_e32 v63, v62, v79
	ds_read_b32 v137, v2 offset:1020
	ds_read_b32 v200, v3
	ds_read_b128 v[14:17], v63
	ds_read_b128 v[18:21], v63 offset:4608
	ds_read_b128 v[22:25], v63 offset:9216
	v_add_u32_e32 v2, v62, v104
	ds_read_b128 v[62:65], v63 offset:13824
	ds_read_b128 v[66:69], v2
	v_subrev_u32_e32 v4, s26, v107
	v_add_u32_e32 v188, s26, v105
	s_mul_i32 s26, s18, 0x4a00
	s_add_i32 s26, s26, 0
	s_add_i32 s26, s26, 0x1c000
	v_add3_u32 v2, s19, v79, v136
	ds_read_b128 v[70:73], v2 offset:64
	ds_read_b128 v[74:77], v2 offset:4672
	ds_read_b128 v[88:91], v2 offset:9280
	ds_read_b128 v[112:115], v2 offset:13888
	v_add3_u32 v3, s19, v104, v136
	ds_read_b128 v[116:119], v3 offset:64
	s_waitcnt lgkmcnt(9)
	v_mfma_f32_16x16x32_bf16 v[14:17], v[14:17], v[10:13], 0
	s_waitcnt lgkmcnt(8)
	v_mfma_f32_16x16x32_bf16 v[18:21], v[18:21], v[10:13], 0
	s_waitcnt lgkmcnt(7)
	v_mfma_f32_16x16x32_bf16 v[22:25], v[22:25], v[10:13], 0
	s_waitcnt lgkmcnt(6)
	v_mfma_f32_16x16x32_bf16 v[62:65], v[62:65], v[10:13], 0
	s_waitcnt lgkmcnt(5)
	v_mfma_f32_16x16x32_bf16 v[66:69], v[66:69], v[10:13], 0
	ds_read_b128 v[120:123], v2 offset:128
	ds_read_b128 v[124:127], v2 offset:4736
	ds_read_b128 v[128:131], v2 offset:9344
	ds_read_b128 v[132:135], v2 offset:13952
	ds_read_b128 v[140:143], v3 offset:128
	s_waitcnt lgkmcnt(9)
	v_mfma_f32_16x16x32_bf16 v[14:17], v[70:73], v[54:57], v[14:17]
	s_waitcnt lgkmcnt(8)
	v_mfma_f32_16x16x32_bf16 v[18:21], v[74:77], v[54:57], v[18:21]
	s_waitcnt lgkmcnt(7)
	v_mfma_f32_16x16x32_bf16 v[22:25], v[88:91], v[54:57], v[22:25]
	s_waitcnt lgkmcnt(6)
	v_mfma_f32_16x16x32_bf16 v[62:65], v[112:115], v[54:57], v[62:65]
	s_waitcnt lgkmcnt(5)
	v_mfma_f32_16x16x32_bf16 v[66:69], v[116:119], v[54:57], v[66:69]
	ds_read_b128 v[70:73], v2 offset:192
	ds_read_b128 v[74:77], v2 offset:4800
	ds_read_b128 v[88:91], v2 offset:9408
	ds_read_b128 v[112:115], v2 offset:14016
	ds_read_b128 v[116:119], v3 offset:192
	s_waitcnt lgkmcnt(9)
	v_mfma_f32_16x16x32_bf16 v[14:17], v[120:123], v[58:61], v[14:17]
	s_waitcnt lgkmcnt(8)
	v_mfma_f32_16x16x32_bf16 v[18:21], v[124:127], v[58:61], v[18:21]
	s_waitcnt lgkmcnt(7)
	v_mfma_f32_16x16x32_bf16 v[22:25], v[128:131], v[58:61], v[22:25]
	s_waitcnt lgkmcnt(6)
	v_mfma_f32_16x16x32_bf16 v[62:65], v[132:135], v[58:61], v[62:65]
	s_waitcnt lgkmcnt(5)
	v_mfma_f32_16x16x32_bf16 v[66:69], v[140:143], v[58:61], v[66:69]
	v_add_u32_e32 v2, s26, v136
	v_add_u32_e32 v3, v2, v79
	ds_read_b128 v[120:123], v3
	ds_read_b128 v[124:127], v3 offset:4608
	ds_read_b128 v[128:131], v3 offset:9216
	ds_read_b128 v[132:135], v3 offset:13824
	v_add_u32_e32 v2, v2, v104
	ds_read_b128 v[140:143], v2
	s_waitcnt lgkmcnt(9)
	v_mfma_f32_16x16x32_bf16 v[144:147], v[70:73], v[108:111], v[14:17]
	s_waitcnt lgkmcnt(8)
	v_mfma_f32_16x16x32_bf16 v[148:151], v[74:77], v[108:111], v[18:21]
	s_waitcnt lgkmcnt(7)
	v_mfma_f32_16x16x32_bf16 v[152:155], v[88:91], v[108:111], v[22:25]
	s_waitcnt lgkmcnt(6)
	v_mfma_f32_16x16x32_bf16 v[74:77], v[112:115], v[108:111], v[62:65]
	s_waitcnt lgkmcnt(5)
	v_mfma_f32_16x16x32_bf16 v[66:69], v[116:119], v[108:111], v[66:69]
	v_add3_u32 v180, s26, v79, v136
	ds_read_b128 v[18:21], v180 offset:64
	ds_read_b128 v[22:25], v180 offset:4672
	ds_read_b128 v[62:65], v180 offset:9280
	ds_read_b128 v[70:73], v180 offset:13888
	v_add3_u32 v136, s26, v104, v136
	ds_read_b128 v[88:91], v136 offset:64
	v_lshl_or_b32 v2, s38, 7, v93
	v_xad_u32 v3, v2, -1, s78
	v_cndmask_b32_e64 v2, v3, v2, s[4:5]
	v_add_u32_e32 v2, s48, v2
	v_mad_i64_i32 v[2:3], s[26:27], v2, s86, v[82:83]
	s_waitcnt lgkmcnt(9)
	v_mfma_f32_16x16x32_bf16 v[112:115], v[120:123], v[10:13], 0
	s_waitcnt lgkmcnt(8)
	v_mfma_f32_16x16x32_bf16 v[116:119], v[124:127], v[10:13], 0
	s_waitcnt lgkmcnt(7)
	v_mfma_f32_16x16x32_bf16 v[120:123], v[128:131], v[10:13], 0
	s_waitcnt lgkmcnt(6)
	v_mfma_f32_16x16x32_bf16 v[124:127], v[132:135], v[10:13], 0
	s_waitcnt lgkmcnt(5)
	v_mfma_f32_16x16x32_bf16 v[128:131], v[140:143], v[10:13], 0
	global_load_dwordx4 v[10:13], v[2:3], off
	global_load_dwordx4 v[14:17], v[2:3], off offset:64
	ds_read_b128 v[132:135], v180 offset:128
	ds_read_b128 v[140:143], v180 offset:4736
	ds_read_b128 v[168:171], v180 offset:9344
	ds_read_b128 v[172:175], v180 offset:13952
	ds_read_b128 v[176:179], v136 offset:128
	s_waitcnt lgkmcnt(9)
	v_mfma_f32_16x16x32_bf16 v[112:115], v[18:21], v[54:57], v[112:115]
	s_waitcnt lgkmcnt(8)
	v_mfma_f32_16x16x32_bf16 v[116:119], v[22:25], v[54:57], v[116:119]
	global_load_dwordx4 v[18:21], v[2:3], off offset:128
	global_load_dwordx4 v[22:25], v[2:3], off offset:192
	s_waitcnt lgkmcnt(7)
	v_mfma_f32_16x16x32_bf16 v[62:65], v[62:65], v[54:57], v[120:123]
	s_waitcnt lgkmcnt(6)
	v_mfma_f32_16x16x32_bf16 v[70:73], v[70:73], v[54:57], v[124:127]
	s_waitcnt lgkmcnt(5)
	v_mfma_f32_16x16x32_bf16 v[54:57], v[88:91], v[54:57], v[128:131]
	ds_read_b128 v[120:123], v180 offset:192
	ds_read_b128 v[124:127], v180 offset:4800
	s_nop 0
	ds_read_b128 v[128:131], v180 offset:9408
	ds_read_b128 v[180:183], v180 offset:14016
	ds_read_b128 v[184:187], v136 offset:192
	v_cndmask_b32_e64 v2, v188, v4, s[4:5]
	v_ashrrev_i32_e32 v3, 31, v2
	v_lshl_add_u64 v[2:3], s[0:1], 0, v[2:3]
	v_lshlrev_b64 v[2:3], 11, v[2:3]
	v_lshl_add_u64 v[2:3], v[84:85], 0, v[2:3]
	s_waitcnt lgkmcnt(9)
	v_mfma_f32_16x16x32_bf16 v[112:115], v[132:135], v[58:61], v[112:115]
	global_store_dwordx4 v[2:3], v[50:53], off sc1
	global_store_dwordx4 v[2:3], v[46:49], off offset:64 sc1
	s_waitcnt lgkmcnt(8)
	v_mfma_f32_16x16x32_bf16 v[116:119], v[140:143], v[58:61], v[116:119]
	s_waitcnt lgkmcnt(7)
	v_mfma_f32_16x16x32_bf16 v[132:135], v[168:171], v[58:61], v[62:65]
	s_waitcnt lgkmcnt(6)
	v_mfma_f32_16x16x32_bf16 v[140:143], v[172:175], v[58:61], v[70:73]
	s_waitcnt lgkmcnt(5)
	v_mfma_f32_16x16x32_bf16 v[168:171], v[176:179], v[58:61], v[54:57]
	v_add3_u32 v2, s25, v94, v95
	ds_read_b64_tr_b16 v[50:51], v2
	ds_read_b64_tr_b16 v[46:47], v2 offset:32
	ds_read_b64_tr_b16 v[54:55], v2 offset:64
	ds_read_b64_tr_b16 v[58:59], v2 offset:96
	ds_read_b64_tr_b16 v[52:53], v2 offset:2560
	ds_read_b64_tr_b16 v[48:49], v2 offset:2592
	ds_read_b64_tr_b16 v[56:57], v2 offset:2624
	ds_read_b64_tr_b16 v[60:61], v2 offset:2656
	v_add3_u32 v2, s19, v96, v106
	v_lshl_add_u32 v201, v78, 2, s36
	ds_read_b64_tr_b16 v[90:91], v2 offset:224
	ds_read_b64_tr_b16 v[88:89], v2 offset:4832
	ds_read_b128 v[62:65], v201 offset:1600
	ds_read_b128 v[172:175], v201
	ds_read_b128 v[176:179], v201 offset:64
	ds_read_b128 v[188:191], v201 offset:128
	ds_read_b128 v[192:195], v201 offset:192
	ds_read_b128 v[70:73], v201 offset:1536
	ds_read_b128 v[196:199], v201 offset:256
	s_waitcnt lgkmcnt(14)
	v_mfma_f32_16x16x32_bf16 v[112:115], v[120:123], v[108:111], v[112:115]
	v_mfma_f32_16x16x32_bf16 v[116:119], v[124:127], v[108:111], v[116:119]
	v_mfma_f32_16x16x32_bf16 v[120:123], v[128:131], v[108:111], v[132:135]
	v_mfma_f32_16x16x32_bf16 v[124:127], v[180:183], v[108:111], v[140:143]
	v_mfma_f32_16x16x32_bf16 v[108:111], v[184:187], v[108:111], v[168:171]
	v_sub_f32_e32 v2, v200, v86
	v_mul_f32_e32 v2, 0x3fb8aa3b, v2
	v_sub_f32_e32 v3, v200, v137
	s_waitcnt lgkmcnt(2)
	v_fmamk_f32 v137, v86, 0xbfb8aa3b, v192
	v_fmamk_f32 v140, v86, 0xbfb8aa3b, v193
	v_exp_f32_e32 v2, v2
	v_exp_f32_e32 v137, v137
	v_exp_f32_e32 v140, v140
	v_mul_f32_e32 v3, 0x3fb8aa3b, v3
	v_fmamk_f32 v141, v86, 0xbfb8aa3b, v194
	v_exp_f32_e32 v4, v3
	v_exp_f32_e32 v141, v141
	v_pk_mul_f32 v[114:115], v[2:3], v[114:115] op_sel_hi:[0,1]
	v_pk_mul_f32 v[112:113], v[2:3], v[112:113] op_sel_hi:[0,1]
	v_pk_mul_f32 v[118:119], v[2:3], v[118:119] op_sel_hi:[0,1]
	v_pk_mul_f32 v[116:117], v[2:3], v[116:117] op_sel_hi:[0,1]
	v_pk_mul_f32 v[122:123], v[2:3], v[122:123] op_sel_hi:[0,1]
	v_pk_mul_f32 v[120:121], v[2:3], v[120:121] op_sel_hi:[0,1]
	v_pk_mul_f32 v[126:127], v[2:3], v[126:127] op_sel_hi:[0,1]
	v_pk_mul_f32 v[124:125], v[2:3], v[124:125] op_sel_hi:[0,1]
	v_pk_mul_f32 v[110:111], v[2:3], v[110:111] op_sel_hi:[0,1]
	v_pk_mul_f32 v[108:109], v[2:3], v[108:109] op_sel_hi:[0,1]
	v_fmamk_f32 v2, v86, 0xbfb8aa3b, v172
	v_fmamk_f32 v3, v86, 0xbfb8aa3b, v173
	v_fmac_f32_e32 v195, 0xbfb8aa3b, v86
	v_mul_f32_e32 v137, v74, v137
	v_mul_f32_e32 v140, v75, v140
	s_waitcnt lgkmcnt(0)
	v_fmamk_f32 v74, v86, 0xbfb8aa3b, v196
	v_fmamk_f32 v75, v86, 0xbfb8aa3b, v197
	v_exp_f32_e32 v2, v2
	v_exp_f32_e32 v3, v3
	v_exp_f32_e32 v142, v195
	v_exp_f32_e32 v74, v74
	v_exp_f32_e32 v75, v75
	v_pk_mul_f32 v[44:45], v[44:45], v[4:5] op_sel_hi:[1,0]
	v_pk_mul_f32 v[42:43], v[42:43], v[4:5] op_sel_hi:[1,0]
	v_pk_mul_f32 v[40:41], v[40:41], v[4:5] op_sel_hi:[1,0]
	v_pk_mul_f32 v[38:39], v[38:39], v[4:5] op_sel_hi:[1,0]
	v_pk_mul_f32 v[36:37], v[36:37], v[4:5] op_sel_hi:[1,0]
	v_pk_mul_f32 v[34:35], v[34:35], v[4:5] op_sel_hi:[1,0]
	v_pk_mul_f32 v[32:33], v[32:33], v[4:5] op_sel_hi:[1,0]
	v_pk_mul_f32 v[30:31], v[30:31], v[4:5] op_sel_hi:[1,0]
	v_pk_mul_f32 v[28:29], v[28:29], v[4:5] op_sel_hi:[1,0]
	v_pk_mul_f32 v[26:27], v[26:27], v[4:5] op_sel_hi:[1,0]
	v_fmamk_f32 v4, v86, 0xbfb8aa3b, v174
	v_fmac_f32_e32 v175, 0xbfb8aa3b, v86
	v_mul_f32_e32 v141, v76, v141
	v_fmamk_f32 v76, v86, 0xbfb8aa3b, v198
	v_fmac_f32_e32 v199, 0xbfb8aa3b, v86
	v_exp_f32_e32 v4, v4
	v_exp_f32_e32 v128, v175
	v_fmamk_f32 v129, v86, 0xbfb8aa3b, v176
	v_fmamk_f32 v130, v86, 0xbfb8aa3b, v177
	v_fmamk_f32 v131, v86, 0xbfb8aa3b, v178
	v_fmac_f32_e32 v179, 0xbfb8aa3b, v86
	v_fmamk_f32 v133, v86, 0xbfb8aa3b, v188
	v_fmamk_f32 v134, v86, 0xbfb8aa3b, v189
	v_fmamk_f32 v135, v86, 0xbfb8aa3b, v190
	v_fmac_f32_e32 v191, 0xbfb8aa3b, v86
	v_exp_f32_e32 v76, v76
	v_exp_f32_e32 v86, v199
	v_mul_f32_e32 v2, v144, v2
	v_mul_f32_e32 v3, v145, v3
	v_exp_f32_e32 v129, v129
	v_exp_f32_e32 v130, v130
	v_exp_f32_e32 v131, v131
	v_exp_f32_e32 v132, v179
	v_exp_f32_e32 v133, v133
	v_exp_f32_e32 v134, v134
	v_exp_f32_e32 v135, v135
	v_exp_f32_e32 v136, v191
	v_mul_f32_e32 v77, v77, v142
	v_mul_f32_e32 v142, v66, v74
	v_mul_f32_e32 v143, v67, v75
	v_cvt_pk_bf16_f32 v66, v2, v3
	v_cvt_pk_bf16_f32 v2, v142, s0
	v_cvt_pk_bf16_f32 v3, v143, s0
	v_mul_f32_e32 v4, v146, v4
	v_mul_f32_e32 v128, v147, v128
	v_mul_f32_e32 v144, v68, v76
	v_mul_f32_e32 v86, v69, v86
	v_cndmask_b32_e64 v2, v2, 0, s[6:7]
	v_cndmask_b32_e64 v3, 0, v3, s[8:9]
	v_cvt_pk_bf16_f32 v67, v4, v128
	v_perm_b32 v2, v3, v2, s89
	v_cvt_pk_bf16_f32 v3, v144, s0
	v_cvt_pk_bf16_f32 v4, v86, s0
	v_mul_f32_e32 v129, v148, v129
	v_mul_f32_e32 v130, v149, v130
	v_mul_f32_e32 v131, v150, v131
	v_mul_f32_e32 v132, v151, v132
	v_mul_f32_e32 v133, v152, v133
	v_mul_f32_e32 v134, v153, v134
	v_mul_f32_e32 v135, v154, v135
	v_mul_f32_e32 v136, v155, v136
	v_cndmask_b32_e64 v3, v3, 0, s[10:11]
	v_cndmask_b32_e64 v4, v4, 0, s[12:13]
	v_cvt_pk_bf16_f32 v68, v129, v130
	v_cvt_pk_bf16_f32 v69, v131, v132
	v_cvt_pk_bf16_f32 v74, v133, v134
	v_cvt_pk_bf16_f32 v75, v135, v136
	v_cvt_pk_bf16_f32 v76, v137, v140
	v_cvt_pk_bf16_f32 v77, v141, v77
	v_perm_b32 v3, v4, v3, s89
	v_mov_b32_e32 v4, v5
	v_add3_u32 v86, s25, v97, v106
	ds_read_b64_tr_b16 v[128:129], v86
	ds_read_b64_tr_b16 v[132:133], v86 offset:32
	ds_read_b64_tr_b16 v[140:141], v86 offset:64
	ds_read_b64_tr_b16 v[144:145], v86 offset:96
	ds_read_b64_tr_b16 v[130:131], v86 offset:2560
	ds_read_b64_tr_b16 v[134:135], v86 offset:2592
	ds_read_b64_tr_b16 v[142:143], v86 offset:2624
	ds_read_b64_tr_b16 v[146:147], v86 offset:2656
	v_add3_u32 v86, s19, v98, v106
	ds_read_b64_tr_b16 v[136:137], v86 offset:224
	ds_read_b64_tr_b16 v[176:177], v86 offset:4832
	ds_read_b128 v[148:151], v201 offset:1664
	ds_read_b128 v[152:155], v201 offset:1728
	v_lshlrev_b32_e32 v86, 16, v90
	v_mul_f32_e32 v70, v70, v86
	v_and_b32_e32 v86, 0xffff0000, v90
	v_mul_f32_e32 v71, v71, v86
	v_cvt_pk_bf16_f32 v70, v70, v71
	v_lshlrev_b32_e32 v71, 16, v91
	v_mul_f32_e32 v71, v72, v71
	v_and_b32_e32 v72, 0xffff0000, v91
	v_mul_f32_e32 v72, v73, v72
	v_cvt_pk_bf16_f32 v71, v71, v72
	v_lshlrev_b32_e32 v72, 16, v88
	v_mul_f32_e32 v62, v62, v72
	v_and_b32_e32 v72, 0xffff0000, v88
	v_mul_f32_e32 v63, v63, v72
	v_cvt_pk_bf16_f32 v72, v62, v63
	v_lshlrev_b32_e32 v62, 16, v89
	v_and_b32_e32 v63, 0xffff0000, v89
	v_mul_f32_e32 v62, v64, v62
	v_mul_f32_e32 v63, v65, v63
	v_cvt_pk_bf16_f32 v73, v62, v63
	v_mfma_f32_16x16x32_bf16 v[112:115], v[50:53], v[66:69], v[112:115]
	s_nop 0
	v_mfma_f32_16x16x32_bf16 v[42:45], v[70:73], v[50:53], v[42:45]
	v_mfma_f32_16x16x32_bf16 v[38:41], v[70:73], v[46:49], v[38:41]
	v_mfma_f32_16x16x32_bf16 v[34:37], v[70:73], v[54:57], v[34:37]
	v_mfma_f32_16x16x32_bf16 v[30:33], v[70:73], v[58:61], v[30:33]
	v_mfma_f32_16x16x32_bf16 v[26:29], v[70:73], v[6:9], v[26:29]
	v_mfma_f32_16x16x32_bf16 v[116:119], v[46:49], v[66:69], v[116:119]
	v_mfma_f32_16x16x32_bf16 v[120:123], v[54:57], v[66:69], v[120:123]
	v_mfma_f32_16x16x32_bf16 v[124:127], v[58:61], v[66:69], v[124:127]
	v_mfma_f32_16x16x32_bf16 v[66:69], v[6:9], v[66:69], v[108:111]
	v_add3_u32 v46, s25, v99, v106
	ds_read_b64_tr_b16 v[62:63], v46
	ds_read_b64_tr_b16 v[70:71], v46 offset:32
	ds_read_b64_tr_b16 v[88:89], v46 offset:64
	ds_read_b64_tr_b16 v[108:109], v46 offset:96
	ds_read_b64_tr_b16 v[64:65], v46 offset:2560
	ds_read_b64_tr_b16 v[72:73], v46 offset:2592
	ds_read_b64_tr_b16 v[90:91], v46 offset:2624
	ds_read_b64_tr_b16 v[110:111], v46 offset:2656
	v_add3_u32 v46, s19, v100, v106
	ds_read_b64_tr_b16 v[178:179], v46 offset:224
	ds_read_b64_tr_b16 v[180:181], v46 offset:4832
	ds_read_b128 v[168:171], v201 offset:1792
	ds_read_b128 v[172:175], v201 offset:1856
	s_waitcnt lgkmcnt(14)
	v_lshlrev_b32_e32 v50, 16, v136
	v_and_b32_e32 v51, 0xffff0000, v136
	s_waitcnt lgkmcnt(13)
	v_mul_f32_e32 v50, v148, v50
	v_mul_f32_e32 v51, v149, v51
	v_cvt_pk_bf16_f32 v50, v50, v51
	v_lshlrev_b32_e32 v51, 16, v137
	v_and_b32_e32 v52, 0xffff0000, v137
	v_mul_f32_e32 v51, v150, v51
	v_mul_f32_e32 v52, v151, v52
	v_cvt_pk_bf16_f32 v51, v51, v52
	v_lshlrev_b32_e32 v52, 16, v176
	v_and_b32_e32 v53, 0xffff0000, v176
	s_waitcnt lgkmcnt(12)
	v_mul_f32_e32 v52, v152, v52
	v_mul_f32_e32 v53, v153, v53
	v_cvt_pk_bf16_f32 v52, v52, v53
	v_lshlrev_b32_e32 v53, 16, v177
	v_and_b32_e32 v58, 0xffff0000, v177
	v_mul_f32_e32 v53, v154, v53
	v_mul_f32_e32 v58, v155, v58
	v_cvt_pk_bf16_f32 v53, v53, v58
	v_mfma_f32_16x16x32_bf16 v[46:49], v[128:131], v[74:77], v[112:115]
	v_mfma_f32_16x16x32_bf16 v[54:57], v[132:135], v[74:77], v[116:119]
	v_mfma_f32_16x16x32_bf16 v[42:45], v[50:53], v[128:131], v[42:45]
	v_mfma_f32_16x16x32_bf16 v[38:41], v[50:53], v[132:135], v[38:41]
	v_mfma_f32_16x16x32_bf16 v[34:37], v[50:53], v[140:143], v[34:37]
	v_mfma_f32_16x16x32_bf16 v[30:33], v[50:53], v[144:147], v[30:33]
	v_mfma_f32_16x16x32_bf16 v[26:29], v[50:53], v[6:9], v[26:29]
	v_mfma_f32_16x16x32_bf16 v[112:115], v[140:143], v[74:77], v[120:123]
	v_mfma_f32_16x16x32_bf16 v[116:119], v[144:147], v[74:77], v[124:127]
	v_mfma_f32_16x16x32_bf16 v[66:69], v[6:9], v[74:77], v[66:69]
	v_add3_u32 v50, s25, v101, v106
	ds_read_b64_tr_b16 v[74:75], v50
	ds_read_b64_tr_b16 v[120:121], v50 offset:32
	ds_read_b64_tr_b16 v[124:125], v50 offset:64
	ds_read_b64_tr_b16 v[128:129], v50 offset:96
	ds_read_b64_tr_b16 v[76:77], v50 offset:2560
	ds_read_b64_tr_b16 v[122:123], v50 offset:2592
	ds_read_b64_tr_b16 v[126:127], v50 offset:2624
	ds_read_b64_tr_b16 v[130:131], v50 offset:2656
	v_add3_u32 v50, s19, v102, v106
	ds_read_b64_tr_b16 v[136:137], v50 offset:224
	ds_read_b64_tr_b16 v[144:145], v50 offset:4832
	ds_read_b128 v[132:135], v201 offset:1920
	ds_read_b128 v[140:143], v201 offset:1984
	s_waitcnt lgkmcnt(14)
	v_mfma_f32_16x16x32_bf16 v[50:53], v[62:65], v[2:5], v[46:49]
	v_mfma_f32_16x16x32_bf16 v[58:61], v[70:73], v[2:5], v[54:57]
	v_mfma_f32_16x16x32_bf16 v[46:49], v[88:91], v[2:5], v[112:115]
	v_mfma_f32_16x16x32_bf16 v[54:57], v[108:111], v[2:5], v[116:119]
	v_mfma_f32_16x16x32_bf16 v[66:69], v[6:9], v[2:5], v[66:69]
	v_lshlrev_b32_e32 v2, 16, v178
	v_and_b32_e32 v3, 0xffff0000, v178
	s_waitcnt lgkmcnt(13)
	v_mul_f32_e32 v2, v168, v2
	v_mul_f32_e32 v3, v169, v3
	v_cvt_pk_bf16_f32 v112, v2, v3
	v_lshlrev_b32_e32 v2, 16, v179
	v_and_b32_e32 v3, 0xffff0000, v179
	v_mul_f32_e32 v2, v170, v2
	v_mul_f32_e32 v3, v171, v3
	v_cvt_pk_bf16_f32 v113, v2, v3
	v_lshlrev_b32_e32 v2, 16, v180
	v_and_b32_e32 v3, 0xffff0000, v180
	s_waitcnt lgkmcnt(12)
	v_mul_f32_e32 v2, v172, v2
	v_mul_f32_e32 v3, v173, v3
	v_cvt_pk_bf16_f32 v114, v2, v3
	v_lshlrev_b32_e32 v2, 16, v181
	v_and_b32_e32 v3, 0xffff0000, v181
	v_mul_f32_e32 v2, v174, v2
	v_mul_f32_e32 v3, v175, v3
	v_cvt_pk_bf16_f32 v115, v2, v3
	s_nop 1
	v_mfma_f32_16x16x32_bf16 v[42:45], v[112:115], v[62:65], v[42:45]
	v_mfma_f32_16x16x32_bf16 v[38:41], v[112:115], v[70:73], v[38:41]
	v_mfma_f32_16x16x32_bf16 v[34:37], v[112:115], v[88:91], v[34:37]
	v_mfma_f32_16x16x32_bf16 v[30:33], v[112:115], v[108:111], v[30:33]
	v_mfma_f32_16x16x32_bf16 v[26:29], v[112:115], v[6:9], v[26:29]
	s_waitcnt lgkmcnt(3)
	v_lshlrev_b32_e32 v2, 16, v136
	v_and_b32_e32 v3, 0xffff0000, v136
	s_waitcnt lgkmcnt(1)
	v_mul_f32_e32 v2, v132, v2
	v_mul_f32_e32 v3, v133, v3
	v_cvt_pk_bf16_f32 v62, v2, v3
	v_lshlrev_b32_e32 v2, 16, v137
	v_and_b32_e32 v3, 0xffff0000, v137
	v_mul_f32_e32 v2, v134, v2
	v_mul_f32_e32 v3, v135, v3
	v_cvt_pk_bf16_f32 v63, v2, v3
	v_lshlrev_b32_e32 v2, 16, v144
	v_and_b32_e32 v3, 0xffff0000, v144
	s_waitcnt lgkmcnt(0)
	v_mul_f32_e32 v2, v140, v2
	v_mul_f32_e32 v3, v141, v3
	v_cvt_pk_bf16_f32 v64, v2, v3
	v_lshlrev_b32_e32 v2, 16, v145
	v_and_b32_e32 v3, 0xffff0000, v145
	v_mul_f32_e32 v2, v142, v2
	v_mul_f32_e32 v3, v143, v3
	v_cvt_pk_bf16_f32 v65, v2, v3
	s_nop 1
	v_mfma_f32_16x16x32_bf16 v[42:45], v[62:65], v[74:77], v[42:45]
	v_mfma_f32_16x16x32_bf16 v[38:41], v[62:65], v[120:123], v[38:41]
	v_mfma_f32_16x16x32_bf16 v[34:37], v[62:65], v[124:127], v[34:37]
	v_mfma_f32_16x16x32_bf16 v[30:33], v[62:65], v[128:131], v[30:33]
	v_mfma_f32_16x16x32_bf16 v[26:29], v[62:65], v[6:9], v[26:29]
	s_xor_b32 s18, s18, 1
	s_mulk_i32 s18, 0x4a00
	s_add_i32 s25, s18, 0
	v_lshlrev_b32_e32 v3, 1, v78
	ds_bpermute_b32 v2, v103, v66
	v_add3_u32 v3, s25, v79, v3
	v_cvt_pk_bf16_f32 v62, v42, v43
	v_cvt_pk_bf16_f32 v63, v44, v45
	v_add_u32_e32 v4, 0x1c0e0, v3
	ds_write_b64 v4, v[62:63]
	v_cvt_pk_bf16_f32 v62, v38, v39
	v_cvt_pk_bf16_f32 v63, v40, v41
	v_add_u32_e32 v4, 0x1d2e0, v3
	ds_write_b64 v4, v[62:63]
	v_cvt_pk_bf16_f32 v62, v34, v35
	v_cvt_pk_bf16_f32 v63, v36, v37
	v_add_u32_e32 v4, 0x1e4e0, v3
	ds_write_b64 v4, v[62:63]
	v_cvt_pk_bf16_f32 v62, v30, v31
	v_cvt_pk_bf16_f32 v63, v32, v33
	v_add_u32_e32 v3, 0x1f6e0, v3
	ds_write_b64 v3, v[62:63]
	s_and_saveexec_b64 s[18:19], s[2:3]
	s_cbranch_execz .LBB0_288
	v_lshl_add_u32 v3, v78, 1, s25
	v_cvt_pk_bf16_f32 v62, v26, v27
	v_cvt_pk_bf16_f32 v63, v28, v29
	v_add_u32_e32 v3, 0x208e0, v3
	ds_write_b64 v3, v[62:63]
	s_branch .LBB0_288
.LBB0_291:
	s_add_i32 s2, s78, 0xffffff80
	v_or_b32_e32 v2, s2, v93
	v_xad_u32 v3, v2, -1, s78
	v_cndmask_b32_e64 v2, v3, v2, s[4:5]
	v_ashrrev_i32_e32 v3, 31, v2
	v_lshl_add_u64 v[2:3], s[0:1], 0, v[2:3]
	v_lshlrev_b64 v[2:3], 11, v[2:3]
	v_lshl_add_u64 v[2:3], s[42:43], 0, v[2:3]
	s_lshl_b32 s68, s17, 1
	v_lshl_add_u64 v[2:3], v[2:3], 0, s[68:69]
	s_lshl_b32 s68, s21, 1
	v_lshl_add_u64 v[2:3], v[2:3], 0, s[68:69]
	v_lshl_add_u64 v[2:3], v[80:81], 1, v[2:3]
	s_and_b64 vcc, exec, s[46:47]
	global_store_dwordx4 v[2:3], v[50:53], off sc1
	global_store_dwordx4 v[2:3], v[46:49], off offset:64 sc1
	s_cbranch_vccz .LBB0_295
	s_waitcnt vmcnt(6)
	v_mbcnt_lo_u32_b32 v16, -1, 0
	v_mbcnt_hi_u32_b32 v16, -1, v16
	s_ashr_i32 s17, s16, 31
	v_lshlrev_b32_e32 v3, 1, v16
	v_ashrrev_i32_e32 v2, 2, v16
	v_and_b32_e32 v3, 24, v3
	v_and_b32_e32 v4, 3, v16
	s_lshl_b64 s[0:1], s[16:17], 16
	v_and_b32_e32 v2, -4, v2
	v_or3_b32 v3, v4, v3, s21
	s_add_u32 s0, s76, s0
	v_lshlrev_b32_e32 v4, 2, v3
	v_ashrrev_i32_e32 v3, 31, v2
	s_addc_u32 s1, s77, s1
	v_lshlrev_b64 v[6:7], 9, v[2:3]
	v_lshl_add_u64 v[6:7], s[0:1], 0, v[6:7]
	v_lshl_add_u64 v[6:7], v[6:7], 0, v[4:5]
	s_mov_b64 s[0:1], 0xe000
	v_lshl_add_u64 v[8:9], v[6:7], 0, s[0:1]
	s_mov_b32 s0, 0xe000
	v_add_co_u32_e32 v10, vcc, s0, v6
	s_mov_b64 s[0:1], 0xe200
	s_nop 0
	v_addc_co_u32_e32 v11, vcc, 0, v7, vcc
	v_lshl_add_u64 v[12:13], v[6:7], 0, s[0:1]
	s_mov_b64 s[0:1], 0xe400
	v_and_or_b32 v4, v16, 15, s31
	v_lshl_add_u64 v[14:15], v[6:7], 0, s[0:1]
	s_mov_b64 s[0:1], 0xe600
	v_cmp_eq_u32_e32 vcc, 0, v4
	global_store_dword v[10:11], v42, off
	global_store_dword v[10:11], v43, off offset:512
	global_store_dword v[10:11], v44, off offset:1024
	v_lshl_add_u64 v[6:7], v[6:7], 0, s[0:1]
	global_store_dword v[10:11], v45, off offset:1536
	global_store_dword v[8:9], v38, off offset:16
	global_store_dword v[12:13], v39, off offset:16
	global_store_dword v[14:15], v40, off offset:16
	global_store_dword v[6:7], v41, off offset:16
	global_store_dword v[8:9], v34, off offset:128
	global_store_dword v[12:13], v35, off offset:128
	global_store_dword v[14:15], v36, off offset:128
	global_store_dword v[6:7], v37, off offset:128
	global_store_dword v[8:9], v30, off offset:144
	global_store_dword v[12:13], v31, off offset:144
	global_store_dword v[14:15], v32, off offset:144
	global_store_dword v[6:7], v33, off offset:144
	s_and_saveexec_b64 s[0:1], vcc
	s_cbranch_execz .LBB0_294
	s_lshl_b64 s[2:3], s[16:17], 9
	v_readlane_b32 s4, v254, 26
	s_add_u32 s2, s4, s2
	v_readlane_b32 s4, v254, 27
	s_addc_u32 s3, s4, s3
	v_lshl_add_u64 v[2:3], v[2:3], 2, s[2:3]
	global_store_dwordx4 v[2:3], v[26:29], off offset:448 sc1

.LBB0_312:
	s_min_u32 s18, s20, 1
	s_lshl_b32 s26, s18, 7
	s_and_b32 s18, s20, 1
	s_mov_b32 s19, s20
	s_mul_i32 s20, s18, 0x5000
	s_add_i32 s25, s20, 0
	s_lshl_b32 s20, s18, 11
	s_add_i32 s20, s20, 0
	s_add_i32 s36, s20, 0x25a00
	s_lshl_b32 s20, s18, 4
	s_add_i32 s20, s20, 0
	s_add_i32 s25, s25, 0x12000
	s_add_i32 s37, s20, 0x26a00
	s_add_i32 s20, s19, 1
	s_mul_i32 s27, s18, 0x9000
	s_cmp_lt_u32 s20, s79
	s_cselect_b32 s38, s20, s19
	v_lshl_add_u32 v3, v104, 2, s36
	s_add_i32 s19, s27, 0
	v_lshlrev_b32_e32 v136, 1, v92
	s_waitcnt vmcnt(4)
	v_mov_b64_e32 v[56:57], v[16:17]
	s_waitcnt vmcnt(3)
	v_mov_b64_e32 v[60:61], v[20:21]
	s_waitcnt vmcnt(2)
	v_mov_b64_e32 v[88:89], v[24:25]
	v_mov_b32_e32 v2, s36
	v_add_u32_e32 v3, 0x80, v3
	v_add_u32_e32 v70, s19, v136
	v_mov_b64_e32 v[54:55], v[14:15]
	v_mov_b64_e32 v[58:59], v[18:19]
	v_mov_b64_e32 v[86:87], v[22:23]
	s_waitcnt lgkmcnt(0)
	s_barrier
	ds_read2st64_b32 v[98:99], v3 offset0:3 offset1:5
	v_mov_b32_e32 v3, s37
	v_add_u32_e32 v71, v70, v91
	ds_read_b32 v137, v2 offset:1020
	ds_read_b32 v216, v3
	ds_read_b128 v[14:17], v71
	ds_read_b128 v[18:21], v71 offset:4608
	ds_read_b128 v[22:25], v71 offset:9216
	ds_read_b128 v[62:65], v71 offset:13824
	ds_read_b128 v[66:69], v71 offset:18432
	v_add_u32_e32 v2, v70, v116
	ds_read_b128 v[70:73], v71 offset:23040
	ds_read_b128 v[74:77], v2
	v_subrev_u32_e32 v4, s26, v119
	v_add_u32_e32 v196, s26, v117
	s_mul_i32 s26, s18, 0x4a00
	s_add_i32 s26, s26, 0
	s_add_i32 s26, s26, 0x1c000
	v_add3_u32 v2, s19, v91, v136
	ds_read_b128 v[78:81], v2 offset:64
	ds_read_b128 v[82:85], v2 offset:4672
	ds_read_b128 v[100:103], v2 offset:9280
	ds_read_b128 v[120:123], v2 offset:13888
	ds_read_b128 v[124:127], v2 offset:18496
	ds_read_b128 v[128:131], v2 offset:23104
	v_add3_u32 v3, s19, v116, v136
	ds_read_b128 v[132:135], v3 offset:64
	s_waitcnt lgkmcnt(13)
	v_mfma_f32_16x16x32_bf16 v[14:17], v[14:17], v[10:13], 0
	s_waitcnt lgkmcnt(12)
	v_mfma_f32_16x16x32_bf16 v[18:21], v[18:21], v[10:13], 0
	s_waitcnt lgkmcnt(11)
	v_mfma_f32_16x16x32_bf16 v[22:25], v[22:25], v[10:13], 0
	s_waitcnt lgkmcnt(10)
	v_mfma_f32_16x16x32_bf16 v[62:65], v[62:65], v[10:13], 0
	s_waitcnt lgkmcnt(9)
	v_mfma_f32_16x16x32_bf16 v[66:69], v[66:69], v[10:13], 0
	s_waitcnt lgkmcnt(8)
	v_mfma_f32_16x16x32_bf16 v[70:73], v[70:73], v[10:13], 0
	s_waitcnt lgkmcnt(7)
	v_mfma_f32_16x16x32_bf16 v[74:77], v[74:77], v[10:13], 0
	ds_read_b128 v[140:143], v2 offset:128
	ds_read_b128 v[144:147], v2 offset:4736
	ds_read_b128 v[148:151], v2 offset:9344
	ds_read_b128 v[152:155], v2 offset:13952
	ds_read_b128 v[168:171], v2 offset:18560
	ds_read_b128 v[172:175], v2 offset:23168
	ds_read_b128 v[176:179], v3 offset:128
	s_waitcnt lgkmcnt(13)
	v_mfma_f32_16x16x32_bf16 v[14:17], v[78:81], v[54:57], v[14:17]
	s_waitcnt lgkmcnt(12)
	v_mfma_f32_16x16x32_bf16 v[18:21], v[82:85], v[54:57], v[18:21]
	s_waitcnt lgkmcnt(11)
	v_mfma_f32_16x16x32_bf16 v[22:25], v[100:103], v[54:57], v[22:25]
	s_waitcnt lgkmcnt(10)
	v_mfma_f32_16x16x32_bf16 v[62:65], v[120:123], v[54:57], v[62:65]
	s_waitcnt lgkmcnt(9)
	v_mfma_f32_16x16x32_bf16 v[66:69], v[124:127], v[54:57], v[66:69]
	s_waitcnt lgkmcnt(8)
	v_mfma_f32_16x16x32_bf16 v[70:73], v[128:131], v[54:57], v[70:73]
	s_waitcnt lgkmcnt(7)
	v_mfma_f32_16x16x32_bf16 v[74:77], v[132:135], v[54:57], v[74:77]
	ds_read_b128 v[78:81], v2 offset:192
	ds_read_b128 v[82:85], v2 offset:4800
	ds_read_b128 v[100:103], v2 offset:9408
	ds_read_b128 v[120:123], v2 offset:14016
	ds_read_b128 v[124:127], v2 offset:18624
	ds_read_b128 v[128:131], v2 offset:23232
	ds_read_b128 v[132:135], v3 offset:192
	s_waitcnt lgkmcnt(13)
	v_mfma_f32_16x16x32_bf16 v[14:17], v[140:143], v[58:61], v[14:17]
	s_waitcnt lgkmcnt(12)
	v_mfma_f32_16x16x32_bf16 v[18:21], v[144:147], v[58:61], v[18:21]
	s_waitcnt lgkmcnt(11)
	v_mfma_f32_16x16x32_bf16 v[22:25], v[148:151], v[58:61], v[22:25]
	s_waitcnt lgkmcnt(10)
	v_mfma_f32_16x16x32_bf16 v[62:65], v[152:155], v[58:61], v[62:65]
	s_waitcnt lgkmcnt(9)
	v_mfma_f32_16x16x32_bf16 v[66:69], v[168:171], v[58:61], v[66:69]
	s_waitcnt lgkmcnt(8)
	v_mfma_f32_16x16x32_bf16 v[70:73], v[172:175], v[58:61], v[70:73]
	s_waitcnt lgkmcnt(7)
	v_mfma_f32_16x16x32_bf16 v[140:143], v[176:179], v[58:61], v[74:77]
	v_add3_u32 v2, s26, v136, v91
	ds_read_b128 v[144:147], v2
	ds_read_b128 v[148:151], v2 offset:4608
	ds_read_b128 v[152:155], v2 offset:9216
	ds_read_b128 v[168:171], v2 offset:13824
	ds_read_b128 v[172:175], v2 offset:18432
	s_waitcnt lgkmcnt(11)
	v_mfma_f32_16x16x32_bf16 v[176:179], v[78:81], v[86:89], v[14:17]
	s_waitcnt lgkmcnt(10)
	v_mfma_f32_16x16x32_bf16 v[180:183], v[82:85], v[86:89], v[18:21]
	s_waitcnt lgkmcnt(9)
	v_mfma_f32_16x16x32_bf16 v[184:187], v[100:103], v[86:89], v[22:25]
	s_waitcnt lgkmcnt(8)
	v_mfma_f32_16x16x32_bf16 v[82:85], v[120:123], v[86:89], v[62:65]
	s_waitcnt lgkmcnt(7)
	v_mfma_f32_16x16x32_bf16 v[78:81], v[124:127], v[86:89], v[66:69]
	s_waitcnt lgkmcnt(6)
	v_mfma_f32_16x16x32_bf16 v[74:77], v[128:131], v[86:89], v[70:73]
	s_waitcnt lgkmcnt(5)
	v_mfma_f32_16x16x32_bf16 v[70:73], v[132:135], v[86:89], v[140:143]
	v_add3_u32 v136, s26, v91, v136
	ds_read_b128 v[18:21], v136 offset:64
	ds_read_b128 v[22:25], v136 offset:4672
	ds_read_b128 v[62:65], v136 offset:9280
	ds_read_b128 v[66:69], v136 offset:13888
	ds_read_b128 v[100:103], v136 offset:18496
	v_lshl_or_b32 v2, s38, 7, v105
	v_xad_u32 v3, v2, -1, s78
	v_cndmask_b32_e64 v2, v3, v2, s[4:5]
	v_add_u32_e32 v2, s48, v2
	v_mad_i64_i32 v[2:3], s[26:27], v2, s86, v[94:95]
	s_waitcnt lgkmcnt(9)
	v_mfma_f32_16x16x32_bf16 v[120:123], v[144:147], v[10:13], 0
	s_waitcnt lgkmcnt(8)
	v_mfma_f32_16x16x32_bf16 v[124:127], v[148:151], v[10:13], 0
	s_waitcnt lgkmcnt(7)
	v_mfma_f32_16x16x32_bf16 v[128:131], v[152:155], v[10:13], 0
	s_waitcnt lgkmcnt(6)
	v_mfma_f32_16x16x32_bf16 v[132:135], v[168:171], v[10:13], 0
	s_waitcnt lgkmcnt(5)
	v_mfma_f32_16x16x32_bf16 v[140:143], v[172:175], v[10:13], 0
	global_load_dwordx4 v[10:13], v[2:3], off
	global_load_dwordx4 v[14:17], v[2:3], off offset:64
	ds_read_b128 v[144:147], v136 offset:128
	ds_read_b128 v[148:151], v136 offset:4736
	ds_read_b128 v[152:155], v136 offset:9344
	ds_read_b128 v[168:171], v136 offset:13952
	ds_read_b128 v[172:175], v136 offset:18560
	s_waitcnt lgkmcnt(9)
	v_mfma_f32_16x16x32_bf16 v[120:123], v[18:21], v[54:57], v[120:123]
	s_waitcnt lgkmcnt(8)
	v_mfma_f32_16x16x32_bf16 v[124:127], v[22:25], v[54:57], v[124:127]
	global_load_dwordx4 v[18:21], v[2:3], off offset:128
	global_load_dwordx4 v[22:25], v[2:3], off offset:192
	s_waitcnt lgkmcnt(7)
	v_mfma_f32_16x16x32_bf16 v[62:65], v[62:65], v[54:57], v[128:131]
	s_waitcnt lgkmcnt(6)
	v_mfma_f32_16x16x32_bf16 v[66:69], v[66:69], v[54:57], v[132:135]
	s_waitcnt lgkmcnt(5)
	v_mfma_f32_16x16x32_bf16 v[54:57], v[100:103], v[54:57], v[140:143]
	ds_read_b128 v[128:131], v136 offset:192
	ds_read_b128 v[132:135], v136 offset:4800
	s_nop 0
	ds_read_b128 v[140:143], v136 offset:9408
	ds_read_b128 v[188:191], v136 offset:14016
	ds_read_b128 v[192:195], v136 offset:18624
	v_cndmask_b32_e64 v2, v196, v4, s[4:5]
	v_ashrrev_i32_e32 v3, 31, v2
	v_lshl_add_u64 v[2:3], s[0:1], 0, v[2:3]
	v_lshlrev_b64 v[2:3], 11, v[2:3]
	v_lshl_add_u64 v[2:3], v[96:97], 0, v[2:3]
	s_waitcnt lgkmcnt(9)
	v_mfma_f32_16x16x32_bf16 v[120:123], v[144:147], v[58:61], v[120:123]
	global_store_dwordx4 v[2:3], v[50:53], off sc1
	global_store_dwordx4 v[2:3], v[46:49], off offset:64 sc1
	s_waitcnt lgkmcnt(8)
	v_mfma_f32_16x16x32_bf16 v[124:127], v[148:151], v[58:61], v[124:127]
	s_waitcnt lgkmcnt(7)
	v_mfma_f32_16x16x32_bf16 v[144:147], v[152:155], v[58:61], v[62:65]
	s_waitcnt lgkmcnt(6)
	v_mfma_f32_16x16x32_bf16 v[148:151], v[168:171], v[58:61], v[66:69]
	s_waitcnt lgkmcnt(5)
	v_mfma_f32_16x16x32_bf16 v[152:155], v[172:175], v[58:61], v[54:57]
	v_add3_u32 v2, s25, v106, v107
	ds_read_b64_tr_b16 v[50:51], v2
	ds_read_b64_tr_b16 v[46:47], v2 offset:32
	ds_read_b64_tr_b16 v[54:55], v2 offset:64
	ds_read_b64_tr_b16 v[58:59], v2 offset:96
	ds_read_b64_tr_b16 v[52:53], v2 offset:2560
	ds_read_b64_tr_b16 v[48:49], v2 offset:2592
	ds_read_b64_tr_b16 v[56:57], v2 offset:2624
	ds_read_b64_tr_b16 v[60:61], v2 offset:2656
	v_add3_u32 v2, s19, v108, v118
	v_lshl_add_u32 v217, v90, 2, s36
	ds_read_b64_tr_b16 v[102:103], v2 offset:160
	ds_read_b64_tr_b16 v[100:101], v2 offset:4768
	ds_read_b128 v[62:65], v217 offset:1600
	ds_read_b128 v[168:171], v217
	ds_read_b128 v[172:175], v217 offset:64
	ds_read_b128 v[196:199], v217 offset:128
	ds_read_b128 v[200:203], v217 offset:192
	ds_read_b128 v[204:207], v217 offset:256
	ds_read_b128 v[208:211], v217 offset:320
	ds_read_b128 v[66:69], v217 offset:1536
	ds_read_b128 v[212:215], v217 offset:384
	s_waitcnt lgkmcnt(14)
	v_mfma_f32_16x16x32_bf16 v[120:123], v[128:131], v[86:89], v[120:123]
	v_mfma_f32_16x16x32_bf16 v[124:127], v[132:135], v[86:89], v[124:127]
	v_mfma_f32_16x16x32_bf16 v[128:131], v[140:143], v[86:89], v[144:147]
	v_mfma_f32_16x16x32_bf16 v[132:135], v[188:191], v[86:89], v[148:151]
	v_mfma_f32_16x16x32_bf16 v[140:143], v[192:195], v[86:89], v[152:155]
	s_waitcnt lgkmcnt(4)
	v_fmamk_f32 v147, v98, 0xbfb8aa3b, v200
	v_fmamk_f32 v148, v98, 0xbfb8aa3b, v201
	v_exp_f32_e32 v147, v147
	v_exp_f32_e32 v148, v148
	v_fmamk_f32 v149, v98, 0xbfb8aa3b, v202
	v_exp_f32_e32 v149, v149
	v_fmac_f32_e32 v203, 0xbfb8aa3b, v98
	v_mul_f32_e32 v82, v82, v147
	v_mul_f32_e32 v83, v83, v148
	s_waitcnt lgkmcnt(3)
	v_fmamk_f32 v147, v98, 0xbfb8aa3b, v204
	v_fmamk_f32 v148, v98, 0xbfb8aa3b, v205
	v_exp_f32_e32 v150, v203
	v_exp_f32_e32 v147, v147
	v_exp_f32_e32 v148, v148
	v_mul_f32_e32 v84, v84, v149
	v_fmamk_f32 v149, v98, 0xbfb8aa3b, v206
	v_exp_f32_e32 v149, v149
	v_sub_f32_e32 v2, v216, v98
	v_fmac_f32_e32 v207, 0xbfb8aa3b, v98
	v_mul_f32_e32 v2, 0x3fb8aa3b, v2
	v_mul_f32_e32 v85, v85, v150
	v_exp_f32_e32 v150, v207
	v_mul_f32_e32 v78, v78, v147
	v_mul_f32_e32 v79, v79, v148
	s_waitcnt lgkmcnt(2)
	v_fmamk_f32 v147, v98, 0xbfb8aa3b, v208
	v_fmamk_f32 v148, v98, 0xbfb8aa3b, v209
	v_exp_f32_e32 v2, v2
	v_sub_f32_e32 v3, v216, v137
	v_exp_f32_e32 v147, v147
	v_exp_f32_e32 v148, v148
	v_mul_f32_e32 v3, 0x3fb8aa3b, v3
	v_mul_f32_e32 v80, v80, v149
	v_fmamk_f32 v149, v98, 0xbfb8aa3b, v210
	v_exp_f32_e32 v4, v3
	v_exp_f32_e32 v149, v149
	v_fmac_f32_e32 v211, 0xbfb8aa3b, v98
	v_mul_f32_e32 v81, v81, v150
	v_exp_f32_e32 v150, v211
	v_pk_mul_f32 v[88:89], v[2:3], v[122:123] op_sel_hi:[0,1]
	v_pk_mul_f32 v[86:87], v[2:3], v[120:121] op_sel_hi:[0,1]
	v_pk_mul_f32 v[122:123], v[2:3], v[126:127] op_sel_hi:[0,1]
	v_pk_mul_f32 v[120:121], v[2:3], v[124:125] op_sel_hi:[0,1]
	v_pk_mul_f32 v[126:127], v[2:3], v[130:131] op_sel_hi:[0,1]
	v_pk_mul_f32 v[124:125], v[2:3], v[128:129] op_sel_hi:[0,1]
	v_pk_mul_f32 v[130:131], v[2:3], v[134:135] op_sel_hi:[0,1]
	v_pk_mul_f32 v[128:129], v[2:3], v[132:133] op_sel_hi:[0,1]
	v_pk_mul_f32 v[134:135], v[2:3], v[142:143] op_sel_hi:[0,1]
	v_pk_mul_f32 v[132:133], v[2:3], v[140:141] op_sel_hi:[0,1]
	v_fmamk_f32 v2, v98, 0xbfb8aa3b, v168
	v_fmamk_f32 v3, v98, 0xbfb8aa3b, v169
	v_mul_f32_e32 v147, v74, v147
	v_mul_f32_e32 v148, v75, v148
	s_waitcnt lgkmcnt(0)
	v_fmamk_f32 v74, v98, 0xbfb8aa3b, v212
	v_fmamk_f32 v75, v98, 0xbfb8aa3b, v213
	v_exp_f32_e32 v2, v2
	v_exp_f32_e32 v3, v3
	v_exp_f32_e32 v74, v74
	v_exp_f32_e32 v75, v75
	v_pk_mul_f32 v[44:45], v[44:45], v[4:5] op_sel_hi:[1,0]
	v_pk_mul_f32 v[42:43], v[42:43], v[4:5] op_sel_hi:[1,0]
	v_pk_mul_f32 v[40:41], v[40:41], v[4:5] op_sel_hi:[1,0]
	v_pk_mul_f32 v[38:39], v[38:39], v[4:5] op_sel_hi:[1,0]
	v_pk_mul_f32 v[36:37], v[36:37], v[4:5] op_sel_hi:[1,0]
	v_pk_mul_f32 v[34:35], v[34:35], v[4:5] op_sel_hi:[1,0]
	v_pk_mul_f32 v[32:33], v[32:33], v[4:5] op_sel_hi:[1,0]
	v_pk_mul_f32 v[30:31], v[30:31], v[4:5] op_sel_hi:[1,0]
	v_pk_mul_f32 v[28:29], v[28:29], v[4:5] op_sel_hi:[1,0]
	v_pk_mul_f32 v[26:27], v[26:27], v[4:5] op_sel_hi:[1,0]
	v_fmamk_f32 v4, v98, 0xbfb8aa3b, v170
	v_fmac_f32_e32 v171, 0xbfb8aa3b, v98
	v_mul_f32_e32 v149, v76, v149
	v_fmamk_f32 v76, v98, 0xbfb8aa3b, v214
	v_fmac_f32_e32 v215, 0xbfb8aa3b, v98
	v_exp_f32_e32 v4, v4
	v_exp_f32_e32 v136, v171
	v_mul_f32_e32 v150, v77, v150
	v_exp_f32_e32 v76, v76
	v_exp_f32_e32 v77, v215
	v_fmamk_f32 v137, v98, 0xbfb8aa3b, v172
	v_fmamk_f32 v140, v98, 0xbfb8aa3b, v173
	v_fmamk_f32 v141, v98, 0xbfb8aa3b, v174
	v_fmac_f32_e32 v175, 0xbfb8aa3b, v98
	v_fmamk_f32 v143, v98, 0xbfb8aa3b, v196
	v_fmamk_f32 v144, v98, 0xbfb8aa3b, v197
	v_fmamk_f32 v145, v98, 0xbfb8aa3b, v198
	v_fmac_f32_e32 v199, 0xbfb8aa3b, v98
	v_mul_f32_e32 v2, v176, v2
	v_mul_f32_e32 v3, v177, v3
	v_exp_f32_e32 v137, v137
	v_exp_f32_e32 v140, v140
	v_exp_f32_e32 v141, v141
	v_exp_f32_e32 v142, v175
	v_exp_f32_e32 v143, v143
	v_exp_f32_e32 v144, v144
	v_exp_f32_e32 v145, v145
	v_exp_f32_e32 v146, v199
	v_mul_f32_e32 v98, v70, v74
	v_mul_f32_e32 v151, v71, v75
	v_cvt_pk_bf16_f32 v70, v2, v3
	v_cvt_pk_bf16_f32 v2, v98, s0
	v_cvt_pk_bf16_f32 v3, v151, s0
	v_mul_f32_e32 v4, v178, v4
	v_mul_f32_e32 v136, v179, v136
	v_mul_f32_e32 v152, v72, v76
	v_mul_f32_e32 v153, v73, v77
	v_cndmask_b32_e64 v2, v2, 0, s[6:7]
	v_cndmask_b32_e64 v3, 0, v3, s[8:9]
	v_cvt_pk_bf16_f32 v71, v4, v136
	v_perm_b32 v2, v3, v2, s89
	v_cvt_pk_bf16_f32 v3, v152, s0
	v_cvt_pk_bf16_f32 v4, v153, s0
	v_mul_f32_e32 v137, v180, v137
	v_mul_f32_e32 v140, v181, v140
	v_mul_f32_e32 v141, v182, v141
	v_mul_f32_e32 v142, v183, v142
	v_mul_f32_e32 v143, v184, v143
	v_mul_f32_e32 v144, v185, v144
	v_mul_f32_e32 v145, v186, v145
	v_mul_f32_e32 v146, v187, v146
	v_cndmask_b32_e64 v3, v3, 0, s[10:11]
	v_cndmask_b32_e64 v4, v4, 0, s[12:13]
	v_cvt_pk_bf16_f32 v72, v137, v140
	v_cvt_pk_bf16_f32 v73, v141, v142
	v_cvt_pk_bf16_f32 v74, v143, v144
	v_cvt_pk_bf16_f32 v75, v145, v146
	v_cvt_pk_bf16_f32 v76, v82, v83
	v_cvt_pk_bf16_f32 v77, v84, v85
	v_cvt_pk_bf16_f32 v78, v78, v79
	v_cvt_pk_bf16_f32 v79, v80, v81
	v_cvt_pk_bf16_f32 v80, v147, v148
	v_cvt_pk_bf16_f32 v81, v149, v150
	v_perm_b32 v3, v4, v3, s89
	v_mov_b32_e32 v4, v5
	v_add3_u32 v98, s25, v109, v118
	ds_read_b64_tr_b16 v[82:83], v98
	ds_read_b64_tr_b16 v[140:141], v98 offset:32
	ds_read_b64_tr_b16 v[144:145], v98 offset:64
	ds_read_b64_tr_b16 v[148:149], v98 offset:96
	ds_read_b64_tr_b16 v[84:85], v98 offset:2560
	ds_read_b64_tr_b16 v[142:143], v98 offset:2592
	ds_read_b64_tr_b16 v[146:147], v98 offset:2624
	ds_read_b64_tr_b16 v[150:151], v98 offset:2656
	v_add3_u32 v98, s19, v110, v118
	ds_read_b64_tr_b16 v[136:137], v98 offset:160
	ds_read_b64_tr_b16 v[172:173], v98 offset:4768
	ds_read_b128 v[152:155], v217 offset:1664
	ds_read_b128 v[168:171], v217 offset:1728
	v_lshlrev_b32_e32 v98, 16, v102
	v_mul_f32_e32 v66, v66, v98
	v_and_b32_e32 v98, 0xffff0000, v102
	v_mul_f32_e32 v67, v67, v98
	v_cvt_pk_bf16_f32 v66, v66, v67
	v_lshlrev_b32_e32 v67, 16, v103
	v_mul_f32_e32 v67, v68, v67
	v_and_b32_e32 v68, 0xffff0000, v103
	v_mul_f32_e32 v68, v69, v68
	v_cvt_pk_bf16_f32 v67, v67, v68
	v_lshlrev_b32_e32 v68, 16, v100
	v_mul_f32_e32 v62, v62, v68
	v_and_b32_e32 v68, 0xffff0000, v100
	v_mul_f32_e32 v63, v63, v68
	v_cvt_pk_bf16_f32 v68, v62, v63
	v_lshlrev_b32_e32 v62, 16, v101
	v_and_b32_e32 v63, 0xffff0000, v101
	v_mul_f32_e32 v62, v64, v62
	v_mul_f32_e32 v63, v65, v63
	v_cvt_pk_bf16_f32 v69, v62, v63
	v_mfma_f32_16x16x32_bf16 v[86:89], v[50:53], v[70:73], v[86:89]
	s_nop 0
	v_mfma_f32_16x16x32_bf16 v[42:45], v[66:69], v[50:53], v[42:45]
	v_mfma_f32_16x16x32_bf16 v[38:41], v[66:69], v[46:49], v[38:41]
	v_mfma_f32_16x16x32_bf16 v[34:37], v[66:69], v[54:57], v[34:37]
	v_mfma_f32_16x16x32_bf16 v[30:33], v[66:69], v[58:61], v[30:33]
	v_mfma_f32_16x16x32_bf16 v[26:29], v[66:69], v[6:9], v[26:29]
	v_mfma_f32_16x16x32_bf16 v[120:123], v[46:49], v[70:73], v[120:123]
	v_mfma_f32_16x16x32_bf16 v[124:127], v[54:57], v[70:73], v[124:127]
	v_mfma_f32_16x16x32_bf16 v[128:131], v[58:61], v[70:73], v[128:131]
	v_mfma_f32_16x16x32_bf16 v[70:73], v[6:9], v[70:73], v[132:135]
	v_add3_u32 v60, s25, v111, v118
	ds_read_b64_tr_b16 v[46:47], v60
	ds_read_b64_tr_b16 v[50:51], v60 offset:32
	ds_read_b64_tr_b16 v[54:55], v60 offset:64
	ds_read_b64_tr_b16 v[58:59], v60 offset:96
	ds_read_b64_tr_b16 v[48:49], v60 offset:2560
	ds_read_b64_tr_b16 v[52:53], v60 offset:2592
	ds_read_b64_tr_b16 v[56:57], v60 offset:2624
	ds_read_b64_tr_b16 v[60:61], v60 offset:2656
	v_add3_u32 v62, s19, v112, v118
	ds_read_b64_tr_b16 v[174:175], v62 offset:160
	ds_read_b64_tr_b16 v[176:177], v62 offset:4768
	ds_read_b128 v[62:65], v217 offset:1792
	ds_read_b128 v[66:69], v217 offset:1856
	s_waitcnt lgkmcnt(14)
	v_mfma_f32_16x16x32_bf16 v[86:89], v[82:85], v[74:77], v[86:89]
	v_and_b32_e32 v98, 0xffff0000, v173
	s_waitcnt lgkmcnt(12)
	v_mul_f32_e32 v98, v171, v98
	v_mfma_f32_16x16x32_bf16 v[100:103], v[140:143], v[74:77], v[120:123]
	v_mfma_f32_16x16x32_bf16 v[120:123], v[144:147], v[74:77], v[124:127]
	v_mfma_f32_16x16x32_bf16 v[124:127], v[148:151], v[74:77], v[128:131]
	v_mfma_f32_16x16x32_bf16 v[70:73], v[6:9], v[74:77], v[70:73]
	v_lshlrev_b32_e32 v74, 16, v136
	v_and_b32_e32 v75, 0xffff0000, v136
	v_mul_f32_e32 v74, v152, v74
	v_mul_f32_e32 v75, v153, v75
	v_cvt_pk_bf16_f32 v74, v74, v75
	v_lshlrev_b32_e32 v75, 16, v137
	v_and_b32_e32 v76, 0xffff0000, v137
	v_mul_f32_e32 v75, v154, v75
	v_mul_f32_e32 v76, v155, v76
	v_cvt_pk_bf16_f32 v75, v75, v76
	v_lshlrev_b32_e32 v76, 16, v172
	v_and_b32_e32 v77, 0xffff0000, v172
	v_mul_f32_e32 v76, v168, v76
	v_mul_f32_e32 v77, v169, v77
	v_cvt_pk_bf16_f32 v76, v76, v77
	v_lshlrev_b32_e32 v77, 16, v173
	v_mul_f32_e32 v77, v170, v77
	v_cvt_pk_bf16_f32 v77, v77, v98
	s_nop 1
	v_mfma_f32_16x16x32_bf16 v[42:45], v[74:77], v[82:85], v[42:45]
	v_mfma_f32_16x16x32_bf16 v[38:41], v[74:77], v[140:143], v[38:41]
	v_mfma_f32_16x16x32_bf16 v[34:37], v[74:77], v[144:147], v[34:37]
	v_mfma_f32_16x16x32_bf16 v[30:33], v[74:77], v[148:151], v[30:33]
	v_mfma_f32_16x16x32_bf16 v[26:29], v[74:77], v[6:9], v[26:29]
	v_add3_u32 v98, s25, v113, v118
	ds_read_b64_tr_b16 v[74:75], v98
	ds_read_b64_tr_b16 v[82:83], v98 offset:32
	ds_read_b64_tr_b16 v[128:129], v98 offset:64
	ds_read_b64_tr_b16 v[132:133], v98 offset:96
	ds_read_b64_tr_b16 v[76:77], v98 offset:2560
	ds_read_b64_tr_b16 v[84:85], v98 offset:2592
	ds_read_b64_tr_b16 v[130:131], v98 offset:2624
	ds_read_b64_tr_b16 v[134:135], v98 offset:2656
	v_add3_u32 v98, s19, v114, v118
	ds_read_b64_tr_b16 v[136:137], v98 offset:160
	ds_read_b64_tr_b16 v[148:149], v98 offset:4768
	ds_read_b128 v[140:143], v217 offset:1920
	ds_read_b128 v[144:147], v217 offset:1984
	s_waitcnt lgkmcnt(14)
	v_mfma_f32_16x16x32_bf16 v[86:89], v[46:49], v[78:81], v[86:89]
	v_mfma_f32_16x16x32_bf16 v[100:103], v[50:53], v[78:81], v[100:103]
	v_mfma_f32_16x16x32_bf16 v[120:123], v[54:57], v[78:81], v[120:123]
	v_mfma_f32_16x16x32_bf16 v[124:127], v[58:61], v[78:81], v[124:127]
	v_mfma_f32_16x16x32_bf16 v[70:73], v[6:9], v[78:81], v[70:73]
	v_lshlrev_b32_e32 v78, 16, v174
	s_waitcnt lgkmcnt(13)
	v_mul_f32_e32 v62, v62, v78
	v_and_b32_e32 v78, 0xffff0000, v174
	v_mul_f32_e32 v63, v63, v78
	v_cvt_pk_bf16_f32 v62, v62, v63
	v_lshlrev_b32_e32 v63, 16, v175
	v_mul_f32_e32 v63, v64, v63
	v_and_b32_e32 v64, 0xffff0000, v175
	v_mul_f32_e32 v64, v65, v64
	v_cvt_pk_bf16_f32 v63, v63, v64
	v_lshlrev_b32_e32 v64, 16, v176
	v_and_b32_e32 v65, 0xffff0000, v176
	s_waitcnt lgkmcnt(12)
	v_mul_f32_e32 v64, v66, v64
	v_mul_f32_e32 v65, v67, v65
	v_cvt_pk_bf16_f32 v64, v64, v65
	v_lshlrev_b32_e32 v65, 16, v177
	v_and_b32_e32 v66, 0xffff0000, v177
	v_mul_f32_e32 v65, v68, v65
	v_mul_f32_e32 v66, v69, v66
	v_cvt_pk_bf16_f32 v65, v65, v66
	s_nop 1
	v_mfma_f32_16x16x32_bf16 v[42:45], v[62:65], v[46:49], v[42:45]
	v_mfma_f32_16x16x32_bf16 v[38:41], v[62:65], v[50:53], v[38:41]
	v_mfma_f32_16x16x32_bf16 v[34:37], v[62:65], v[54:57], v[34:37]
	v_mfma_f32_16x16x32_bf16 v[30:33], v[62:65], v[58:61], v[30:33]
	v_mfma_f32_16x16x32_bf16 v[26:29], v[62:65], v[6:9], v[26:29]
	s_waitcnt lgkmcnt(7)
	v_mfma_f32_16x16x32_bf16 v[50:53], v[74:77], v[2:5], v[86:89]
	s_waitcnt lgkmcnt(6)
	v_mfma_f32_16x16x32_bf16 v[58:61], v[82:85], v[2:5], v[100:103]
	s_waitcnt lgkmcnt(5)
	v_mfma_f32_16x16x32_bf16 v[46:49], v[128:131], v[2:5], v[120:123]
	s_waitcnt lgkmcnt(4)
	v_mfma_f32_16x16x32_bf16 v[54:57], v[132:135], v[2:5], v[124:127]
	v_mfma_f32_16x16x32_bf16 v[62:65], v[6:9], v[2:5], v[70:73]
	s_waitcnt lgkmcnt(3)
	v_lshlrev_b32_e32 v2, 16, v136
	v_and_b32_e32 v3, 0xffff0000, v136
	s_waitcnt lgkmcnt(1)
	v_mul_f32_e32 v2, v140, v2
	v_mul_f32_e32 v3, v141, v3
	s_nop 1
	v_cvt_pk_bf16_f32 v64, v2, v3
	v_lshlrev_b32_e32 v2, 16, v137
	v_and_b32_e32 v3, 0xffff0000, v137
	v_mul_f32_e32 v2, v142, v2
	v_mul_f32_e32 v3, v143, v3
	v_cvt_pk_bf16_f32 v65, v2, v3
	v_lshlrev_b32_e32 v2, 16, v148
	v_and_b32_e32 v3, 0xffff0000, v148
	s_waitcnt lgkmcnt(0)
	v_mul_f32_e32 v2, v144, v2
	v_mul_f32_e32 v3, v145, v3
	v_cvt_pk_bf16_f32 v66, v2, v3
	v_lshlrev_b32_e32 v2, 16, v149
	v_and_b32_e32 v3, 0xffff0000, v149
	v_mul_f32_e32 v2, v146, v2
	v_mul_f32_e32 v3, v147, v3
	v_cvt_pk_bf16_f32 v67, v2, v3
	s_nop 1
	v_mfma_f32_16x16x32_bf16 v[42:45], v[64:67], v[74:77], v[42:45]
	v_mfma_f32_16x16x32_bf16 v[38:41], v[64:67], v[82:85], v[38:41]
	v_mfma_f32_16x16x32_bf16 v[34:37], v[64:67], v[128:131], v[34:37]
	v_mfma_f32_16x16x32_bf16 v[30:33], v[64:67], v[132:135], v[30:33]
	v_mfma_f32_16x16x32_bf16 v[26:29], v[64:67], v[6:9], v[26:29]
	s_xor_b32 s18, s18, 1
	s_mulk_i32 s18, 0x4a00
	s_add_i32 s25, s18, 0
	v_lshlrev_b32_e32 v3, 1, v90
	ds_bpermute_b32 v2, v115, v62
	v_add3_u32 v3, s25, v91, v3
	v_cvt_pk_bf16_f32 v62, v42, v43
	v_cvt_pk_bf16_f32 v63, v44, v45
	v_add_u32_e32 v4, 0x1c0a0, v3
	ds_write_b64 v4, v[62:63]
	v_cvt_pk_bf16_f32 v62, v38, v39
	v_cvt_pk_bf16_f32 v63, v40, v41
	v_add_u32_e32 v4, 0x1d2a0, v3
	ds_write_b64 v4, v[62:63]
	v_cvt_pk_bf16_f32 v62, v34, v35
	v_cvt_pk_bf16_f32 v63, v36, v37
	v_add_u32_e32 v4, 0x1e4a0, v3
	ds_write_b64 v4, v[62:63]
	v_cvt_pk_bf16_f32 v62, v30, v31
	v_cvt_pk_bf16_f32 v63, v32, v33
	v_add_u32_e32 v3, 0x1f6a0, v3
	ds_write_b64 v3, v[62:63]
	s_and_saveexec_b64 s[18:19], s[2:3]
	s_cbranch_execz .LBB0_311
	v_lshl_add_u32 v3, v90, 1, s25
	v_cvt_pk_bf16_f32 v62, v26, v27
	v_cvt_pk_bf16_f32 v63, v28, v29
	v_add_u32_e32 v3, 0x208a0, v3
	ds_write_b64 v3, v[62:63]
	s_branch .LBB0_311
.LBB0_314:
	s_add_i32 s2, s78, 0xffffff80
	v_or_b32_e32 v2, s2, v105
	v_xad_u32 v3, v2, -1, s78
	v_cndmask_b32_e64 v2, v3, v2, s[4:5]
	v_ashrrev_i32_e32 v3, 31, v2
	v_lshl_add_u64 v[2:3], s[0:1], 0, v[2:3]
	v_lshlrev_b64 v[2:3], 11, v[2:3]
	v_lshl_add_u64 v[2:3], s[42:43], 0, v[2:3]
	s_lshl_b32 s68, s17, 1
	v_lshl_add_u64 v[2:3], v[2:3], 0, s[68:69]
	s_lshl_b32 s68, s21, 1
	v_lshl_add_u64 v[2:3], v[2:3], 0, s[68:69]
	v_lshl_add_u64 v[2:3], v[92:93], 1, v[2:3]
	s_and_b64 vcc, exec, s[46:47]
	global_store_dwordx4 v[2:3], v[50:53], off sc1
	global_store_dwordx4 v[2:3], v[46:49], off offset:64 sc1
	s_cbranch_vccz .LBB0_318
	s_waitcnt vmcnt(6)
	v_mbcnt_lo_u32_b32 v16, -1, 0
	v_mbcnt_hi_u32_b32 v16, -1, v16
	s_ashr_i32 s17, s16, 31
	v_lshlrev_b32_e32 v3, 1, v16
	v_ashrrev_i32_e32 v2, 2, v16
	v_and_b32_e32 v3, 24, v3
	v_and_b32_e32 v4, 3, v16
	s_lshl_b64 s[0:1], s[16:17], 16
	v_and_b32_e32 v2, -4, v2
	v_or3_b32 v3, v4, v3, s21
	s_add_u32 s0, s76, s0
	v_lshlrev_b32_e32 v4, 2, v3
	v_ashrrev_i32_e32 v3, 31, v2
	s_addc_u32 s1, s77, s1
	v_lshlrev_b64 v[6:7], 9, v[2:3]
	v_lshl_add_u64 v[6:7], s[0:1], 0, v[6:7]
	v_lshl_add_u64 v[6:7], v[6:7], 0, v[4:5]
	s_mov_b64 s[0:1], 0xa000
	v_lshl_add_u64 v[8:9], v[6:7], 0, s[0:1]
	s_mov_b32 s0, 0xa000
	v_add_co_u32_e32 v10, vcc, s0, v6
	s_mov_b64 s[0:1], 0xa200
	s_nop 0
	v_addc_co_u32_e32 v11, vcc, 0, v7, vcc
	v_lshl_add_u64 v[12:13], v[6:7], 0, s[0:1]
	s_mov_b64 s[0:1], 0xa400
	v_and_or_b32 v4, v16, 15, s31
	v_lshl_add_u64 v[14:15], v[6:7], 0, s[0:1]
	s_mov_b64 s[0:1], 0xa600
	v_cmp_eq_u32_e32 vcc, 0, v4
	global_store_dword v[10:11], v42, off
	global_store_dword v[10:11], v43, off offset:512
	global_store_dword v[10:11], v44, off offset:1024
	v_lshl_add_u64 v[6:7], v[6:7], 0, s[0:1]
	global_store_dword v[10:11], v45, off offset:1536
	global_store_dword v[8:9], v38, off offset:16
	global_store_dword v[12:13], v39, off offset:16
	global_store_dword v[14:15], v40, off offset:16
	global_store_dword v[6:7], v41, off offset:16
	global_store_dword v[8:9], v34, off offset:128
	global_store_dword v[12:13], v35, off offset:128
	global_store_dword v[14:15], v36, off offset:128
	global_store_dword v[6:7], v37, off offset:128
	global_store_dword v[8:9], v30, off offset:144
	global_store_dword v[12:13], v31, off offset:144
	global_store_dword v[14:15], v32, off offset:144
	global_store_dword v[6:7], v33, off offset:144
	s_and_saveexec_b64 s[0:1], vcc
	s_cbranch_execz .LBB0_317
	s_lshl_b64 s[2:3], s[16:17], 9
	v_readlane_b32 s4, v254, 26
	s_add_u32 s2, s4, s2
	v_readlane_b32 s4, v254, 27
	s_addc_u32 s3, s4, s3
	v_lshl_add_u64 v[2:3], v[2:3], 2, s[2:3]
	global_store_dwordx4 v[2:3], v[26:29], off offset:320 sc1

.LBB0_331:
	s_min_u32 s18, s20, 1
	s_lshl_b32 s27, s18, 7
	s_and_b32 s18, s20, 1
	s_mov_b32 s19, s20
	s_mul_i32 s20, s18, 0x5000
	s_add_i32 s25, s20, 0
	s_lshl_b32 s20, s18, 11
	s_add_i32 s26, s20, 0
	s_lshl_b32 s20, s18, 4
	s_add_i32 s20, s20, 0
	s_add_i32 s25, s25, 0x12000
	s_add_i32 s26, s26, 0x25a00
	s_add_i32 s37, s20, 0x26a00
	s_add_i32 s20, s19, 1
	s_waitcnt vmcnt(4)
	v_mov_b64_e32 v[60:61], v[16:17]
	s_mul_i32 s36, s18, 0x9000
	s_cmp_lt_u32 s20, s79
	v_mov_b64_e32 v[58:59], v[14:15]
	s_cselect_b32 s38, s20, s19
	v_lshl_add_u32 v15, v114, 2, s26
	s_add_i32 s19, s36, 0
	v_lshlrev_b32_e32 v192, 1, v2
	v_add_u32_e32 v15, 0xc0, v15
	v_add_u32_e32 v78, s19, v192
	s_waitcnt vmcnt(2)
	v_mov_b64_e32 v[84:85], v[24:25]
	v_mov_b64_e32 v[56:57], v[20:21]
	s_waitcnt lgkmcnt(0)
	s_barrier
	v_mov_b32_e32 v14, s26
	ds_read2st64_b32 v[108:109], v15 offset0:3 offset1:5
	v_mov_b32_e32 v15, s37
	v_add_u32_e32 v74, v78, v4
	v_mov_b64_e32 v[82:83], v[22:23]
	v_mov_b64_e32 v[54:55], v[18:19]
	ds_read_b32 v220, v14 offset:1020
	ds_read_b32 v221, v15
	ds_read_b128 v[14:17], v74
	ds_read_b128 v[18:21], v74 offset:4608
	ds_read_b128 v[22:25], v74 offset:9216
	ds_read_b128 v[62:65], v74 offset:13824
	ds_read_b128 v[66:69], v74 offset:18432
	ds_read_b128 v[70:73], v74 offset:23040
	ds_read_b128 v[74:77], v74 offset:27648
	v_add_u32_e32 v78, v78, v125
	ds_read_b128 v[78:81], v78
	v_subrev_u32_e32 v129, s27, v128
	v_add_u32_e32 v194, s27, v126
	s_mul_i32 s27, s18, 0x4a00
	s_add_i32 s27, s27, 0
	s_add_i32 s27, s27, 0x1c000
	v_add3_u32 v188, s19, v4, v192
	ds_read_b128 v[86:89], v188 offset:64
	ds_read_b128 v[90:93], v188 offset:4672
	ds_read_b128 v[94:97], v188 offset:9280
	ds_read_b128 v[98:101], v188 offset:13888
	ds_read_b128 v[110:113], v188 offset:18496
	ds_read_b128 v[130:133], v188 offset:23104
	v_add3_u32 v189, s19, v125, v192
	ds_read_b128 v[134:137], v188 offset:27712
	ds_read_b128 v[140:143], v189 offset:64
	s_waitcnt lgkmcnt(14)
	v_mfma_f32_16x16x32_bf16 v[14:17], v[14:17], v[10:13], 0
	v_mfma_f32_16x16x32_bf16 v[18:21], v[18:21], v[10:13], 0
	s_waitcnt lgkmcnt(13)
	v_mfma_f32_16x16x32_bf16 v[22:25], v[22:25], v[10:13], 0
	s_waitcnt lgkmcnt(12)
	v_mfma_f32_16x16x32_bf16 v[62:65], v[62:65], v[10:13], 0
	s_waitcnt lgkmcnt(11)
	v_mfma_f32_16x16x32_bf16 v[66:69], v[66:69], v[10:13], 0
	s_waitcnt lgkmcnt(10)
	v_mfma_f32_16x16x32_bf16 v[70:73], v[70:73], v[10:13], 0
	s_waitcnt lgkmcnt(9)
	v_mfma_f32_16x16x32_bf16 v[74:77], v[74:77], v[10:13], 0
	s_waitcnt lgkmcnt(8)
	v_mfma_f32_16x16x32_bf16 v[78:81], v[78:81], v[10:13], 0
	ds_read_b128 v[144:147], v188 offset:128
	ds_read_b128 v[148:151], v188 offset:4736
	ds_read_b128 v[152:155], v188 offset:9344
	ds_read_b128 v[168:171], v188 offset:13952
	ds_read_b128 v[172:175], v188 offset:18560
	ds_read_b128 v[176:179], v188 offset:23168
	ds_read_b128 v[180:183], v188 offset:27776
	ds_read_b128 v[184:187], v189 offset:128
	s_waitcnt lgkmcnt(14)
	v_mfma_f32_16x16x32_bf16 v[14:17], v[86:89], v[58:61], v[14:17]
	v_mfma_f32_16x16x32_bf16 v[18:21], v[90:93], v[58:61], v[18:21]
	s_waitcnt lgkmcnt(13)
	v_mfma_f32_16x16x32_bf16 v[22:25], v[94:97], v[58:61], v[22:25]
	s_waitcnt lgkmcnt(12)
	v_mfma_f32_16x16x32_bf16 v[62:65], v[98:101], v[58:61], v[62:65]
	s_waitcnt lgkmcnt(11)
	v_mfma_f32_16x16x32_bf16 v[66:69], v[110:113], v[58:61], v[66:69]
	s_waitcnt lgkmcnt(10)
	v_mfma_f32_16x16x32_bf16 v[70:73], v[130:133], v[58:61], v[70:73]
	s_waitcnt lgkmcnt(9)
	v_mfma_f32_16x16x32_bf16 v[74:77], v[134:137], v[58:61], v[74:77]
	s_waitcnt lgkmcnt(8)
	v_mfma_f32_16x16x32_bf16 v[78:81], v[140:143], v[58:61], v[78:81]
	ds_read_b128 v[86:89], v188 offset:192
	ds_read_b128 v[90:93], v188 offset:4800
	ds_read_b128 v[94:97], v188 offset:9408
	ds_read_b128 v[98:101], v188 offset:14016
	ds_read_b128 v[110:113], v188 offset:18624
	ds_read_b128 v[130:133], v188 offset:23232
	ds_read_b128 v[134:137], v188 offset:27840
	ds_read_b128 v[140:143], v189 offset:192
	s_waitcnt lgkmcnt(14)
	v_mfma_f32_16x16x32_bf16 v[14:17], v[144:147], v[54:57], v[14:17]
	v_mfma_f32_16x16x32_bf16 v[18:21], v[148:151], v[54:57], v[18:21]
	s_waitcnt lgkmcnt(13)
	v_mfma_f32_16x16x32_bf16 v[22:25], v[152:155], v[54:57], v[22:25]
	s_waitcnt lgkmcnt(12)
	v_mfma_f32_16x16x32_bf16 v[62:65], v[168:171], v[54:57], v[62:65]
	s_waitcnt lgkmcnt(11)
	v_mfma_f32_16x16x32_bf16 v[66:69], v[172:175], v[54:57], v[66:69]
	s_waitcnt lgkmcnt(10)
	v_mfma_f32_16x16x32_bf16 v[70:73], v[176:179], v[54:57], v[70:73]
	s_waitcnt lgkmcnt(9)
	v_mfma_f32_16x16x32_bf16 v[74:77], v[180:183], v[54:57], v[74:77]
	s_waitcnt lgkmcnt(8)
	v_mfma_f32_16x16x32_bf16 v[144:147], v[184:187], v[54:57], v[78:81]
	s_nop 2
	v_add3_u32 v78, s27, v192, v4
	ds_read_b128 v[148:151], v78
	ds_read_b128 v[152:155], v78 offset:4608
	ds_read_b128 v[168:171], v78 offset:9216
	ds_read_b128 v[172:175], v78 offset:13824
	ds_read_b128 v[176:179], v78 offset:18432
	s_waitcnt lgkmcnt(12)
	v_mfma_f32_16x16x32_bf16 v[180:183], v[86:89], v[82:85], v[14:17]
	s_waitcnt lgkmcnt(11)
	v_mfma_f32_16x16x32_bf16 v[184:187], v[90:93], v[82:85], v[18:21]
	s_waitcnt lgkmcnt(10)
	v_mfma_f32_16x16x32_bf16 v[188:191], v[94:97], v[82:85], v[22:25]
	s_waitcnt lgkmcnt(9)
	v_mfma_f32_16x16x32_bf16 v[90:93], v[98:101], v[82:85], v[62:65]
	s_waitcnt lgkmcnt(8)
	v_mfma_f32_16x16x32_bf16 v[86:89], v[110:113], v[82:85], v[66:69]
	s_waitcnt lgkmcnt(7)
	v_mfma_f32_16x16x32_bf16 v[78:81], v[130:133], v[82:85], v[70:73]
	s_waitcnt lgkmcnt(6)
	v_mfma_f32_16x16x32_bf16 v[74:77], v[134:137], v[82:85], v[74:77]
	s_waitcnt lgkmcnt(5)
	v_mfma_f32_16x16x32_bf16 v[70:73], v[140:143], v[82:85], v[144:147]
	v_add3_u32 v195, s27, v4, v192
	ds_read_b128 v[18:21], v195 offset:64
	ds_read_b128 v[22:25], v195 offset:4672
	ds_read_b128 v[62:65], v195 offset:9280
	ds_read_b128 v[66:69], v195 offset:13888
	ds_read_b128 v[94:97], v195 offset:18496
	v_lshl_or_b32 v14, s38, 7, v103
	v_xad_u32 v15, v14, -1, s78
	v_cndmask_b32_e64 v14, v15, v14, s[4:5]
	v_add_u32_e32 v14, s48, v14
	v_mad_i64_i32 v[192:193], s[44:45], v14, s86, v[104:105]
	s_waitcnt lgkmcnt(9)
	v_mfma_f32_16x16x32_bf16 v[98:101], v[148:151], v[10:13], 0
	s_waitcnt lgkmcnt(8)
	v_mfma_f32_16x16x32_bf16 v[110:113], v[152:155], v[10:13], 0
	s_waitcnt lgkmcnt(7)
	v_mfma_f32_16x16x32_bf16 v[130:133], v[168:171], v[10:13], 0
	s_waitcnt lgkmcnt(6)
	v_mfma_f32_16x16x32_bf16 v[134:137], v[172:175], v[10:13], 0
	s_waitcnt lgkmcnt(5)
	v_mfma_f32_16x16x32_bf16 v[140:143], v[176:179], v[10:13], 0
	global_load_dwordx4 v[10:13], v[192:193], off
	global_load_dwordx4 v[14:17], v[192:193], off offset:64
	ds_read_b128 v[144:147], v195 offset:128
	ds_read_b128 v[148:151], v195 offset:4736
	ds_read_b128 v[152:155], v195 offset:9344
	ds_read_b128 v[168:171], v195 offset:13952
	ds_read_b128 v[172:175], v195 offset:18560
	s_waitcnt lgkmcnt(9)
	v_mfma_f32_16x16x32_bf16 v[98:101], v[18:21], v[58:61], v[98:101]
	s_waitcnt lgkmcnt(8)
	v_mfma_f32_16x16x32_bf16 v[110:113], v[22:25], v[58:61], v[110:113]
	global_load_dwordx4 v[18:21], v[192:193], off offset:128
	global_load_dwordx4 v[22:25], v[192:193], off offset:192
	s_waitcnt lgkmcnt(7)
	v_mfma_f32_16x16x32_bf16 v[62:65], v[62:65], v[58:61], v[130:133]
	s_waitcnt lgkmcnt(6)
	v_mfma_f32_16x16x32_bf16 v[66:69], v[66:69], v[58:61], v[134:137]
	s_waitcnt lgkmcnt(5)
	v_mfma_f32_16x16x32_bf16 v[58:61], v[94:97], v[58:61], v[140:143]
	ds_read_b128 v[94:97], v195 offset:192
	ds_read_b128 v[130:133], v195 offset:4800
	ds_read_b128 v[134:137], v195 offset:9408
	ds_read_b128 v[140:143], v195 offset:14016
	ds_read_b128 v[176:179], v195 offset:18624
	s_waitcnt lgkmcnt(9)
	v_mfma_f32_16x16x32_bf16 v[98:101], v[144:147], v[54:57], v[98:101]
	s_waitcnt lgkmcnt(8)
	v_mfma_f32_16x16x32_bf16 v[144:147], v[148:151], v[54:57], v[110:113]
	s_waitcnt lgkmcnt(7)
	v_mfma_f32_16x16x32_bf16 v[148:151], v[152:155], v[54:57], v[62:65]
	s_nop 2
	v_cndmask_b32_e64 v62, v194, v129, s[4:5]
	v_ashrrev_i32_e32 v63, 31, v62
	v_lshl_add_u64 v[62:63], s[0:1], 0, v[62:63]
	v_lshlrev_b64 v[62:63], 11, v[62:63]
	v_lshl_add_u64 v[62:63], v[106:107], 0, v[62:63]
	s_waitcnt lgkmcnt(6)
	v_mfma_f32_16x16x32_bf16 v[152:155], v[168:171], v[54:57], v[66:69]
	global_store_dwordx4 v[62:63], v[50:53], off sc1
	global_store_dwordx4 v[62:63], v[46:49], off offset:64 sc1
	s_waitcnt lgkmcnt(5)
	v_mfma_f32_16x16x32_bf16 v[168:171], v[172:175], v[54:57], v[58:61]
	s_nop 2
	v_add3_u32 v60, s25, v115, v116
	v_add3_u32 v62, s19, v117, v127
	v_lshl_add_u32 v129, v102, 2, s26
	ds_read_b64_tr_b16 v[50:51], v60
	ds_read_b64_tr_b16 v[46:47], v60 offset:32
	ds_read_b64_tr_b16 v[54:55], v60 offset:64
	ds_read_b64_tr_b16 v[58:59], v60 offset:96
	ds_read_b64_tr_b16 v[52:53], v60 offset:2560
	ds_read_b64_tr_b16 v[48:49], v60 offset:2592
	ds_read_b64_tr_b16 v[56:57], v60 offset:2624
	ds_read_b64_tr_b16 v[60:61], v60 offset:2656
	ds_read_b64_tr_b16 v[112:113], v62 offset:128
	ds_read_b64_tr_b16 v[110:111], v62 offset:4736
	ds_read_b128 v[66:69], v129 offset:1536
	ds_read_b128 v[62:65], v129 offset:1600
	ds_read_b128 v[172:175], v129
	ds_read_b128 v[192:195], v129 offset:64
	ds_read_b128 v[196:199], v129 offset:128
	ds_read_b128 v[200:203], v129 offset:192
	ds_read_b128 v[204:207], v129 offset:256
	ds_read_b128 v[208:211], v129 offset:320
	ds_read_b128 v[212:215], v129 offset:384
	ds_read_b128 v[216:219], v129 offset:448
	s_waitcnt lgkmcnt(14)
	v_mfma_f32_16x16x32_bf16 v[94:97], v[94:97], v[82:85], v[98:101]
	v_mfma_f32_16x16x32_bf16 v[98:101], v[130:133], v[82:85], v[144:147]
	v_mfma_f32_16x16x32_bf16 v[130:133], v[134:137], v[82:85], v[148:151]
	v_mfma_f32_16x16x32_bf16 v[134:137], v[140:143], v[82:85], v[152:155]
	v_mfma_f32_16x16x32_bf16 v[140:143], v[176:179], v[82:85], v[168:171]
	s_waitcnt lgkmcnt(4)
	s_nop 0
	v_fmamk_f32 v152, v108, 0xbfb8aa3b, v200
	v_fmamk_f32 v153, v108, 0xbfb8aa3b, v201
	v_exp_f32_e32 v152, v152
	v_exp_f32_e32 v153, v153
	v_fmamk_f32 v154, v108, 0xbfb8aa3b, v202
	v_exp_f32_e32 v154, v154
	v_mul_f32_e32 v90, v90, v152
	v_mul_f32_e32 v91, v91, v153
	s_waitcnt lgkmcnt(3)
	v_fmamk_f32 v152, v108, 0xbfb8aa3b, v204
	v_fmamk_f32 v153, v108, 0xbfb8aa3b, v205
	v_fmac_f32_e32 v203, 0xbfb8aa3b, v108
	v_exp_f32_e32 v152, v152
	v_exp_f32_e32 v153, v153
	v_exp_f32_e32 v155, v203
	v_mul_f32_e32 v92, v92, v154
	v_fmamk_f32 v154, v108, 0xbfb8aa3b, v206
	v_exp_f32_e32 v154, v154
	v_fmac_f32_e32 v207, 0xbfb8aa3b, v108
	v_mul_f32_e32 v86, v86, v152
	v_mul_f32_e32 v87, v87, v153
	s_waitcnt lgkmcnt(2)
	v_fmamk_f32 v152, v108, 0xbfb8aa3b, v208
	v_fmamk_f32 v153, v108, 0xbfb8aa3b, v209
	v_mul_f32_e32 v93, v93, v155
	v_exp_f32_e32 v155, v207
	v_exp_f32_e32 v152, v152
	v_exp_f32_e32 v153, v153
	v_sub_f32_e32 v82, v221, v108
	v_mul_f32_e32 v88, v88, v154
	v_fmamk_f32 v154, v108, 0xbfb8aa3b, v210
	v_mul_f32_e32 v82, 0x3fb8aa3b, v82
	v_exp_f32_e32 v154, v154
	v_exp_f32_e32 v144, v82
	v_sub_f32_e32 v82, v221, v220
	v_fmac_f32_e32 v211, 0xbfb8aa3b, v108
	v_mul_f32_e32 v82, 0x3fb8aa3b, v82
	v_mul_f32_e32 v89, v89, v155
	v_exp_f32_e32 v155, v211
	v_mul_f32_e32 v152, v78, v152
	v_mul_f32_e32 v153, v79, v153
	s_waitcnt lgkmcnt(1)
	v_fmamk_f32 v78, v108, 0xbfb8aa3b, v212
	v_fmamk_f32 v79, v108, 0xbfb8aa3b, v213
	v_exp_f32_e32 v146, v82
	v_exp_f32_e32 v78, v78
	v_exp_f32_e32 v79, v79
	v_mul_f32_e32 v154, v80, v154
	v_fmamk_f32 v80, v108, 0xbfb8aa3b, v214
	v_exp_f32_e32 v80, v80
	v_fmac_f32_e32 v215, 0xbfb8aa3b, v108
	v_mul_f32_e32 v81, v81, v155
	v_exp_f32_e32 v155, v215
	v_pk_mul_f32 v[84:85], v[144:145], v[96:97] op_sel_hi:[0,1]
	v_pk_mul_f32 v[96:97], v[144:145], v[100:101] op_sel_hi:[0,1]
	v_pk_mul_f32 v[100:101], v[28:29], v[146:147] op_sel_hi:[1,0]
	v_fmamk_f32 v28, v108, 0xbfb8aa3b, v174
	v_fmac_f32_e32 v175, 0xbfb8aa3b, v108
	v_mul_f32_e32 v168, v74, v78
	v_mul_f32_e32 v169, v75, v79
	s_waitcnt lgkmcnt(0)
	v_fmamk_f32 v74, v108, 0xbfb8aa3b, v216
	v_fmamk_f32 v75, v108, 0xbfb8aa3b, v217
	v_exp_f32_e32 v28, v28
	v_exp_f32_e32 v29, v175
	v_exp_f32_e32 v74, v74
	v_exp_f32_e32 v75, v75
	v_mul_f32_e32 v170, v76, v80
	v_fmamk_f32 v76, v108, 0xbfb8aa3b, v218
	v_fmac_f32_e32 v219, 0xbfb8aa3b, v108
	v_mul_f32_e32 v155, v77, v155
	v_exp_f32_e32 v76, v76
	v_exp_f32_e32 v77, v219
	v_pk_mul_f32 v[82:83], v[144:145], v[94:95] op_sel_hi:[0,1]
	v_pk_mul_f32 v[94:95], v[144:145], v[98:99] op_sel_hi:[0,1]
	v_pk_mul_f32 v[98:99], v[26:27], v[146:147] op_sel_hi:[1,0]
	v_fmamk_f32 v26, v108, 0xbfb8aa3b, v172
	v_fmamk_f32 v27, v108, 0xbfb8aa3b, v173
	v_pk_mul_f32 v[44:45], v[44:45], v[146:147] op_sel_hi:[1,0]
	v_pk_mul_f32 v[42:43], v[42:43], v[146:147] op_sel_hi:[1,0]
	v_pk_mul_f32 v[40:41], v[40:41], v[146:147] op_sel_hi:[1,0]
	v_pk_mul_f32 v[38:39], v[38:39], v[146:147] op_sel_hi:[1,0]
	v_pk_mul_f32 v[132:133], v[144:145], v[132:133] op_sel_hi:[0,1]
	v_pk_mul_f32 v[130:131], v[144:145], v[130:131] op_sel_hi:[0,1]
	v_pk_mul_f32 v[36:37], v[36:37], v[146:147] op_sel_hi:[1,0]
	v_pk_mul_f32 v[34:35], v[34:35], v[146:147] op_sel_hi:[1,0]
	v_pk_mul_f32 v[136:137], v[144:145], v[136:137] op_sel_hi:[0,1]
	v_pk_mul_f32 v[134:135], v[144:145], v[134:135] op_sel_hi:[0,1]
	v_pk_mul_f32 v[32:33], v[32:33], v[146:147] op_sel_hi:[1,0]
	v_pk_mul_f32 v[30:31], v[30:31], v[146:147] op_sel_hi:[1,0]
	v_pk_mul_f32 v[142:143], v[144:145], v[142:143] op_sel_hi:[0,1]
	v_pk_mul_f32 v[140:141], v[144:145], v[140:141] op_sel_hi:[0,1]
	v_exp_f32_e32 v26, v26
	v_exp_f32_e32 v27, v27
	v_mul_f32_e32 v28, v182, v28
	v_mul_f32_e32 v29, v183, v29
	v_fmamk_f32 v144, v108, 0xbfb8aa3b, v192
	v_fmamk_f32 v145, v108, 0xbfb8aa3b, v193
	v_fmamk_f32 v146, v108, 0xbfb8aa3b, v194
	v_fmac_f32_e32 v195, 0xbfb8aa3b, v108
	v_fmamk_f32 v148, v108, 0xbfb8aa3b, v196
	v_fmamk_f32 v149, v108, 0xbfb8aa3b, v197
	v_fmamk_f32 v150, v108, 0xbfb8aa3b, v198
	v_fmac_f32_e32 v199, 0xbfb8aa3b, v108
	v_mul_f32_e32 v108, v70, v74
	v_mul_f32_e32 v171, v71, v75
	v_exp_f32_e32 v144, v144
	v_exp_f32_e32 v145, v145
	v_exp_f32_e32 v146, v146
	v_exp_f32_e32 v147, v195
	v_exp_f32_e32 v148, v148
	v_exp_f32_e32 v149, v149
	v_exp_f32_e32 v150, v150
	v_exp_f32_e32 v151, v199
	v_cvt_pk_bf16_f32 v71, v28, v29
	v_cvt_pk_bf16_f32 v28, v108, s0
	v_cvt_pk_bf16_f32 v29, v171, s0
	v_mul_f32_e32 v172, v72, v76
	v_mul_f32_e32 v173, v73, v77
	v_cndmask_b32_e64 v28, v28, 0, s[6:7]
	v_cndmask_b32_e64 v29, 0, v29, s[8:9]
	v_cvt_pk_bf16_f32 v78, v86, v87
	v_perm_b32 v28, v29, v28, s89
	v_cvt_pk_bf16_f32 v29, v172, s0
	v_cvt_pk_bf16_f32 v86, v173, s0
	v_mul_f32_e32 v26, v180, v26
	v_mul_f32_e32 v27, v181, v27
	v_cndmask_b32_e64 v29, v29, 0, s[10:11]
	v_cndmask_b32_e64 v86, v86, 0, s[12:13]
	v_mul_f32_e32 v144, v184, v144
	v_mul_f32_e32 v145, v185, v145
	v_mul_f32_e32 v146, v186, v146
	v_mul_f32_e32 v147, v187, v147
	v_mul_f32_e32 v148, v188, v148
	v_mul_f32_e32 v149, v189, v149
	v_mul_f32_e32 v150, v190, v150
	v_mul_f32_e32 v151, v191, v151
	v_cvt_pk_bf16_f32 v70, v26, v27
	v_cvt_pk_bf16_f32 v26, v168, v169
	v_cvt_pk_bf16_f32 v27, v170, v155
	v_perm_b32 v29, v86, v29, s89
	v_cvt_pk_bf16_f32 v72, v144, v145
	v_cvt_pk_bf16_f32 v73, v146, v147
	v_cvt_pk_bf16_f32 v74, v148, v149
	v_cvt_pk_bf16_f32 v75, v150, v151
	v_cvt_pk_bf16_f32 v76, v90, v91
	v_cvt_pk_bf16_f32 v77, v92, v93
	v_cvt_pk_bf16_f32 v79, v88, v89
	v_cvt_pk_bf16_f32 v80, v152, v153
	v_cvt_pk_bf16_f32 v81, v154, v81
	v_add3_u32 v108, s25, v118, v127
	ds_read_b64_tr_b16 v[86:87], v108
	ds_read_b64_tr_b16 v[90:91], v108 offset:32
	ds_read_b64_tr_b16 v[144:145], v108 offset:64
	ds_read_b64_tr_b16 v[148:149], v108 offset:96
	ds_read_b64_tr_b16 v[88:89], v108 offset:2560
	ds_read_b64_tr_b16 v[92:93], v108 offset:2592
	ds_read_b64_tr_b16 v[146:147], v108 offset:2624
	ds_read_b64_tr_b16 v[150:151], v108 offset:2656
	v_add3_u32 v108, s19, v119, v127
	ds_read_b64_tr_b16 v[172:173], v108 offset:128
	ds_read_b64_tr_b16 v[174:175], v108 offset:4736
	ds_read_b128 v[152:155], v129 offset:1664
	ds_read_b128 v[168:171], v129 offset:1728
	v_lshlrev_b32_e32 v108, 16, v112
	v_mul_f32_e32 v66, v66, v108
	v_and_b32_e32 v108, 0xffff0000, v112
	v_mul_f32_e32 v67, v67, v108
	v_cvt_pk_bf16_f32 v66, v66, v67
	v_lshlrev_b32_e32 v67, 16, v113
	v_mul_f32_e32 v67, v68, v67
	v_and_b32_e32 v68, 0xffff0000, v113
	v_mul_f32_e32 v68, v69, v68
	v_cvt_pk_bf16_f32 v67, v67, v68
	v_lshlrev_b32_e32 v68, 16, v110
	v_mul_f32_e32 v62, v62, v68
	v_and_b32_e32 v68, 0xffff0000, v110
	v_mul_f32_e32 v63, v63, v68
	v_cvt_pk_bf16_f32 v68, v62, v63
	v_lshlrev_b32_e32 v62, 16, v111
	v_and_b32_e32 v63, 0xffff0000, v111
	v_mul_f32_e32 v62, v64, v62
	v_mul_f32_e32 v63, v65, v63
	v_cvt_pk_bf16_f32 v69, v62, v63
	v_mfma_f32_16x16x32_bf16 v[94:97], v[46:49], v[70:73], v[94:97]
	s_nop 0
	v_mfma_f32_16x16x32_bf16 v[42:45], v[66:69], v[50:53], v[42:45]
	v_mfma_f32_16x16x32_bf16 v[38:41], v[66:69], v[46:49], v[38:41]
	v_mfma_f32_16x16x32_bf16 v[34:37], v[66:69], v[54:57], v[34:37]
	v_mfma_f32_16x16x32_bf16 v[30:33], v[66:69], v[58:61], v[30:33]
	v_mfma_f32_16x16x32_bf16 v[46:49], v[66:69], v[6:9], v[98:101]
	v_mfma_f32_16x16x32_bf16 v[82:85], v[50:53], v[70:73], v[82:85]
	v_mfma_f32_16x16x32_bf16 v[130:133], v[54:57], v[70:73], v[130:133]
	v_mfma_f32_16x16x32_bf16 v[134:137], v[58:61], v[70:73], v[134:137]
	v_mfma_f32_16x16x32_bf16 v[70:73], v[6:9], v[70:73], v[140:143]
	v_add3_u32 v64, s25, v120, v127
	ds_read_b64_tr_b16 v[50:51], v64
	ds_read_b64_tr_b16 v[54:55], v64 offset:32
	ds_read_b64_tr_b16 v[58:59], v64 offset:64
	ds_read_b64_tr_b16 v[62:63], v64 offset:96
	ds_read_b64_tr_b16 v[52:53], v64 offset:2560
	ds_read_b64_tr_b16 v[56:57], v64 offset:2592
	ds_read_b64_tr_b16 v[60:61], v64 offset:2624
	ds_read_b64_tr_b16 v[64:65], v64 offset:2656
	v_add3_u32 v66, s19, v121, v127
	ds_read_b64_tr_b16 v[176:177], v66 offset:128
	ds_read_b64_tr_b16 v[178:179], v66 offset:4736
	ds_read_b128 v[66:69], v129 offset:1792
	ds_read_b128 v[98:101], v129 offset:1856
	s_waitcnt lgkmcnt(14)
	v_mfma_f32_16x16x32_bf16 v[82:85], v[86:89], v[74:77], v[82:85]
	v_and_b32_e32 v108, 0xffff0000, v175
	s_waitcnt lgkmcnt(12)
	v_mul_f32_e32 v108, v171, v108
	v_mfma_f32_16x16x32_bf16 v[94:97], v[90:93], v[74:77], v[94:97]
	v_mfma_f32_16x16x32_bf16 v[110:113], v[144:147], v[74:77], v[130:133]
	v_mfma_f32_16x16x32_bf16 v[130:133], v[148:151], v[74:77], v[134:137]
	v_mfma_f32_16x16x32_bf16 v[70:73], v[6:9], v[74:77], v[70:73]
	v_lshlrev_b32_e32 v74, 16, v172
	v_and_b32_e32 v75, 0xffff0000, v172
	v_mul_f32_e32 v74, v152, v74
	v_mul_f32_e32 v75, v153, v75
	v_cvt_pk_bf16_f32 v74, v74, v75
	v_lshlrev_b32_e32 v75, 16, v173
	v_and_b32_e32 v76, 0xffff0000, v173
	v_mul_f32_e32 v75, v154, v75
	v_mul_f32_e32 v76, v155, v76
	v_cvt_pk_bf16_f32 v75, v75, v76
	v_lshlrev_b32_e32 v76, 16, v174
	v_and_b32_e32 v77, 0xffff0000, v174
	v_mul_f32_e32 v76, v168, v76
	v_mul_f32_e32 v77, v169, v77
	v_cvt_pk_bf16_f32 v76, v76, v77
	v_lshlrev_b32_e32 v77, 16, v175
	v_mul_f32_e32 v77, v170, v77
	v_cvt_pk_bf16_f32 v77, v77, v108
	s_nop 1
	v_mfma_f32_16x16x32_bf16 v[42:45], v[74:77], v[86:89], v[42:45]
	v_mfma_f32_16x16x32_bf16 v[38:41], v[74:77], v[90:93], v[38:41]
	v_mfma_f32_16x16x32_bf16 v[34:37], v[74:77], v[144:147], v[34:37]
	v_mfma_f32_16x16x32_bf16 v[30:33], v[74:77], v[148:151], v[30:33]
	v_mfma_f32_16x16x32_bf16 v[46:49], v[74:77], v[6:9], v[46:49]
	v_add3_u32 v108, s25, v122, v127
	ds_read_b64_tr_b16 v[74:75], v108
	ds_read_b64_tr_b16 v[86:87], v108 offset:32
	ds_read_b64_tr_b16 v[90:91], v108 offset:64
	ds_read_b64_tr_b16 v[134:135], v108 offset:96
	ds_read_b64_tr_b16 v[76:77], v108 offset:2560
	ds_read_b64_tr_b16 v[88:89], v108 offset:2592
	ds_read_b64_tr_b16 v[92:93], v108 offset:2624
	ds_read_b64_tr_b16 v[136:137], v108 offset:2656
	v_add3_u32 v108, s19, v123, v127
	ds_read_b64_tr_b16 v[148:149], v108 offset:128
	ds_read_b64_tr_b16 v[150:151], v108 offset:4736
	ds_read_b128 v[140:143], v129 offset:1920
	ds_read_b128 v[144:147], v129 offset:1984
	s_waitcnt lgkmcnt(14)
	v_mfma_f32_16x16x32_bf16 v[82:85], v[50:53], v[78:81], v[82:85]
	v_mfma_f32_16x16x32_bf16 v[94:97], v[54:57], v[78:81], v[94:97]
	v_mfma_f32_16x16x32_bf16 v[110:113], v[58:61], v[78:81], v[110:113]
	v_mfma_f32_16x16x32_bf16 v[130:133], v[62:65], v[78:81], v[130:133]
	v_mfma_f32_16x16x32_bf16 v[70:73], v[6:9], v[78:81], v[70:73]
	v_lshlrev_b32_e32 v78, 16, v176
	s_waitcnt lgkmcnt(13)
	v_mul_f32_e32 v66, v66, v78
	v_and_b32_e32 v78, 0xffff0000, v176
	v_mul_f32_e32 v67, v67, v78
	v_cvt_pk_bf16_f32 v66, v66, v67
	v_lshlrev_b32_e32 v67, 16, v177
	v_mul_f32_e32 v67, v68, v67
	v_and_b32_e32 v68, 0xffff0000, v177
	v_mul_f32_e32 v68, v69, v68
	v_cvt_pk_bf16_f32 v67, v67, v68
	v_lshlrev_b32_e32 v68, 16, v178
	v_and_b32_e32 v69, 0xffff0000, v178
	s_waitcnt lgkmcnt(12)
	v_mul_f32_e32 v68, v98, v68
	v_mul_f32_e32 v69, v99, v69
	v_cvt_pk_bf16_f32 v68, v68, v69
	v_lshlrev_b32_e32 v69, 16, v179
	v_and_b32_e32 v78, 0xffff0000, v179
	v_mul_f32_e32 v69, v100, v69
	v_mul_f32_e32 v78, v101, v78
	v_cvt_pk_bf16_f32 v69, v69, v78
	s_nop 1
	v_mfma_f32_16x16x32_bf16 v[42:45], v[66:69], v[50:53], v[42:45]
	v_mfma_f32_16x16x32_bf16 v[38:41], v[66:69], v[54:57], v[38:41]
	v_mfma_f32_16x16x32_bf16 v[34:37], v[66:69], v[58:61], v[34:37]
	v_mfma_f32_16x16x32_bf16 v[30:33], v[66:69], v[62:65], v[30:33]
	v_mfma_f32_16x16x32_bf16 v[62:65], v[66:69], v[6:9], v[46:49]
	s_waitcnt lgkmcnt(7)
	v_mfma_f32_16x16x32_bf16 v[50:53], v[74:77], v[26:29], v[82:85]
	s_waitcnt lgkmcnt(6)
	v_mfma_f32_16x16x32_bf16 v[58:61], v[86:89], v[26:29], v[94:97]
	s_waitcnt lgkmcnt(5)
	v_mfma_f32_16x16x32_bf16 v[46:49], v[90:93], v[26:29], v[110:113]
	s_waitcnt lgkmcnt(4)
	v_mfma_f32_16x16x32_bf16 v[54:57], v[134:137], v[26:29], v[130:133]
	v_mfma_f32_16x16x32_bf16 v[66:69], v[6:9], v[26:29], v[70:73]
	s_waitcnt lgkmcnt(3)
	v_lshlrev_b32_e32 v26, 16, v148
	v_and_b32_e32 v27, 0xffff0000, v148
	s_waitcnt lgkmcnt(1)
	v_mul_f32_e32 v26, v140, v26
	v_mul_f32_e32 v27, v141, v27
	v_cvt_pk_bf16_f32 v26, v26, v27
	v_lshlrev_b32_e32 v27, 16, v149
	v_and_b32_e32 v28, 0xffff0000, v149
	v_mul_f32_e32 v27, v142, v27
	v_mul_f32_e32 v28, v143, v28
	v_cvt_pk_bf16_f32 v27, v27, v28
	v_lshlrev_b32_e32 v28, 16, v150
	v_and_b32_e32 v29, 0xffff0000, v150
	s_waitcnt lgkmcnt(0)
	v_mul_f32_e32 v28, v144, v28
	v_mul_f32_e32 v29, v145, v29
	v_cvt_pk_bf16_f32 v28, v28, v29
	v_lshlrev_b32_e32 v29, 16, v151
	v_and_b32_e32 v67, 0xffff0000, v151
	v_mul_f32_e32 v29, v146, v29
	v_mul_f32_e32 v67, v147, v67
	v_cvt_pk_bf16_f32 v29, v29, v67
	s_nop 1
	v_mfma_f32_16x16x32_bf16 v[42:45], v[26:29], v[74:77], v[42:45]
	v_mfma_f32_16x16x32_bf16 v[38:41], v[26:29], v[86:89], v[38:41]
	v_mfma_f32_16x16x32_bf16 v[34:37], v[26:29], v[90:93], v[34:37]
	v_mfma_f32_16x16x32_bf16 v[30:33], v[26:29], v[134:137], v[30:33]
	v_mfma_f32_16x16x32_bf16 v[26:29], v[26:29], v[6:9], v[62:65]
	s_xor_b32 s18, s18, 1
	s_mulk_i32 s18, 0x4a00
	s_add_i32 s25, s18, 0
	v_lshlrev_b32_e32 v63, 1, v102
	ds_bpermute_b32 v62, v124, v66
	v_add3_u32 v63, s25, v4, v63
	v_cvt_pk_bf16_f32 v64, v42, v43
	v_cvt_pk_bf16_f32 v65, v44, v45
	v_add_u32_e32 v66, 0x1c080, v63
	ds_write_b64 v66, v[64:65]
	v_cvt_pk_bf16_f32 v64, v38, v39
	v_cvt_pk_bf16_f32 v65, v40, v41
	v_add_u32_e32 v66, 0x1d280, v63
	ds_write_b64 v66, v[64:65]
	v_cvt_pk_bf16_f32 v64, v34, v35
	v_cvt_pk_bf16_f32 v65, v36, v37
	v_add_u32_e32 v66, 0x1e480, v63
	ds_write_b64 v66, v[64:65]
	v_cvt_pk_bf16_f32 v64, v30, v31
	v_cvt_pk_bf16_f32 v65, v32, v33
	v_add_u32_e32 v63, 0x1f680, v63
	ds_write_b64 v63, v[64:65]
	s_and_saveexec_b64 s[18:19], s[2:3]
	s_cbranch_execz .LBB0_330
	v_lshl_add_u32 v63, v102, 1, s25
	v_cvt_pk_bf16_f32 v64, v26, v27
	v_cvt_pk_bf16_f32 v65, v28, v29
	v_add_u32_e32 v63, 0x20880, v63
	ds_write_b64 v63, v[64:65]
	s_branch .LBB0_330
.LBB0_333:
	s_add_i32 s2, s78, 0xffffff80
	v_or_b32_e32 v4, s2, v103
	v_xad_u32 v6, v4, -1, s78
	v_cndmask_b32_e64 v6, v6, v4, s[4:5]
	v_ashrrev_i32_e32 v7, 31, v6
	v_lshl_add_u64 v[6:7], s[0:1], 0, v[6:7]
	v_lshlrev_b64 v[6:7], 11, v[6:7]
	v_lshl_add_u64 v[6:7], s[42:43], 0, v[6:7]
	s_lshl_b32 s68, s17, 1
	v_lshl_add_u64 v[6:7], v[6:7], 0, s[68:69]
	s_lshl_b32 s68, s21, 1
	v_lshl_add_u64 v[6:7], v[6:7], 0, s[68:69]
	v_lshl_add_u64 v[2:3], v[2:3], 1, v[6:7]
	s_and_b64 vcc, exec, s[46:47]
	global_store_dwordx4 v[2:3], v[50:53], off sc1
	global_store_dwordx4 v[2:3], v[46:49], off offset:64 sc1
	s_cbranch_vccz .LBB0_337
	s_waitcnt vmcnt(6)
	v_mbcnt_lo_u32_b32 v16, -1, 0
	v_mbcnt_hi_u32_b32 v16, -1, v16
	s_ashr_i32 s17, s16, 31
	v_lshlrev_b32_e32 v3, 1, v16
	v_ashrrev_i32_e32 v2, 2, v16
	v_and_b32_e32 v3, 24, v3
	v_and_b32_e32 v4, 3, v16
	s_lshl_b64 s[0:1], s[16:17], 16
	v_and_b32_e32 v2, -4, v2
	v_or3_b32 v3, v4, v3, s21
	s_add_u32 s0, s76, s0
	v_lshlrev_b32_e32 v4, 2, v3
	v_ashrrev_i32_e32 v3, 31, v2
	s_addc_u32 s1, s77, s1
	v_lshlrev_b64 v[6:7], 9, v[2:3]
	v_lshl_add_u64 v[6:7], s[0:1], 0, v[6:7]
	v_lshl_add_u64 v[6:7], v[6:7], 0, v[4:5]
	s_mov_b64 s[0:1], 0x8000
	v_lshl_add_u64 v[8:9], v[6:7], 0, s[0:1]
	s_mov_b32 s0, 0x8000
	v_add_co_u32_e32 v10, vcc, s0, v6
	s_mov_b64 s[0:1], 0x8200
	s_nop 0
	v_addc_co_u32_e32 v11, vcc, 0, v7, vcc
	v_lshl_add_u64 v[12:13], v[6:7], 0, s[0:1]
	s_mov_b64 s[0:1], 0x8400
	v_and_or_b32 v4, v16, 15, s31
	v_lshl_add_u64 v[14:15], v[6:7], 0, s[0:1]
	s_mov_b64 s[0:1], 0x8600
	v_cmp_eq_u32_e32 vcc, 0, v4
	global_store_dword v[10:11], v42, off
	global_store_dword v[10:11], v43, off offset:512
	global_store_dword v[10:11], v44, off offset:1024
	v_lshl_add_u64 v[6:7], v[6:7], 0, s[0:1]
	global_store_dword v[10:11], v45, off offset:1536
	global_store_dword v[8:9], v38, off offset:16
	global_store_dword v[12:13], v39, off offset:16
	global_store_dword v[14:15], v40, off offset:16
	global_store_dword v[6:7], v41, off offset:16
	global_store_dword v[8:9], v34, off offset:128
	global_store_dword v[12:13], v35, off offset:128
	global_store_dword v[14:15], v36, off offset:128
	global_store_dword v[6:7], v37, off offset:128
	global_store_dword v[8:9], v30, off offset:144
	global_store_dword v[12:13], v31, off offset:144
	global_store_dword v[14:15], v32, off offset:144
	global_store_dword v[6:7], v33, off offset:144
	s_and_saveexec_b64 s[0:1], vcc
	s_cbranch_execz .LBB0_336
	s_lshl_b64 s[2:3], s[16:17], 9
	v_readlane_b32 s4, v254, 26
	s_add_u32 s2, s4, s2
	v_readlane_b32 s4, v254, 27
	s_addc_u32 s3, s4, s3
	v_lshl_add_u64 v[2:3], v[2:3], 2, s[2:3]
	global_store_dwordx4 v[2:3], v[26:29], off offset:256 sc1

.LBB0_356:
	s_mov_b32 s19, s17
	s_min_u32 s17, s17, 1
	s_lshl_b32 s17, s17, 7
	s_and_b32 s20, s19, 1
	v_subrev_u32_e32 v130, s17, v188
	v_add_u32_e32 v131, s17, v143
	s_mul_i32 s17, s20, 0x9000
	s_add_i32 s21, s17, 0
	s_mul_i32 s17, s20, 0x5000
	s_waitcnt vmcnt(6)
	v_mov_b64_e32 v[112:113], v[88:89]
	s_add_i32 s26, s17, 0
	v_mov_b64_e32 v[110:111], v[86:87]
	s_add_i32 s26, s26, 0x12000
	v_add3_u32 v86, s21, v142, v183
	ds_write_b128 v86, v[10:13]
	ds_write_b128 v86, v[14:17] offset:4608
	ds_write_b128 v86, v[42:45] offset:9216
	ds_write_b128 v86, v[46:49] offset:13824
	ds_write_b128 v86, v[50:53] offset:18432
	ds_write_b128 v86, v[54:57] offset:23040
	ds_write_b128 v86, v[58:61] offset:27648
	ds_write_b128 v86, v[62:65] offset:32256
	v_lshl_add_u32 v10, v172, 1, s26
	s_lshl_b32 s17, s20, 11
	v_add3_u32 v10, v10, v186, v184
	s_add_i32 s27, s17, 0
	v_add_u32_e32 v11, 0x1000, v10
	s_add_i32 s27, s27, 0x25a00
	s_lshl_b32 s17, s20, 4
	ds_write2_b64 v11, v[66:67], v[68:69] offset0:128 offset1:132
	v_add_u32_e32 v11, 0x2800, v10
	s_waitcnt vmcnt(5)
	ds_write2_b64 v11, v[78:79], v[80:81] offset1:4
	s_add_i32 s17, s17, 0
	v_lshl_add_u32 v11, v168, 2, s27
	v_lshlrev_b32_e32 v136, 1, v2
	ds_write2_b64 v10, v[70:71], v[72:73] offset1:4
	v_add_u32_e32 v10, 0x3800, v10
	s_add_i32 s37, s17, 0x26a00
	v_add_u32_e32 v11, 0xc0, v11
	v_add_u32_e32 v46, s21, v136
	s_waitcnt vmcnt(4)
	ds_write2_b64 v10, v[82:83], v[84:85] offset0:128 offset1:132
	s_waitcnt lgkmcnt(0)
	s_barrier
	v_mov_b32_e32 v10, s27
	ds_read2st64_b32 v[150:151], v11 offset0:2 offset1:4
	v_mov_b32_e32 v11, s37
	v_add_u32_e32 v42, v46, v141
	ds_read_b32 v189, v10 offset:1020
	ds_read_b32 v246, v11
	ds_read_b128 v[10:13], v42
	ds_read_b128 v[14:17], v42 offset:4608
	ds_read_b128 v[42:45], v42 offset:9216
	v_add_u32_e32 v46, v46, v185
	ds_read_b128 v[46:49], v46
	s_add_i32 s17, s19, 1
	s_mul_i32 s36, s20, 0x4a00
	s_cmp_lt_u32 s17, s79
	s_waitcnt vmcnt(3)
	v_mov_b64_e32 v[108:109], v[92:93]
	s_waitcnt vmcnt(2)
	v_mov_b64_e32 v[104:105], v[96:97]
	s_cselect_b32 s37, s17, s19
	s_add_i32 s19, s36, 0
	v_mov_b64_e32 v[106:107], v[90:91]
	v_mov_b64_e32 v[102:103], v[94:95]
	s_add_i32 s19, s19, 0x1c000
	v_add3_u32 v94, s21, v141, v136
	ds_read_b128 v[50:53], v94 offset:64
	ds_read_b128 v[54:57], v94 offset:4672
	v_add3_u32 v114, s21, v185, v136
	ds_read_b128 v[58:61], v94 offset:9280
	ds_read_b128 v[62:65], v114 offset:64
	s_lshl_b32 s44, s37, 7
	s_waitcnt lgkmcnt(6)
	v_mfma_f32_16x16x32_bf16 v[70:73], v[14:17], v[34:37], 0
	v_or_b32_e32 v137, s44, v170
	v_bitop3_b32 v15, s44, v156, v170 bitop3:0x36
	v_or_b32_e32 v14, 16, v137
	v_mfma_f32_16x16x32_bf16 v[66:69], v[10:13], v[34:37], 0
	v_xad_u32 v10, v137, -1, s78
	v_add_u32_e32 v15, s78, v15
	v_cndmask_b32_e64 v10, v10, v137, s[4:5]
	v_cndmask_b32_e64 v14, v15, v14, s[4:5]
	v_add_u32_e32 v10, s48, v10
	v_add_u32_e32 v14, s48, v14
	v_mad_i64_i32 v[10:11], s[56:57], v10, s86, v[148:149]
	v_mad_i64_i32 v[14:15], s[56:57], v14, s86, v[148:149]
	global_load_dwordx4 v[10:13], v[10:11], off offset:2048
	s_waitcnt lgkmcnt(5)
	v_mfma_f32_16x16x32_bf16 v[42:45], v[42:45], v[34:37], 0
	global_load_dwordx4 v[14:17], v[14:15], off offset:2048
	s_waitcnt lgkmcnt(4)
	v_mfma_f32_16x16x32_bf16 v[46:49], v[46:49], v[34:37], 0
	ds_read_b128 v[78:81], v94 offset:128
	ds_read_b128 v[82:85], v94 offset:4736
	ds_read_b128 v[86:89], v94 offset:9344
	ds_read_b128 v[90:93], v114 offset:128
	s_waitcnt lgkmcnt(5)
	v_mfma_f32_16x16x32_bf16 v[58:61], v[58:61], v[110:113], v[42:45]
	s_waitcnt lgkmcnt(4)
	v_mfma_f32_16x16x32_bf16 v[62:65], v[62:65], v[110:113], v[46:49]
	s_nop 0
	v_bitop3_b32 v43, s44, v157, v170 bitop3:0x36
	v_or_b32_e32 v42, 32, v137
	v_add_u32_e32 v43, s78, v43
	v_bitop3_b32 v47, s44, v158, v170 bitop3:0x36
	v_or_b32_e32 v46, 48, v137
	v_add_u32_e32 v47, s78, v47
	v_cndmask_b32_e64 v42, v43, v42, s[4:5]
	v_cndmask_b32_e64 v46, v47, v46, s[4:5]
	v_add_u32_e32 v42, s48, v42
	v_add_u32_e32 v46, s48, v46
	v_mad_i64_i32 v[42:43], s[56:57], v42, s86, v[148:149]
	v_mad_i64_i32 v[46:47], s[56:57], v46, s86, v[148:149]
	global_load_dwordx4 v[42:45], v[42:43], off offset:2048
	v_mfma_f32_16x16x32_bf16 v[50:53], v[50:53], v[110:113], v[66:69]
	global_load_dwordx4 v[46:49], v[46:47], off offset:2048
	v_mfma_f32_16x16x32_bf16 v[54:57], v[54:57], v[110:113], v[70:73]
	s_nop 0
	ds_read_b128 v[66:69], v94 offset:192
	s_nop 0
	ds_read_b128 v[70:73], v94 offset:4800
	ds_read_b128 v[94:97], v94 offset:9408
	ds_read_b128 v[114:117], v114 offset:192
	s_waitcnt lgkmcnt(7)
	v_mfma_f32_16x16x32_bf16 v[78:81], v[78:81], v[106:109], v[50:53]
	s_waitcnt lgkmcnt(6)
	v_mfma_f32_16x16x32_bf16 v[82:85], v[82:85], v[106:109], v[54:57]
	s_nop 0
	v_bitop3_b32 v51, s44, v159, v170 bitop3:0x36
	v_or_b32_e32 v50, 64, v137
	v_add_u32_e32 v51, s78, v51
	v_bitop3_b32 v55, s44, v160, v170 bitop3:0x36
	v_or_b32_e32 v54, 0x50, v137
	v_add_u32_e32 v55, s78, v55
	v_cndmask_b32_e64 v50, v51, v50, s[4:5]
	v_cndmask_b32_e64 v54, v55, v54, s[4:5]
	v_add_u32_e32 v50, s48, v50
	v_add_u32_e32 v54, s48, v54
	v_mad_i64_i32 v[50:51], s[56:57], v50, s86, v[148:149]
	v_mad_i64_i32 v[54:55], s[56:57], v54, s86, v[148:149]
	global_load_dwordx4 v[50:53], v[50:51], off offset:2048
	s_waitcnt lgkmcnt(5)
	v_mfma_f32_16x16x32_bf16 v[58:61], v[86:89], v[106:109], v[58:61]
	global_load_dwordx4 v[54:57], v[54:55], off offset:2048
	s_waitcnt lgkmcnt(4)
	v_mfma_f32_16x16x32_bf16 v[62:65], v[90:93], v[106:109], v[62:65]
	v_add_u32_e32 v118, s19, v136
	v_add_u32_e32 v119, v118, v141
	v_add_u32_e32 v118, v118, v185
	ds_read_b128 v[86:89], v119
	ds_read_b128 v[90:93], v119 offset:4608
	ds_read_b128 v[132:135], v118
	ds_read_b128 v[152:155], v119 offset:9216
	ds_read_b128 v[190:193], v119 offset:18432
	s_waitcnt lgkmcnt(6)
	v_mfma_f32_16x16x32_bf16 v[118:121], v[94:97], v[102:105], v[58:61]
	s_waitcnt lgkmcnt(5)
	v_mfma_f32_16x16x32_bf16 v[114:117], v[114:117], v[102:105], v[62:65]
	s_nop 0
	v_bitop3_b32 v59, s44, v161, v170 bitop3:0x36
	v_or_b32_e32 v58, 0x60, v137
	v_add_u32_e32 v59, s78, v59
	v_bitop3_b32 v63, s44, v162, v170 bitop3:0x36
	v_or_b32_e32 v62, 0x70, v137
	v_add_u32_e32 v63, s78, v63
	v_cndmask_b32_e64 v58, v59, v58, s[4:5]
	v_cndmask_b32_e64 v62, v63, v62, s[4:5]
	v_add_u32_e32 v58, s48, v58
	v_add_u32_e32 v62, s48, v62
	v_mad_i64_i32 v[58:59], s[56:57], v58, s86, v[148:149]
	v_mad_i64_i32 v[62:63], s[56:57], v62, s86, v[148:149]
	global_load_dwordx4 v[58:61], v[58:59], off offset:2048
	v_mfma_f32_16x16x32_bf16 v[126:129], v[66:69], v[102:105], v[78:81]
	global_load_dwordx4 v[62:65], v[62:63], off offset:2048
	v_mfma_f32_16x16x32_bf16 v[122:125], v[70:73], v[102:105], v[82:85]
	v_add3_u32 v234, s19, v141, v136
	v_add3_u32 v232, s19, v185, v136
	ds_read_b128 v[78:81], v234 offset:64
	ds_read_b128 v[82:85], v234 offset:4672
	ds_read_b128 v[94:97], v232 offset:64
	ds_read_b128 v[194:197], v234 offset:9280
	ds_read_b128 v[198:201], v234 offset:18496
	v_or_b32_e32 v233, s44, v169
	v_xad_u32 v66, v233, -1, s78
	s_waitcnt lgkmcnt(9)
	v_mfma_f32_16x16x32_bf16 v[202:205], v[86:89], v[34:37], 0
	v_cndmask_b32_e64 v66, v66, v233, s[4:5]
	v_add_u32_e32 v66, s48, v66
	v_mov_b64_e32 v[136:137], s[40:41]
	s_waitcnt lgkmcnt(8)
	v_mfma_f32_16x16x32_bf16 v[90:93], v[90:93], v[34:37], 0
	v_mad_i64_i32 v[66:67], s[56:57], v66, s86, v[136:137]
	v_lshl_add_u64 v[66:67], v[66:67], 0, s[68:69]
	s_waitcnt lgkmcnt(6)
	v_mfma_f32_16x16x32_bf16 v[152:155], v[152:155], v[34:37], 0
	s_mov_b32 s19, s69
	v_lshl_add_u64 v[66:67], v[66:67], 0, s[18:19]
	v_lshl_add_u64 v[66:67], v[66:67], 0, v[4:5]
	v_mfma_f32_16x16x32_bf16 v[132:135], v[132:135], v[34:37], 0
	s_waitcnt lgkmcnt(5)
	v_mfma_f32_16x16x32_bf16 v[190:193], v[190:193], v[34:37], 0
	v_bitop3_b32 v37, s44, v157, v169 bitop3:0x36
	v_or_b32_e32 v36, 32, v233
	v_add_u32_e32 v37, s78, v37
	v_cndmask_b32_e64 v36, v37, v36, s[4:5]
	v_add_u32_e32 v36, s48, v36
	v_mad_i64_i32 v[36:37], s[56:57], v36, s86, v[136:137]
	v_lshl_add_u64 v[36:37], v[36:37], 0, s[68:69]
	v_add_co_u32_e32 v34, vcc, s84, v66
	v_lshl_add_u64 v[36:37], v[36:37], 0, s[18:19]
	s_nop 0
	v_addc_co_u32_e32 v35, vcc, 0, v67, vcc
	v_lshl_add_u64 v[36:37], v[36:37], 0, v[4:5]
	v_add_co_u32_e32 v36, vcc, s84, v36
	s_nop 1
	v_addc_co_u32_e32 v37, vcc, 0, v37, vcc
	global_load_dwordx4 v[70:73], v[34:35], off
	global_load_dwordx4 v[66:69], v[36:37], off
	v_or_b32_e32 v34, s44, v171
	v_xad_u32 v35, v34, -1, s78
	v_cndmask_b32_e64 v34, v35, v34, s[4:5]
	v_add_u32_e32 v34, s48, v34
	v_mad_i64_i32 v[230:231], s[56:57], v34, s86, v[144:145]
	global_load_dwordx4 v[34:37], v[230:231], off
	global_load_dwordx4 v[86:89], v[230:231], off offset:64
	ds_read_b128 v[206:209], v234 offset:128
	ds_read_b128 v[210:213], v234 offset:4736
	ds_read_b128 v[214:217], v232 offset:128
	ds_read_b128 v[218:221], v234 offset:9344
	ds_read_b128 v[222:225], v234 offset:18560
	s_waitcnt lgkmcnt(9)
	v_mfma_f32_16x16x32_bf16 v[202:205], v[78:81], v[110:113], v[202:205]
	v_bitop3_b32 v79, s44, v159, v169 bitop3:0x36
	v_or_b32_e32 v78, 64, v233
	v_add_u32_e32 v79, s78, v79
	s_waitcnt lgkmcnt(8)
	v_mfma_f32_16x16x32_bf16 v[226:229], v[82:85], v[110:113], v[90:93]
	v_cndmask_b32_e64 v78, v79, v78, s[4:5]
	v_bitop3_b32 v83, s44, v161, v169 bitop3:0x36
	v_add_u32_e32 v78, s48, v78
	v_or_b32_e32 v82, 0x60, v233
	v_add_u32_e32 v83, s78, v83
	v_mad_i64_i32 v[78:79], s[56:57], v78, s86, v[136:137]
	v_cndmask_b32_e64 v82, v83, v82, s[4:5]
	v_lshl_add_u64 v[78:79], v[78:79], 0, s[68:69]
	v_add_u32_e32 v82, s48, v82
	v_lshl_add_u64 v[78:79], v[78:79], 0, s[18:19]
	v_mad_i64_i32 v[82:83], s[44:45], v82, s86, v[136:137]
	v_lshl_add_u64 v[78:79], v[78:79], 0, v[4:5]
	v_lshl_add_u64 v[82:83], v[82:83], 0, s[68:69]
	v_add_co_u32_e32 v78, vcc, s84, v78
	v_lshl_add_u64 v[82:83], v[82:83], 0, s[18:19]
	s_nop 0
	v_addc_co_u32_e32 v79, vcc, 0, v79, vcc
	v_lshl_add_u64 v[82:83], v[82:83], 0, v[4:5]
	v_add_co_u32_e32 v82, vcc, s84, v82
	s_waitcnt lgkmcnt(7)
	v_mfma_f32_16x16x32_bf16 v[132:135], v[94:97], v[110:113], v[132:135]
	v_addc_co_u32_e32 v83, vcc, 0, v83, vcc
	global_load_dwordx4 v[78:81], v[78:79], off
	s_nop 0
	global_load_dwordx4 v[82:85], v[82:83], off
	s_nop 0
	global_load_dwordx4 v[90:93], v[230:231], off offset:128
	global_load_dwordx4 v[94:97], v[230:231], off offset:192
	s_waitcnt lgkmcnt(6)
	v_mfma_f32_16x16x32_bf16 v[152:155], v[194:197], v[110:113], v[152:155]
	s_waitcnt lgkmcnt(5)
	v_mfma_f32_16x16x32_bf16 v[110:113], v[198:201], v[110:113], v[190:193]
	s_nop 2
	ds_read_b128 v[190:193], v234 offset:192
	ds_read_b128 v[194:197], v234 offset:4800
	ds_read_b128 v[198:201], v232 offset:192
	ds_read_b128 v[230:233], v234 offset:9408
	ds_read_b128 v[234:237], v234 offset:18624
	v_cndmask_b32_e64 v130, v131, v130, s[4:5]
	v_ashrrev_i32_e32 v131, 31, v130
	v_lshl_add_u64 v[130:131], s[0:1], 0, v[130:131]
	v_lshlrev_b64 v[130:131], 11, v[130:131]
	v_lshl_add_u64 v[130:131], v[146:147], 0, v[130:131]
	s_waitcnt lgkmcnt(9)
	v_mfma_f32_16x16x32_bf16 v[202:205], v[206:209], v[106:109], v[202:205]
	global_store_dwordx4 v[130:131], v[98:101], off sc1
	global_store_dwordx4 v[130:131], v[74:77], off offset:64 sc1
	s_waitcnt lgkmcnt(8)
	v_mfma_f32_16x16x32_bf16 v[206:209], v[210:213], v[106:109], v[226:229]
	s_waitcnt lgkmcnt(6)
	v_mfma_f32_16x16x32_bf16 v[210:213], v[218:221], v[106:109], v[152:155]
	v_mfma_f32_16x16x32_bf16 v[214:217], v[214:217], v[106:109], v[132:135]
	s_waitcnt lgkmcnt(5)
	v_mfma_f32_16x16x32_bf16 v[218:221], v[222:225], v[106:109], v[110:113]
	s_nop 2
	v_add3_u32 v112, s26, v173, v174
	ds_read_b64_tr_b16 v[98:99], v112
	ds_read_b64_tr_b16 v[74:75], v112 offset:32
	ds_read_b64_tr_b16 v[106:107], v112 offset:64
	ds_read_b64_tr_b16 v[110:111], v112 offset:96
	ds_read_b64_tr_b16 v[100:101], v112 offset:2560
	ds_read_b64_tr_b16 v[76:77], v112 offset:2592
	ds_read_b64_tr_b16 v[108:109], v112 offset:2624
	ds_read_b64_tr_b16 v[112:113], v112 offset:2656
	v_add3_u32 v130, s21, v175, v187
	v_lshl_add_u32 v247, v140, 2, s27
	ds_read_b64_tr_b16 v[154:155], v130 offset:96
	ds_read_b64_tr_b16 v[152:153], v130 offset:4704
	ds_read_b128 v[134:137], v247 offset:1536
	ds_read_b128 v[130:133], v247 offset:1600
	ds_read_b128 v[222:225], v247
	ds_read_b128 v[226:229], v247 offset:64
	ds_read_b128 v[238:241], v247 offset:128
	ds_read_b128 v[242:245], v247 offset:192
	s_waitcnt lgkmcnt(14)
	v_mfma_f32_16x16x32_bf16 v[190:193], v[190:193], v[102:105], v[202:205]
	v_mfma_f32_16x16x32_bf16 v[194:197], v[194:197], v[102:105], v[206:209]
	v_mfma_f32_16x16x32_bf16 v[202:205], v[230:233], v[102:105], v[210:213]
	v_mfma_f32_16x16x32_bf16 v[198:201], v[198:201], v[102:105], v[214:217]
	v_mfma_f32_16x16x32_bf16 v[102:105], v[234:237], v[102:105], v[218:221]
	v_sub_f32_e32 v206, v246, v150
	v_mul_f32_e32 v206, 0x3fb8aa3b, v206
	v_exp_f32_e32 v206, v206
	v_sub_f32_e32 v189, v246, v189
	v_mul_f32_e32 v189, 0x3fb8aa3b, v189
	v_exp_f32_e32 v208, v189
	v_pk_mul_f32 v[192:193], v[206:207], v[192:193] op_sel_hi:[0,1]
	v_pk_mul_f32 v[190:191], v[206:207], v[190:191] op_sel_hi:[0,1]
	v_pk_mul_f32 v[196:197], v[206:207], v[196:197] op_sel_hi:[0,1]
	v_pk_mul_f32 v[194:195], v[206:207], v[194:195] op_sel_hi:[0,1]
	v_pk_mul_f32 v[204:205], v[206:207], v[204:205] op_sel_hi:[0,1]
	v_pk_mul_f32 v[202:203], v[206:207], v[202:203] op_sel_hi:[0,1]
	v_pk_mul_f32 v[200:201], v[206:207], v[200:201] op_sel_hi:[0,1]
	v_pk_mul_f32 v[198:199], v[206:207], v[198:199] op_sel_hi:[0,1]
	v_pk_mul_f32 v[104:105], v[206:207], v[104:105] op_sel_hi:[0,1]
	v_pk_mul_f32 v[102:103], v[206:207], v[102:103] op_sel_hi:[0,1]
	s_waitcnt lgkmcnt(3)
	v_fmamk_f32 v189, v150, 0xbfb8aa3b, v222
	v_fmamk_f32 v206, v150, 0xbfb8aa3b, v223
	v_exp_f32_e32 v189, v189
	v_exp_f32_e32 v206, v206
	v_fmamk_f32 v207, v150, 0xbfb8aa3b, v224
	v_exp_f32_e32 v207, v207
	v_mul_f32_e32 v126, v126, v189
	v_mul_f32_e32 v127, v127, v206
	s_waitcnt lgkmcnt(2)
	v_fmamk_f32 v189, v150, 0xbfb8aa3b, v226
	v_fmamk_f32 v206, v150, 0xbfb8aa3b, v227
	v_exp_f32_e32 v189, v189
	v_exp_f32_e32 v206, v206
	v_fmac_f32_e32 v225, 0xbfb8aa3b, v150
	v_mul_f32_e32 v128, v128, v207
	v_fmamk_f32 v207, v150, 0xbfb8aa3b, v228
	v_pk_mul_f32 v[40:41], v[40:41], v[208:209] op_sel_hi:[1,0]
	v_pk_mul_f32 v[38:39], v[38:39], v[208:209] op_sel_hi:[1,0]
	v_pk_mul_f32 v[32:33], v[32:33], v[208:209] op_sel_hi:[1,0]
	v_pk_mul_f32 v[30:31], v[30:31], v[208:209] op_sel_hi:[1,0]
	v_pk_mul_f32 v[28:29], v[28:29], v[208:209] op_sel_hi:[1,0]
	v_pk_mul_f32 v[26:27], v[26:27], v[208:209] op_sel_hi:[1,0]
	v_pk_mul_f32 v[24:25], v[24:25], v[208:209] op_sel_hi:[1,0]
	v_pk_mul_f32 v[22:23], v[22:23], v[208:209] op_sel_hi:[1,0]
	v_pk_mul_f32 v[20:21], v[20:21], v[208:209] op_sel_hi:[1,0]
	v_pk_mul_f32 v[18:19], v[18:19], v[208:209] op_sel_hi:[1,0]
	v_exp_f32_e32 v208, v225
	v_exp_f32_e32 v207, v207
	v_mul_f32_e32 v122, v122, v189
	v_mul_f32_e32 v123, v123, v206
	s_waitcnt lgkmcnt(1)
	v_fmamk_f32 v189, v150, 0xbfb8aa3b, v238
	v_fmamk_f32 v206, v150, 0xbfb8aa3b, v239
	v_fmac_f32_e32 v229, 0xbfb8aa3b, v150
	v_exp_f32_e32 v189, v189
	v_exp_f32_e32 v206, v206
	v_mul_f32_e32 v129, v129, v208
	v_exp_f32_e32 v208, v229
	v_mul_f32_e32 v124, v124, v207
	v_fmamk_f32 v207, v150, 0xbfb8aa3b, v240
	v_exp_f32_e32 v207, v207
	v_fmac_f32_e32 v241, 0xbfb8aa3b, v150
	v_mul_f32_e32 v118, v118, v189
	v_mul_f32_e32 v119, v119, v206
	s_waitcnt lgkmcnt(0)
	v_fmamk_f32 v189, v150, 0xbfb8aa3b, v242
	v_fmamk_f32 v206, v150, 0xbfb8aa3b, v243
	v_mul_f32_e32 v125, v125, v208
	v_exp_f32_e32 v208, v241
	v_exp_f32_e32 v189, v189
	v_exp_f32_e32 v206, v206
	v_mul_f32_e32 v120, v120, v207
	v_fmamk_f32 v207, v150, 0xbfb8aa3b, v244
	v_fmac_f32_e32 v245, 0xbfb8aa3b, v150
	v_exp_f32_e32 v207, v207
	v_exp_f32_e32 v150, v245
	v_mul_f32_e32 v121, v121, v208
	v_mul_f32_e32 v189, v114, v189
	v_mul_f32_e32 v206, v115, v206
	v_cvt_pk_bf16_f32 v118, v118, v119
	v_cvt_pk_bf16_f32 v119, v120, v121
	v_cvt_pk_bf16_f32 v120, v189, s0
	v_cvt_pk_bf16_f32 v121, v206, s0
	v_mul_f32_e32 v207, v116, v207
	v_mul_f32_e32 v150, v117, v150
	v_cndmask_b32_e64 v120, v120, 0, s[6:7]
	v_cndmask_b32_e64 v121, 0, v121, s[8:9]
	v_cvt_pk_bf16_f32 v116, v122, v123
	v_perm_b32 v120, v121, v120, s89
	v_cvt_pk_bf16_f32 v121, v207, s0
	v_cvt_pk_bf16_f32 v122, v150, s0
	v_cndmask_b32_e64 v121, v121, 0, s[10:11]
	v_cndmask_b32_e64 v122, v122, 0, s[12:13]
	v_cvt_pk_bf16_f32 v114, v126, v127
	v_cvt_pk_bf16_f32 v115, v128, v129
	v_cvt_pk_bf16_f32 v117, v124, v125
	v_perm_b32 v121, v122, v121, s89
	v_add3_u32 v150, s26, v176, v187
	ds_read_b64_tr_b16 v[122:123], v150
	ds_read_b64_tr_b16 v[126:127], v150 offset:32
	ds_read_b64_tr_b16 v[206:207], v150 offset:64
	ds_read_b64_tr_b16 v[210:211], v150 offset:96
	ds_read_b64_tr_b16 v[124:125], v150 offset:2560
	ds_read_b64_tr_b16 v[128:129], v150 offset:2592
	ds_read_b64_tr_b16 v[208:209], v150 offset:2624
	ds_read_b64_tr_b16 v[212:213], v150 offset:2656
	v_add3_u32 v150, s21, v177, v187
	ds_read_b64_tr_b16 v[230:231], v150 offset:96
	ds_read_b64_tr_b16 v[232:233], v150 offset:4704
	ds_read_b128 v[214:217], v247 offset:1664
	ds_read_b128 v[218:221], v247 offset:1728
	v_mfma_f32_16x16x32_bf16 v[190:193], v[98:101], v[114:117], v[190:193]
	v_mfma_f32_16x16x32_bf16 v[194:197], v[74:77], v[114:117], v[194:197]
	v_mfma_f32_16x16x32_bf16 v[202:205], v[106:109], v[114:117], v[202:205]
	v_mfma_f32_16x16x32_bf16 v[198:201], v[110:113], v[114:117], v[198:201]
	v_mfma_f32_16x16x32_bf16 v[114:117], v[6:9], v[114:117], v[102:105]
	s_nop 2
	v_lshlrev_b32_e32 v102, 16, v154
	v_and_b32_e32 v103, 0xffff0000, v154
	v_mul_f32_e32 v102, v134, v102
	v_mul_f32_e32 v103, v135, v103
	v_cvt_pk_bf16_f32 v102, v102, v103
	v_lshlrev_b32_e32 v103, 16, v155
	v_and_b32_e32 v104, 0xffff0000, v155
	v_mul_f32_e32 v103, v136, v103
	v_mul_f32_e32 v104, v137, v104
	v_cvt_pk_bf16_f32 v103, v103, v104
	v_lshlrev_b32_e32 v104, 16, v152
	v_and_b32_e32 v105, 0xffff0000, v152
	v_mul_f32_e32 v104, v130, v104
	v_mul_f32_e32 v105, v131, v105
	v_cvt_pk_bf16_f32 v104, v104, v105
	v_lshlrev_b32_e32 v105, 16, v153
	v_and_b32_e32 v130, 0xffff0000, v153
	v_mul_f32_e32 v105, v132, v105
	v_mul_f32_e32 v130, v133, v130
	v_cvt_pk_bf16_f32 v105, v105, v130
	s_nop 1
	v_mfma_f32_16x16x32_bf16 v[38:41], v[102:105], v[98:101], v[38:41]
	v_mfma_f32_16x16x32_bf16 v[30:33], v[102:105], v[74:77], v[30:33]
	v_mfma_f32_16x16x32_bf16 v[26:29], v[102:105], v[106:109], v[26:29]
	v_mfma_f32_16x16x32_bf16 v[22:25], v[102:105], v[110:113], v[22:25]
	v_mfma_f32_16x16x32_bf16 v[18:21], v[102:105], v[6:9], v[18:21]
	v_add3_u32 v74, s26, v178, v187
	ds_read_b64_tr_b16 v[110:111], v74
	ds_read_b64_tr_b16 v[130:131], v74 offset:32
	ds_read_b64_tr_b16 v[134:135], v74 offset:64
	ds_read_b64_tr_b16 v[152:153], v74 offset:96
	ds_read_b64_tr_b16 v[112:113], v74 offset:2560
	ds_read_b64_tr_b16 v[132:133], v74 offset:2592
	ds_read_b64_tr_b16 v[136:137], v74 offset:2624
	ds_read_b64_tr_b16 v[154:155], v74 offset:2656
	v_add3_u32 v74, s21, v179, v187
	ds_read_b64_tr_b16 v[234:235], v74 offset:96
	ds_read_b64_tr_b16 v[236:237], v74 offset:4704
	ds_read_b128 v[222:225], v247 offset:1792
	ds_read_b128 v[226:229], v247 offset:1856
	v_mfma_f32_16x16x32_bf16 v[114:117], v[6:9], v[118:121], v[114:117]
	s_waitcnt lgkmcnt(14)
	v_mfma_f32_16x16x32_bf16 v[98:101], v[122:125], v[118:121], v[190:193]
	v_mfma_f32_16x16x32_bf16 v[106:109], v[126:129], v[118:121], v[194:197]
	s_nop 4
	v_lshlrev_b32_e32 v115, 16, v230
	v_and_b32_e32 v116, 0xffff0000, v230
	s_waitcnt lgkmcnt(13)
	v_mul_f32_e32 v115, v214, v115
	v_mul_f32_e32 v116, v215, v116
	v_cvt_pk_bf16_f32 v116, v115, v116
	v_lshlrev_b32_e32 v115, 16, v231
	v_and_b32_e32 v117, 0xffff0000, v231
	v_mul_f32_e32 v115, v216, v115
	v_mul_f32_e32 v117, v217, v117
	v_mfma_f32_16x16x32_bf16 v[74:77], v[206:209], v[118:121], v[202:205]
	v_cvt_pk_bf16_f32 v117, v115, v117
	v_lshlrev_b32_e32 v115, 16, v232
	s_waitcnt lgkmcnt(12)
	v_mul_f32_e32 v115, v218, v115
	v_mfma_f32_16x16x32_bf16 v[102:105], v[210:213], v[118:121], v[198:201]
	v_and_b32_e32 v118, 0xffff0000, v232
	v_mul_f32_e32 v118, v219, v118
	v_cvt_pk_bf16_f32 v118, v115, v118
	v_lshlrev_b32_e32 v115, 16, v233
	v_and_b32_e32 v119, 0xffff0000, v233
	v_mul_f32_e32 v115, v220, v115
	v_mul_f32_e32 v119, v221, v119
	v_cvt_pk_bf16_f32 v119, v115, v119
	s_nop 1
	v_mfma_f32_16x16x32_bf16 v[38:41], v[116:119], v[122:125], v[38:41]
	v_mfma_f32_16x16x32_bf16 v[30:33], v[116:119], v[126:129], v[30:33]
	v_mfma_f32_16x16x32_bf16 v[26:29], v[116:119], v[206:209], v[26:29]
	v_mfma_f32_16x16x32_bf16 v[22:25], v[116:119], v[210:213], v[22:25]
	v_mfma_f32_16x16x32_bf16 v[18:21], v[116:119], v[6:9], v[18:21]
	v_add3_u32 v115, s26, v180, v187
	ds_read_b64_tr_b16 v[116:117], v115
	ds_read_b64_tr_b16 v[120:121], v115 offset:32
	ds_read_b64_tr_b16 v[124:125], v115 offset:64
	ds_read_b64_tr_b16 v[190:191], v115 offset:96
	ds_read_b64_tr_b16 v[118:119], v115 offset:2560
	ds_read_b64_tr_b16 v[122:123], v115 offset:2592
	ds_read_b64_tr_b16 v[126:127], v115 offset:2624
	ds_read_b64_tr_b16 v[192:193], v115 offset:2656
	v_add3_u32 v115, s21, v181, v187
	ds_read_b64_tr_b16 v[128:129], v115 offset:96
	ds_read_b64_tr_b16 v[206:207], v115 offset:4704
	ds_read_b128 v[194:197], v247 offset:1920
	ds_read_b128 v[198:201], v247 offset:1984
	s_waitcnt lgkmcnt(14)
	v_lshlrev_b32_e32 v115, 16, v234
	v_and_b32_e32 v150, 0xffff0000, v234
	s_waitcnt lgkmcnt(13)
	v_mul_f32_e32 v115, v222, v115
	v_mul_f32_e32 v150, v223, v150
	v_cvt_pk_bf16_f32 v202, v115, v150
	v_lshlrev_b32_e32 v115, 16, v235
	v_and_b32_e32 v150, 0xffff0000, v235
	v_mul_f32_e32 v115, v224, v115
	v_mul_f32_e32 v150, v225, v150
	v_cvt_pk_bf16_f32 v203, v115, v150
	v_lshlrev_b32_e32 v115, 16, v236
	v_and_b32_e32 v150, 0xffff0000, v236
	s_waitcnt lgkmcnt(12)
	v_mul_f32_e32 v115, v226, v115
	v_mul_f32_e32 v150, v227, v150
	v_cvt_pk_bf16_f32 v204, v115, v150
	v_lshlrev_b32_e32 v115, 16, v237
	v_and_b32_e32 v150, 0xffff0000, v237
	v_mul_f32_e32 v115, v228, v115
	v_mul_f32_e32 v150, v229, v150
	v_cvt_pk_bf16_f32 v205, v115, v150
	s_nop 1
	v_mfma_f32_16x16x32_bf16 v[38:41], v[202:205], v[110:113], v[38:41]
	v_mfma_f32_16x16x32_bf16 v[30:33], v[202:205], v[130:133], v[30:33]
	v_mfma_f32_16x16x32_bf16 v[26:29], v[202:205], v[134:137], v[26:29]
	v_mfma_f32_16x16x32_bf16 v[22:25], v[202:205], v[152:155], v[22:25]
	v_mfma_f32_16x16x32_bf16 v[18:21], v[202:205], v[6:9], v[18:21]
	s_waitcnt lgkmcnt(3)
	v_lshlrev_b32_e32 v110, 16, v128
	v_and_b32_e32 v111, 0xffff0000, v128
	s_waitcnt lgkmcnt(1)
	v_mul_f32_e32 v110, v194, v110
	v_mul_f32_e32 v111, v195, v111
	v_cvt_pk_bf16_f32 v110, v110, v111
	v_lshlrev_b32_e32 v111, 16, v129
	v_and_b32_e32 v112, 0xffff0000, v129
	v_mul_f32_e32 v111, v196, v111
	v_mul_f32_e32 v112, v197, v112
	v_cvt_pk_bf16_f32 v111, v111, v112
	v_lshlrev_b32_e32 v112, 16, v206
	v_and_b32_e32 v113, 0xffff0000, v206
	s_waitcnt lgkmcnt(0)
	v_mul_f32_e32 v112, v198, v112
	v_mul_f32_e32 v113, v199, v113
	v_cvt_pk_bf16_f32 v112, v112, v113
	v_lshlrev_b32_e32 v113, 16, v207
	v_and_b32_e32 v115, 0xffff0000, v207
	v_mul_f32_e32 v113, v200, v113
	v_mul_f32_e32 v115, v201, v115
	v_cvt_pk_bf16_f32 v113, v113, v115
	s_nop 1
	v_mfma_f32_16x16x32_bf16 v[38:41], v[110:113], v[116:119], v[38:41]
	v_mfma_f32_16x16x32_bf16 v[30:33], v[110:113], v[120:123], v[30:33]
	v_mfma_f32_16x16x32_bf16 v[26:29], v[110:113], v[124:127], v[26:29]
	v_mfma_f32_16x16x32_bf16 v[22:25], v[110:113], v[190:193], v[22:25]
	v_mfma_f32_16x16x32_bf16 v[18:21], v[110:113], v[6:9], v[18:21]
	s_xor_b32 s19, s20, 1
	s_mulk_i32 s19, 0x4a00
	s_add_i32 s19, s19, 0
	v_lshlrev_b32_e32 v111, 1, v140
	ds_bpermute_b32 v110, v182, v114
	v_add3_u32 v114, s19, v141, v111
	v_cvt_pk_bf16_f32 v112, v38, v39
	v_cvt_pk_bf16_f32 v113, v40, v41
	v_add_u32_e32 v115, 0x1c060, v114
	ds_write_b64 v115, v[112:113]
	v_cvt_pk_bf16_f32 v112, v30, v31
	v_cvt_pk_bf16_f32 v113, v32, v33
	v_add_u32_e32 v115, 0x1d260, v114
	ds_write_b64 v115, v[112:113]
	v_cvt_pk_bf16_f32 v112, v26, v27
	v_cvt_pk_bf16_f32 v113, v28, v29
	v_add_u32_e32 v114, 0x1e460, v114
	ds_write_b64 v114, v[112:113]
	v_add_u32_e32 v114, s19, v185
	s_mov_b32 s20, 0x1c060
	v_cvt_pk_bf16_f32 v112, v22, v23
	v_cvt_pk_bf16_f32 v113, v24, v25
	v_add3_u32 v111, v114, v111, s20
	ds_write_b64 v111, v[112:113]
	s_and_saveexec_b64 s[20:21], s[2:3]
	s_cbranch_execz .LBB0_355
	v_lshl_add_u32 v111, v140, 1, s19
	v_cvt_pk_bf16_f32 v112, v18, v19
	v_cvt_pk_bf16_f32 v113, v20, v21
	v_add_u32_e32 v111, 0x20860, v111
	ds_write_b64 v111, v[112:113]
	s_branch .LBB0_355
.LBB0_358:
	s_add_i32 s2, s78, 0xffffff80
	v_or_b32_e32 v4, s2, v171
	v_xad_u32 v6, v4, -1, s78
	v_cndmask_b32_e64 v6, v6, v4, s[4:5]
	v_ashrrev_i32_e32 v7, 31, v6
	v_lshl_add_u64 v[6:7], s[0:1], 0, v[6:7]
	v_lshlrev_b64 v[6:7], 11, v[6:7]
	v_lshl_add_u64 v[6:7], s[42:43], 0, v[6:7]
	v_lshl_add_u64 v[6:7], v[6:7], 0, s[68:69]
	s_mov_b32 s19, s69
	v_lshl_add_u64 v[6:7], v[6:7], 0, s[18:19]
	v_lshl_add_u64 v[2:3], v[2:3], 1, v[6:7]
	s_and_b64 vcc, exec, s[46:47]
	global_store_dwordx4 v[2:3], v[98:101], off sc1
	global_store_dwordx4 v[2:3], v[74:77], off offset:64 sc1
	s_cbranch_vccz .LBB0_362
	s_waitcnt vmcnt(18)
	v_mbcnt_lo_u32_b32 v16, -1, 0
	v_mbcnt_hi_u32_b32 v16, -1, v16
	s_ashr_i32 s17, s16, 31
	v_lshlrev_b32_e32 v3, 1, v16
	v_ashrrev_i32_e32 v2, 2, v16
	v_and_b32_e32 v3, 24, v3
	v_and_b32_e32 v4, 3, v16
	s_lshl_b64 s[0:1], s[16:17], 16
	v_and_b32_e32 v2, -4, v2
	v_or3_b32 v3, v4, v3, s25
	s_add_u32 s0, s76, s0
	v_lshlrev_b32_e32 v4, 2, v3
	v_ashrrev_i32_e32 v3, 31, v2
	s_addc_u32 s1, s77, s1
	v_lshlrev_b64 v[6:7], 9, v[2:3]
	v_lshl_add_u64 v[6:7], s[0:1], 0, v[6:7]
	v_lshl_add_u64 v[6:7], v[6:7], 0, v[4:5]
	s_mov_b64 s[0:1], 0x6000
	v_lshl_add_u64 v[8:9], v[6:7], 0, s[0:1]
	s_movk_i32 s0, 0x6000
	v_add_co_u32_e32 v10, vcc, s0, v6
	s_mov_b64 s[0:1], 0x6200
	s_nop 0
	v_addc_co_u32_e32 v11, vcc, 0, v7, vcc
	v_lshl_add_u64 v[12:13], v[6:7], 0, s[0:1]
	s_mov_b64 s[0:1], 0x6400
	v_and_or_b32 v4, v16, 15, s31
	v_lshl_add_u64 v[14:15], v[6:7], 0, s[0:1]
	s_mov_b64 s[0:1], 0x6600
	v_cmp_eq_u32_e32 vcc, 0, v4
	global_store_dword v[10:11], v38, off
	global_store_dword v[10:11], v39, off offset:512
	global_store_dword v[10:11], v40, off offset:1024
	v_lshl_add_u64 v[6:7], v[6:7], 0, s[0:1]
	global_store_dword v[10:11], v41, off offset:1536
	global_store_dword v[8:9], v30, off offset:16
	global_store_dword v[12:13], v31, off offset:16
	global_store_dword v[14:15], v32, off offset:16
	global_store_dword v[6:7], v33, off offset:16
	global_store_dword v[8:9], v26, off offset:128
	global_store_dword v[12:13], v27, off offset:128
	global_store_dword v[14:15], v28, off offset:128
	global_store_dword v[6:7], v29, off offset:128
	global_store_dword v[8:9], v22, off offset:144
	global_store_dword v[12:13], v23, off offset:144
	global_store_dword v[14:15], v24, off offset:144
	global_store_dword v[6:7], v25, off offset:144
	s_and_saveexec_b64 s[0:1], vcc
	s_cbranch_execz .LBB0_361
	s_lshl_b64 s[2:3], s[16:17], 9
	v_readlane_b32 s4, v254, 26
	s_add_u32 s2, s4, s2
	v_readlane_b32 s4, v254, 27
	s_addc_u32 s3, s4, s3
	v_lshl_add_u64 v[2:3], v[2:3], 2, s[2:3]
	global_store_dwordx4 v[2:3], v[18:21], off offset:192 sc1

.LBB0_368:
	s_mov_b32 s19, s17
	s_min_u32 s17, s17, 1
	s_lshl_b32 s17, s17, 7
	s_and_b32 s20, s19, 1
	v_subrev_u32_e32 v173, s17, v172
	v_add_u32_e32 v230, s17, v129
	s_mul_i32 s17, s20, 0x9000
	s_add_i32 s21, s17, 0
	s_mul_i32 s17, s20, 0x5000
	s_waitcnt vmcnt(6)
	v_mov_b64_e32 v[116:117], v[88:89]
	s_add_i32 s26, s17, 0
	v_mov_b64_e32 v[114:115], v[86:87]
	s_add_i32 s26, s26, 0x12000
	v_add3_u32 v86, s21, v128, v155
	ds_write_b128 v86, v[10:13]
	ds_write_b128 v86, v[18:21] offset:4608
	ds_write_b128 v86, v[38:41] offset:9216
	ds_write_b128 v86, v[46:49] offset:13824
	ds_write_b128 v86, v[50:53] offset:18432
	ds_write_b128 v86, v[54:57] offset:23040
	ds_write_b128 v86, v[58:61] offset:27648
	ds_write_b128 v86, v[62:65] offset:32256
	v_lshl_add_u32 v10, v144, 1, s26
	s_lshl_b32 s17, s20, 11
	v_add3_u32 v10, v10, v170, v168
	s_add_i32 s27, s17, 0
	v_add_u32_e32 v11, 0x1000, v10
	s_add_i32 s27, s27, 0x25a00
	s_lshl_b32 s17, s20, 4
	ds_write2_b64 v11, v[66:67], v[68:69] offset0:128 offset1:132
	v_add_u32_e32 v11, 0x2800, v10
	s_waitcnt vmcnt(5)
	ds_write2_b64 v11, v[78:79], v[80:81] offset1:4
	s_add_i32 s17, s17, 0
	v_lshl_add_u32 v11, v140, 2, s27
	ds_write2_b64 v10, v[70:71], v[72:73] offset1:4
	v_add_u32_e32 v10, 0x3800, v10
	s_add_i32 s37, s17, 0x26a00
	v_add_u32_e32 v11, 0x80, v11
	v_lshlrev_b32_e32 v186, 1, v2
	s_waitcnt vmcnt(4)
	ds_write2_b64 v10, v[82:83], v[84:85] offset0:128 offset1:132
	s_waitcnt lgkmcnt(0)
	s_barrier
	v_mov_b32_e32 v10, s27
	ds_read2st64_b32 v[136:137], v11 offset0:2 offset1:4
	v_mov_b32_e32 v11, s37
	v_add_u32_e32 v18, s21, v186
	v_add_u32_e32 v19, v18, v127
	ds_read_b32 v238, v10 offset:1020
	ds_read_b32 v239, v11
	ds_read_b128 v[10:13], v19
	v_add_u32_e32 v38, v18, v169
	ds_read_b128 v[18:21], v19 offset:4608
	ds_read_b128 v[38:41], v38
	s_add_i32 s17, s19, 1
	s_mul_i32 s36, s20, 0x4a00
	s_cmp_lt_u32 s17, s79
	s_waitcnt vmcnt(3)
	v_mov_b64_e32 v[108:109], v[92:93]
	s_waitcnt vmcnt(2)
	v_mov_b64_e32 v[104:105], v[96:97]
	s_cselect_b32 s37, s17, s19
	s_add_i32 s19, s36, 0
	v_mov_b64_e32 v[106:107], v[90:91]
	v_mov_b64_e32 v[102:103], v[94:95]
	s_add_i32 s19, s19, 0x1c000
	v_add3_u32 v82, s21, v127, v186
	v_add3_u32 v86, s21, v169, v186
	ds_read_b128 v[46:49], v82 offset:64
	ds_read_b128 v[50:53], v82 offset:4672
	ds_read_b128 v[54:57], v86 offset:64
	s_lshl_b32 s44, s37, 7
	s_waitcnt lgkmcnt(4)
	v_mfma_f32_16x16x32_bf16 v[62:65], v[18:21], v[42:45], 0
	v_or_b32_e32 v182, s44, v142
	v_bitop3_b32 v19, s44, v156, v142 bitop3:0x36
	v_or_b32_e32 v18, 16, v182
	v_mfma_f32_16x16x32_bf16 v[58:61], v[10:13], v[42:45], 0
	v_xad_u32 v10, v182, -1, s78
	v_add_u32_e32 v19, s78, v19
	v_cndmask_b32_e64 v10, v10, v182, s[4:5]
	v_cndmask_b32_e64 v18, v19, v18, s[4:5]
	v_add_u32_e32 v10, s48, v10
	v_add_u32_e32 v18, s48, v18
	v_mad_i64_i32 v[10:11], s[56:57], v10, s86, v[134:135]
	v_mad_i64_i32 v[18:19], s[56:57], v18, s86, v[134:135]
	global_load_dwordx4 v[10:13], v[10:11], off offset:2048
	s_waitcnt lgkmcnt(3)
	v_mfma_f32_16x16x32_bf16 v[38:41], v[38:41], v[42:45], 0
	global_load_dwordx4 v[18:21], v[18:19], off offset:2048
	ds_read_b128 v[66:69], v82 offset:128
	ds_read_b128 v[70:73], v82 offset:4736
	ds_read_b128 v[78:81], v86 offset:128
	s_waitcnt lgkmcnt(5)
	v_mfma_f32_16x16x32_bf16 v[58:61], v[46:49], v[114:117], v[58:61]
	v_bitop3_b32 v47, s44, v158, v142 bitop3:0x36
	v_or_b32_e32 v46, 48, v182
	v_add_u32_e32 v47, s78, v47
	s_waitcnt lgkmcnt(3)
	v_mfma_f32_16x16x32_bf16 v[54:57], v[54:57], v[114:117], v[38:41]
	v_cndmask_b32_e64 v46, v47, v46, s[4:5]
	v_add_u32_e32 v46, s48, v46
	v_mad_i64_i32 v[46:47], s[56:57], v46, s86, v[134:135]
	v_bitop3_b32 v39, s44, v157, v142 bitop3:0x36
	v_or_b32_e32 v38, 32, v182
	v_add_u32_e32 v39, s78, v39
	v_cndmask_b32_e64 v38, v39, v38, s[4:5]
	v_add_u32_e32 v38, s48, v38
	v_mad_i64_i32 v[38:39], s[56:57], v38, s86, v[134:135]
	global_load_dwordx4 v[38:41], v[38:39], off offset:2048
	v_mfma_f32_16x16x32_bf16 v[50:53], v[50:53], v[114:117], v[62:65]
	global_load_dwordx4 v[46:49], v[46:47], off offset:2048
	s_nop 1
	ds_read_b128 v[62:65], v82 offset:192
	ds_read_b128 v[82:85], v82 offset:4800
	ds_read_b128 v[86:89], v86 offset:192
	s_waitcnt lgkmcnt(5)
	v_mfma_f32_16x16x32_bf16 v[58:61], v[66:69], v[106:109], v[58:61]
	s_waitcnt lgkmcnt(4)
	v_mfma_f32_16x16x32_bf16 v[66:69], v[70:73], v[106:109], v[50:53]
	s_waitcnt lgkmcnt(3)
	v_mfma_f32_16x16x32_bf16 v[70:73], v[78:81], v[106:109], v[54:57]
	s_nop 0
	v_bitop3_b32 v51, s44, v159, v142 bitop3:0x36
	v_or_b32_e32 v50, 64, v182
	v_add_u32_e32 v51, s78, v51
	v_bitop3_b32 v55, s44, v160, v142 bitop3:0x36
	v_or_b32_e32 v54, 0x50, v182
	v_add_u32_e32 v55, s78, v55
	v_cndmask_b32_e64 v50, v51, v50, s[4:5]
	v_cndmask_b32_e64 v54, v55, v54, s[4:5]
	v_add_u32_e32 v50, s48, v50
	v_add_u32_e32 v54, s48, v54
	v_mad_i64_i32 v[50:51], s[56:57], v50, s86, v[134:135]
	v_mad_i64_i32 v[54:55], s[56:57], v54, s86, v[134:135]
	global_load_dwordx4 v[50:53], v[50:51], off offset:2048
	s_nop 0
	global_load_dwordx4 v[54:57], v[54:55], off offset:2048
	v_add_u32_e32 v94, s19, v186
	v_add_u32_e32 v110, v94, v127
	v_add_u32_e32 v94, v94, v169
	ds_read_b128 v[78:81], v110
	ds_read_b128 v[90:93], v110 offset:4608
	ds_read_b128 v[94:97], v94
	ds_read_b128 v[174:177], v110 offset:13824
	ds_read_b128 v[178:181], v110 offset:18432
	s_waitcnt lgkmcnt(7)
	v_mfma_f32_16x16x32_bf16 v[122:125], v[62:65], v[102:105], v[58:61]
	v_bitop3_b32 v63, s44, v162, v142 bitop3:0x36
	v_or_b32_e32 v62, 0x70, v182
	v_add_u32_e32 v63, s78, v63
	v_bitop3_b32 v59, s44, v161, v142 bitop3:0x36
	v_or_b32_e32 v58, 0x60, v182
	v_add_u32_e32 v59, s78, v59
	v_cndmask_b32_e64 v58, v59, v58, s[4:5]
	v_cndmask_b32_e64 v62, v63, v62, s[4:5]
	v_add_u32_e32 v58, s48, v58
	v_add_u32_e32 v62, s48, v62
	v_mad_i64_i32 v[58:59], s[56:57], v58, s86, v[134:135]
	v_mad_i64_i32 v[62:63], s[56:57], v62, s86, v[134:135]
	global_load_dwordx4 v[58:61], v[58:59], off offset:2048
	s_waitcnt lgkmcnt(5)
	v_mfma_f32_16x16x32_bf16 v[110:113], v[86:89], v[102:105], v[70:73]
	global_load_dwordx4 v[62:65], v[62:63], off offset:2048
	v_mfma_f32_16x16x32_bf16 v[118:121], v[82:85], v[102:105], v[66:69]
	v_add3_u32 v226, s19, v127, v186
	v_add3_u32 v227, s19, v169, v186
	ds_read_b128 v[82:85], v226 offset:64
	ds_read_b128 v[182:185], v226 offset:4672
	ds_read_b128 v[186:189], v227 offset:64
	ds_read_b128 v[190:193], v226 offset:13888
	ds_read_b128 v[194:197], v226 offset:18496
	v_or_b32_e32 v228, s44, v141
	v_xad_u32 v66, v228, -1, s78
	s_waitcnt lgkmcnt(9)
	v_mfma_f32_16x16x32_bf16 v[78:81], v[78:81], v[42:45], 0
	v_cndmask_b32_e64 v66, v66, v228, s[4:5]
	v_add_u32_e32 v66, s48, v66
	v_mov_b64_e32 v[222:223], s[40:41]
	s_waitcnt lgkmcnt(8)
	v_mfma_f32_16x16x32_bf16 v[90:93], v[90:93], v[42:45], 0
	v_mad_i64_i32 v[66:67], s[56:57], v66, s86, v[222:223]
	v_lshl_add_u64 v[66:67], v[66:67], 0, s[68:69]
	s_waitcnt lgkmcnt(7)
	v_mfma_f32_16x16x32_bf16 v[94:97], v[94:97], v[42:45], 0
	s_mov_b32 s19, s69
	v_lshl_add_u64 v[66:67], v[66:67], 0, s[18:19]
	v_lshl_add_u64 v[66:67], v[66:67], 0, v[4:5]
	s_waitcnt lgkmcnt(6)
	v_mfma_f32_16x16x32_bf16 v[174:177], v[174:177], v[42:45], 0
	s_waitcnt lgkmcnt(5)
	v_mfma_f32_16x16x32_bf16 v[178:181], v[178:181], v[42:45], 0
	v_bitop3_b32 v45, s44, v157, v141 bitop3:0x36
	v_or_b32_e32 v44, 32, v228
	v_add_u32_e32 v45, s78, v45
	v_cndmask_b32_e64 v44, v45, v44, s[4:5]
	v_add_u32_e32 v44, s48, v44
	v_mad_i64_i32 v[44:45], s[56:57], v44, s86, v[222:223]
	v_lshl_add_u64 v[44:45], v[44:45], 0, s[68:69]
	v_add_co_u32_e32 v42, vcc, s84, v66
	v_lshl_add_u64 v[44:45], v[44:45], 0, s[18:19]
	s_nop 0
	v_addc_co_u32_e32 v43, vcc, 0, v67, vcc
	v_lshl_add_u64 v[44:45], v[44:45], 0, v[4:5]
	v_add_co_u32_e32 v44, vcc, s84, v44
	s_nop 1
	v_addc_co_u32_e32 v45, vcc, 0, v45, vcc
	global_load_dwordx4 v[70:73], v[42:43], off
	global_load_dwordx4 v[66:69], v[44:45], off
	v_or_b32_e32 v42, s44, v143
	v_xad_u32 v43, v42, -1, s78
	v_cndmask_b32_e64 v42, v43, v42, s[4:5]
	v_add_u32_e32 v42, s48, v42
	v_mad_i64_i32 v[224:225], s[56:57], v42, s86, v[130:131]
	global_load_dwordx4 v[42:45], v[224:225], off
	global_load_dwordx4 v[86:89], v[224:225], off offset:64
	ds_read_b128 v[198:201], v226 offset:128
	ds_read_b128 v[202:205], v226 offset:4736
	ds_read_b128 v[206:209], v227 offset:128
	ds_read_b128 v[210:213], v226 offset:13952
	ds_read_b128 v[214:217], v226 offset:18560
	s_waitcnt lgkmcnt(9)
	v_mfma_f32_16x16x32_bf16 v[218:221], v[82:85], v[114:117], v[78:81]
	v_bitop3_b32 v83, s44, v161, v141 bitop3:0x36
	v_or_b32_e32 v82, 0x60, v228
	v_add_u32_e32 v83, s78, v83
	v_bitop3_b32 v79, s44, v159, v141 bitop3:0x36
	v_or_b32_e32 v78, 64, v228
	v_add_u32_e32 v79, s78, v79
	v_cndmask_b32_e64 v78, v79, v78, s[4:5]
	v_add_u32_e32 v78, s48, v78
	v_mad_i64_i32 v[78:79], s[56:57], v78, s86, v[222:223]
	v_cndmask_b32_e64 v82, v83, v82, s[4:5]
	v_lshl_add_u64 v[78:79], v[78:79], 0, s[68:69]
	v_add_u32_e32 v82, s48, v82
	v_lshl_add_u64 v[78:79], v[78:79], 0, s[18:19]
	v_mad_i64_i32 v[82:83], s[44:45], v82, s86, v[222:223]
	v_lshl_add_u64 v[78:79], v[78:79], 0, v[4:5]
	v_lshl_add_u64 v[82:83], v[82:83], 0, s[68:69]
	v_add_co_u32_e32 v78, vcc, s84, v78
	v_lshl_add_u64 v[82:83], v[82:83], 0, s[18:19]
	s_nop 0
	v_addc_co_u32_e32 v79, vcc, 0, v79, vcc
	v_lshl_add_u64 v[82:83], v[82:83], 0, v[4:5]
	v_add_co_u32_e32 v82, vcc, s84, v82
	s_waitcnt lgkmcnt(8)
	v_mfma_f32_16x16x32_bf16 v[182:185], v[182:185], v[114:117], v[90:93]
	v_addc_co_u32_e32 v83, vcc, 0, v83, vcc
	global_load_dwordx4 v[78:81], v[78:79], off
	s_waitcnt lgkmcnt(7)
	v_mfma_f32_16x16x32_bf16 v[186:189], v[186:189], v[114:117], v[94:97]
	global_load_dwordx4 v[82:85], v[82:83], off
	s_nop 0
	global_load_dwordx4 v[90:93], v[224:225], off offset:128
	global_load_dwordx4 v[94:97], v[224:225], off offset:192
	s_waitcnt lgkmcnt(6)
	v_mfma_f32_16x16x32_bf16 v[174:177], v[190:193], v[114:117], v[174:177]
	s_waitcnt lgkmcnt(5)
	v_mfma_f32_16x16x32_bf16 v[114:117], v[194:197], v[114:117], v[178:181]
	s_nop 2
	ds_read_b128 v[178:181], v226 offset:192
	ds_read_b128 v[190:193], v226 offset:4800
	ds_read_b128 v[194:197], v227 offset:192
	ds_read_b128 v[222:225], v226 offset:14016
	ds_read_b128 v[226:229], v226 offset:18624
	s_waitcnt lgkmcnt(8)
	v_mfma_f32_16x16x32_bf16 v[182:185], v[202:205], v[106:109], v[182:185]
	v_cndmask_b32_e64 v202, v230, v173, s[4:5]
	v_ashrrev_i32_e32 v203, 31, v202
	v_lshl_add_u64 v[202:203], s[0:1], 0, v[202:203]
	v_lshlrev_b64 v[202:203], 11, v[202:203]
	v_lshl_add_u64 v[202:203], v[132:133], 0, v[202:203]
	v_mfma_f32_16x16x32_bf16 v[198:201], v[198:201], v[106:109], v[218:221]
	global_store_dwordx4 v[202:203], v[98:101], off sc1
	global_store_dwordx4 v[202:203], v[74:77], off offset:64 sc1
	s_waitcnt lgkmcnt(7)
	v_mfma_f32_16x16x32_bf16 v[186:189], v[206:209], v[106:109], v[186:189]
	s_waitcnt lgkmcnt(6)
	v_mfma_f32_16x16x32_bf16 v[174:177], v[210:213], v[106:109], v[174:177]
	s_waitcnt lgkmcnt(5)
	v_mfma_f32_16x16x32_bf16 v[202:205], v[214:217], v[106:109], v[114:117]
	s_nop 2
	v_add3_u32 v116, s26, v145, v146
	ds_read_b64_tr_b16 v[98:99], v116
	ds_read_b64_tr_b16 v[74:75], v116 offset:32
	ds_read_b64_tr_b16 v[106:107], v116 offset:64
	ds_read_b64_tr_b16 v[114:115], v116 offset:96
	ds_read_b64_tr_b16 v[100:101], v116 offset:2560
	ds_read_b64_tr_b16 v[76:77], v116 offset:2592
	ds_read_b64_tr_b16 v[108:109], v116 offset:2624
	ds_read_b64_tr_b16 v[116:117], v116 offset:2656
	v_add3_u32 v173, s21, v147, v171
	ds_read_b64_tr_b16 v[234:235], v173 offset:64
	ds_read_b64_tr_b16 v[236:237], v173 offset:4672
	v_lshl_add_u32 v173, v126, 2, s27
	ds_read_b128 v[206:209], v173 offset:1600
	ds_read_b128 v[210:213], v173
	ds_read_b128 v[214:217], v173 offset:64
	ds_read_b128 v[218:221], v173 offset:1536
	ds_read_b128 v[230:233], v173 offset:128
	s_waitcnt lgkmcnt(14)
	v_mfma_f32_16x16x32_bf16 v[178:181], v[178:181], v[102:105], v[198:201]
	v_mfma_f32_16x16x32_bf16 v[182:185], v[190:193], v[102:105], v[182:185]
	v_mfma_f32_16x16x32_bf16 v[186:189], v[194:197], v[102:105], v[186:189]
	v_mfma_f32_16x16x32_bf16 v[174:177], v[222:225], v[102:105], v[174:177]
	v_mfma_f32_16x16x32_bf16 v[102:105], v[226:229], v[102:105], v[202:205]
	v_sub_f32_e32 v190, v239, v136
	v_mul_f32_e32 v190, 0x3fb8aa3b, v190
	v_sub_f32_e32 v191, v239, v238
	v_exp_f32_e32 v190, v190
	v_mul_f32_e32 v191, 0x3fb8aa3b, v191
	v_exp_f32_e32 v192, v191
	s_waitcnt lgkmcnt(3)
	v_fmac_f32_e32 v213, 0xbfb8aa3b, v136
	v_pk_mul_f32 v[180:181], v[190:191], v[180:181] op_sel_hi:[0,1]
	v_pk_mul_f32 v[178:179], v[190:191], v[178:179] op_sel_hi:[0,1]
	v_pk_mul_f32 v[184:185], v[190:191], v[184:185] op_sel_hi:[0,1]
	v_pk_mul_f32 v[182:183], v[190:191], v[182:183] op_sel_hi:[0,1]
	v_pk_mul_f32 v[188:189], v[190:191], v[188:189] op_sel_hi:[0,1]
	v_pk_mul_f32 v[186:187], v[190:191], v[186:187] op_sel_hi:[0,1]
	v_pk_mul_f32 v[176:177], v[190:191], v[176:177] op_sel_hi:[0,1]
	v_pk_mul_f32 v[174:175], v[190:191], v[174:175] op_sel_hi:[0,1]
	v_pk_mul_f32 v[104:105], v[190:191], v[104:105] op_sel_hi:[0,1]
	v_pk_mul_f32 v[102:103], v[190:191], v[102:103] op_sel_hi:[0,1]
	v_fmamk_f32 v190, v136, 0xbfb8aa3b, v210
	v_fmamk_f32 v191, v136, 0xbfb8aa3b, v211
	v_pk_mul_f32 v[36:37], v[36:37], v[192:193] op_sel_hi:[1,0]
	v_pk_mul_f32 v[34:35], v[34:35], v[192:193] op_sel_hi:[1,0]
	v_pk_mul_f32 v[32:33], v[32:33], v[192:193] op_sel_hi:[1,0]
	v_pk_mul_f32 v[30:31], v[30:31], v[192:193] op_sel_hi:[1,0]
	v_pk_mul_f32 v[28:29], v[28:29], v[192:193] op_sel_hi:[1,0]
	v_pk_mul_f32 v[26:27], v[26:27], v[192:193] op_sel_hi:[1,0]
	v_pk_mul_f32 v[24:25], v[24:25], v[192:193] op_sel_hi:[1,0]
	v_pk_mul_f32 v[22:23], v[22:23], v[192:193] op_sel_hi:[1,0]
	v_pk_mul_f32 v[16:17], v[16:17], v[192:193] op_sel_hi:[1,0]
	v_pk_mul_f32 v[14:15], v[14:15], v[192:193] op_sel_hi:[1,0]
	v_exp_f32_e32 v190, v190
	v_exp_f32_e32 v191, v191
	v_fmamk_f32 v192, v136, 0xbfb8aa3b, v212
	v_exp_f32_e32 v192, v192
	v_mul_f32_e32 v122, v122, v190
	v_mul_f32_e32 v123, v123, v191
	s_waitcnt lgkmcnt(2)
	v_fmamk_f32 v190, v136, 0xbfb8aa3b, v214
	v_fmamk_f32 v191, v136, 0xbfb8aa3b, v215
	v_mul_f32_e32 v124, v124, v192
	v_exp_f32_e32 v190, v190
	v_exp_f32_e32 v191, v191
	v_fmamk_f32 v192, v136, 0xbfb8aa3b, v216
	v_exp_f32_e32 v192, v192
	v_exp_f32_e32 v193, v213
	v_mul_f32_e32 v118, v118, v190
	v_mul_f32_e32 v119, v119, v191
	s_waitcnt lgkmcnt(0)
	v_fmamk_f32 v190, v136, 0xbfb8aa3b, v230
	v_fmamk_f32 v191, v136, 0xbfb8aa3b, v231
	v_mul_f32_e32 v120, v120, v192
	v_exp_f32_e32 v190, v190
	v_exp_f32_e32 v191, v191
	v_fmamk_f32 v192, v136, 0xbfb8aa3b, v232
	v_fmac_f32_e32 v217, 0xbfb8aa3b, v136
	v_exp_f32_e32 v192, v192
	v_fmac_f32_e32 v233, 0xbfb8aa3b, v136
	v_mul_f32_e32 v125, v125, v193
	v_exp_f32_e32 v193, v217
	v_exp_f32_e32 v136, v233
	v_mul_f32_e32 v190, v110, v190
	v_mul_f32_e32 v191, v111, v191
	v_mul_f32_e32 v192, v112, v192
	v_cvt_pk_bf16_f32 v112, v118, v119
	v_cvt_pk_bf16_f32 v118, v190, s0
	v_cvt_pk_bf16_f32 v119, v191, s0
	v_mul_f32_e32 v121, v121, v193
	v_mul_f32_e32 v136, v113, v136
	v_cndmask_b32_e64 v118, v118, 0, s[6:7]
	v_cndmask_b32_e64 v119, 0, v119, s[8:9]
	v_cvt_pk_bf16_f32 v113, v120, v121
	v_perm_b32 v118, v119, v118, s89
	v_cvt_pk_bf16_f32 v119, v192, s0
	v_cvt_pk_bf16_f32 v120, v136, s0
	v_cvt_pk_bf16_f32 v110, v122, v123
	v_cndmask_b32_e64 v119, v119, 0, s[10:11]
	v_cndmask_b32_e64 v120, v120, 0, s[12:13]
	v_cvt_pk_bf16_f32 v111, v124, v125
	v_perm_b32 v119, v120, v119, s89
	v_mov_b32_e32 v120, v5
	v_mov_b32_e32 v121, v5
	v_add3_u32 v136, s26, v148, v171
	ds_read_b64_tr_b16 v[122:123], v136
	ds_read_b64_tr_b16 v[190:191], v136 offset:32
	ds_read_b64_tr_b16 v[194:195], v136 offset:64
	ds_read_b64_tr_b16 v[198:199], v136 offset:96
	ds_read_b64_tr_b16 v[124:125], v136 offset:2560
	ds_read_b64_tr_b16 v[192:193], v136 offset:2592
	ds_read_b64_tr_b16 v[196:197], v136 offset:2624
	ds_read_b64_tr_b16 v[200:201], v136 offset:2656
	v_add3_u32 v136, s21, v149, v171
	ds_read_b64_tr_b16 v[230:231], v136 offset:64
	ds_read_b64_tr_b16 v[232:233], v136 offset:4672
	ds_read_b128 v[202:205], v173 offset:1664
	ds_read_b128 v[210:213], v173 offset:1728
	v_mfma_f32_16x16x32_bf16 v[178:181], v[98:101], v[110:113], v[178:181]
	v_and_b32_e32 v136, 0xffff0000, v237
	v_mul_f32_e32 v136, v209, v136
	v_mfma_f32_16x16x32_bf16 v[182:185], v[74:77], v[110:113], v[182:185]
	v_mfma_f32_16x16x32_bf16 v[186:189], v[106:109], v[110:113], v[186:189]
	v_mfma_f32_16x16x32_bf16 v[174:177], v[114:117], v[110:113], v[174:177]
	v_mfma_f32_16x16x32_bf16 v[110:113], v[6:9], v[110:113], v[102:105]
	s_nop 2
	v_lshlrev_b32_e32 v102, 16, v234
	v_and_b32_e32 v103, 0xffff0000, v234
	v_mul_f32_e32 v102, v218, v102
	v_mul_f32_e32 v103, v219, v103
	v_cvt_pk_bf16_f32 v102, v102, v103
	v_lshlrev_b32_e32 v103, 16, v235
	v_and_b32_e32 v104, 0xffff0000, v235
	v_mul_f32_e32 v103, v220, v103
	v_mul_f32_e32 v104, v221, v104
	v_cvt_pk_bf16_f32 v103, v103, v104
	v_lshlrev_b32_e32 v104, 16, v236
	v_and_b32_e32 v105, 0xffff0000, v236
	v_mul_f32_e32 v104, v206, v104
	v_mul_f32_e32 v105, v207, v105
	v_cvt_pk_bf16_f32 v104, v104, v105
	v_lshlrev_b32_e32 v105, 16, v237
	v_mul_f32_e32 v105, v208, v105
	v_cvt_pk_bf16_f32 v105, v105, v136
	s_nop 1
	v_mfma_f32_16x16x32_bf16 v[34:37], v[102:105], v[98:101], v[34:37]
	v_mfma_f32_16x16x32_bf16 v[30:33], v[102:105], v[74:77], v[30:33]
	v_mfma_f32_16x16x32_bf16 v[26:29], v[102:105], v[106:109], v[26:29]
	v_mfma_f32_16x16x32_bf16 v[22:25], v[102:105], v[114:117], v[22:25]
	v_mfma_f32_16x16x32_bf16 v[14:17], v[102:105], v[6:9], v[14:17]
	v_add3_u32 v74, s26, v150, v171
	ds_read_b64_tr_b16 v[114:115], v74
	ds_read_b64_tr_b16 v[206:207], v74 offset:32
	ds_read_b64_tr_b16 v[214:215], v74 offset:64
	ds_read_b64_tr_b16 v[218:219], v74 offset:96
	ds_read_b64_tr_b16 v[116:117], v74 offset:2560
	ds_read_b64_tr_b16 v[208:209], v74 offset:2592
	ds_read_b64_tr_b16 v[216:217], v74 offset:2624
	ds_read_b64_tr_b16 v[220:221], v74 offset:2656
	v_add3_u32 v74, s21, v151, v171
	ds_read_b64_tr_b16 v[234:235], v74 offset:64
	ds_read_b64_tr_b16 v[236:237], v74 offset:4672
	ds_read_b128 v[222:225], v173 offset:1792
	ds_read_b128 v[226:229], v173 offset:1856
	v_mfma_f32_16x16x32_bf16 v[110:113], v[6:9], v[118:121], v[110:113]
	s_waitcnt lgkmcnt(14)
	v_mfma_f32_16x16x32_bf16 v[98:101], v[122:125], v[118:121], v[178:181]
	v_mfma_f32_16x16x32_bf16 v[106:109], v[190:193], v[118:121], v[182:185]
	s_nop 4
	v_lshlrev_b32_e32 v111, 16, v230
	v_and_b32_e32 v112, 0xffff0000, v230
	s_waitcnt lgkmcnt(13)
	v_mul_f32_e32 v111, v202, v111
	v_mul_f32_e32 v112, v203, v112
	v_mfma_f32_16x16x32_bf16 v[74:77], v[194:197], v[118:121], v[186:189]
	v_mfma_f32_16x16x32_bf16 v[102:105], v[198:201], v[118:121], v[174:177]
	v_cvt_pk_bf16_f32 v118, v111, v112
	v_lshlrev_b32_e32 v111, 16, v231
	v_and_b32_e32 v112, 0xffff0000, v231
	v_mul_f32_e32 v111, v204, v111
	v_mul_f32_e32 v112, v205, v112
	v_cvt_pk_bf16_f32 v119, v111, v112
	v_lshlrev_b32_e32 v111, 16, v232
	v_and_b32_e32 v112, 0xffff0000, v232
	s_waitcnt lgkmcnt(12)
	v_mul_f32_e32 v111, v210, v111
	v_mul_f32_e32 v112, v211, v112
	v_cvt_pk_bf16_f32 v120, v111, v112
	v_lshlrev_b32_e32 v111, 16, v233
	v_and_b32_e32 v112, 0xffff0000, v233
	v_mul_f32_e32 v111, v212, v111
	v_mul_f32_e32 v112, v213, v112
	v_cvt_pk_bf16_f32 v121, v111, v112
	s_nop 1
	v_mfma_f32_16x16x32_bf16 v[34:37], v[118:121], v[122:125], v[34:37]
	v_mfma_f32_16x16x32_bf16 v[30:33], v[118:121], v[190:193], v[30:33]
	v_mfma_f32_16x16x32_bf16 v[26:29], v[118:121], v[194:197], v[26:29]
	v_mfma_f32_16x16x32_bf16 v[22:25], v[118:121], v[198:201], v[22:25]
	v_mfma_f32_16x16x32_bf16 v[14:17], v[118:121], v[6:9], v[14:17]
	v_add3_u32 v111, s26, v152, v171
	ds_read_b64_tr_b16 v[118:119], v111
	ds_read_b64_tr_b16 v[122:123], v111 offset:32
	ds_read_b64_tr_b16 v[174:175], v111 offset:64
	ds_read_b64_tr_b16 v[178:179], v111 offset:96
	ds_read_b64_tr_b16 v[120:121], v111 offset:2560
	ds_read_b64_tr_b16 v[124:125], v111 offset:2592
	ds_read_b64_tr_b16 v[176:177], v111 offset:2624
	ds_read_b64_tr_b16 v[180:181], v111 offset:2656
	v_add3_u32 v111, s21, v153, v171
	ds_read_b64_tr_b16 v[112:113], v111 offset:64
	ds_read_b64_tr_b16 v[194:195], v111 offset:4672
	ds_read_b128 v[182:185], v173 offset:1920
	ds_read_b128 v[186:189], v173 offset:1984
	s_waitcnt lgkmcnt(14)
	v_lshlrev_b32_e32 v111, 16, v234
	v_and_b32_e32 v136, 0xffff0000, v234
	s_waitcnt lgkmcnt(13)
	v_mul_f32_e32 v111, v222, v111
	v_mul_f32_e32 v136, v223, v136
	v_cvt_pk_bf16_f32 v190, v111, v136
	v_lshlrev_b32_e32 v111, 16, v235
	v_and_b32_e32 v136, 0xffff0000, v235
	v_mul_f32_e32 v111, v224, v111
	v_mul_f32_e32 v136, v225, v136
	v_cvt_pk_bf16_f32 v191, v111, v136
	v_lshlrev_b32_e32 v111, 16, v236
	v_and_b32_e32 v136, 0xffff0000, v236
	s_waitcnt lgkmcnt(12)
	v_mul_f32_e32 v111, v226, v111
	v_mul_f32_e32 v136, v227, v136
	v_cvt_pk_bf16_f32 v192, v111, v136
	v_lshlrev_b32_e32 v111, 16, v237
	v_and_b32_e32 v136, 0xffff0000, v237
	v_mul_f32_e32 v111, v228, v111
	v_mul_f32_e32 v136, v229, v136
	v_cvt_pk_bf16_f32 v193, v111, v136
	s_nop 1
	v_mfma_f32_16x16x32_bf16 v[34:37], v[190:193], v[114:117], v[34:37]
	v_mfma_f32_16x16x32_bf16 v[30:33], v[190:193], v[206:209], v[30:33]
	v_mfma_f32_16x16x32_bf16 v[26:29], v[190:193], v[214:217], v[26:29]
	v_mfma_f32_16x16x32_bf16 v[22:25], v[190:193], v[218:221], v[22:25]
	v_mfma_f32_16x16x32_bf16 v[14:17], v[190:193], v[6:9], v[14:17]
	s_waitcnt lgkmcnt(3)
	v_lshlrev_b32_e32 v111, 16, v112
	v_and_b32_e32 v112, 0xffff0000, v112
	s_waitcnt lgkmcnt(1)
	v_mul_f32_e32 v111, v182, v111
	v_mul_f32_e32 v112, v183, v112
	v_cvt_pk_bf16_f32 v112, v111, v112
	v_lshlrev_b32_e32 v111, 16, v113
	v_and_b32_e32 v113, 0xffff0000, v113
	v_mul_f32_e32 v111, v184, v111
	v_mul_f32_e32 v113, v185, v113
	v_cvt_pk_bf16_f32 v113, v111, v113
	v_lshlrev_b32_e32 v111, 16, v194
	v_and_b32_e32 v114, 0xffff0000, v194
	s_waitcnt lgkmcnt(0)
	v_mul_f32_e32 v111, v186, v111
	v_mul_f32_e32 v114, v187, v114
	v_cvt_pk_bf16_f32 v114, v111, v114
	v_lshlrev_b32_e32 v111, 16, v195
	v_and_b32_e32 v115, 0xffff0000, v195
	v_mul_f32_e32 v111, v188, v111
	v_mul_f32_e32 v115, v189, v115
	v_cvt_pk_bf16_f32 v115, v111, v115
	s_nop 1
	v_mfma_f32_16x16x32_bf16 v[34:37], v[112:115], v[118:121], v[34:37]
	v_mfma_f32_16x16x32_bf16 v[30:33], v[112:115], v[122:125], v[30:33]
	v_mfma_f32_16x16x32_bf16 v[26:29], v[112:115], v[174:177], v[26:29]
	v_mfma_f32_16x16x32_bf16 v[22:25], v[112:115], v[178:181], v[22:25]
	v_mfma_f32_16x16x32_bf16 v[14:17], v[112:115], v[6:9], v[14:17]
	s_xor_b32 s19, s20, 1
	s_mulk_i32 s19, 0x4a00
	s_add_i32 s19, s19, 0
	v_lshlrev_b32_e32 v111, 1, v126
	v_add3_u32 v114, s19, v127, v111
	ds_bpermute_b32 v110, v154, v110
	v_cvt_pk_bf16_f32 v112, v34, v35
	v_cvt_pk_bf16_f32 v113, v36, v37
	v_add_u32_e32 v115, 0x1c040, v114
	ds_write_b64 v115, v[112:113]
	v_cvt_pk_bf16_f32 v112, v30, v31
	v_cvt_pk_bf16_f32 v113, v32, v33
	v_add_u32_e32 v115, 0x1d240, v114
	ds_write_b64 v115, v[112:113]
	v_add_u32_e32 v115, s19, v169
	s_mov_b32 s20, 0x1c040
	v_cvt_pk_bf16_f32 v112, v26, v27
	v_cvt_pk_bf16_f32 v113, v28, v29
	v_add3_u32 v111, v115, v111, s20
	ds_write_b64 v111, v[112:113]
	v_cvt_pk_bf16_f32 v112, v22, v23
	v_cvt_pk_bf16_f32 v113, v24, v25
	v_add_u32_e32 v111, 0x1f640, v114
	ds_write_b64 v111, v[112:113]
	s_and_saveexec_b64 s[20:21], s[2:3]
	s_cbranch_execz .LBB0_367
	v_lshl_add_u32 v111, v126, 1, s19
	v_cvt_pk_bf16_f32 v112, v14, v15
	v_cvt_pk_bf16_f32 v113, v16, v17
	v_add_u32_e32 v111, 0x20840, v111
	ds_write_b64 v111, v[112:113]
	s_branch .LBB0_367
.LBB0_370:
	s_add_i32 s2, s78, 0xffffff80
	v_or_b32_e32 v4, s2, v143
	v_xad_u32 v6, v4, -1, s78
	v_cndmask_b32_e64 v6, v6, v4, s[4:5]
	v_ashrrev_i32_e32 v7, 31, v6
	v_lshl_add_u64 v[6:7], s[0:1], 0, v[6:7]
	v_lshlrev_b64 v[6:7], 11, v[6:7]
	v_lshl_add_u64 v[6:7], s[42:43], 0, v[6:7]
	v_lshl_add_u64 v[6:7], v[6:7], 0, s[68:69]
	s_mov_b32 s19, s69
	v_lshl_add_u64 v[6:7], v[6:7], 0, s[18:19]
	v_lshl_add_u64 v[2:3], v[2:3], 1, v[6:7]
	s_and_b64 vcc, exec, s[46:47]
	global_store_dwordx4 v[2:3], v[98:101], off sc1
	global_store_dwordx4 v[2:3], v[74:77], off offset:64 sc1
	s_cbranch_vccz .LBB0_374
	s_waitcnt vmcnt(18)
	v_mbcnt_lo_u32_b32 v20, -1, 0
	v_mbcnt_hi_u32_b32 v20, -1, v20
	s_ashr_i32 s17, s16, 31
	v_lshlrev_b32_e32 v3, 1, v20
	v_ashrrev_i32_e32 v2, 2, v20
	v_and_b32_e32 v3, 24, v3
	v_and_b32_e32 v4, 3, v20
	s_lshl_b64 s[0:1], s[16:17], 16
	v_and_b32_e32 v2, -4, v2
	v_or3_b32 v3, v4, v3, s25
	s_add_u32 s0, s76, s0
	v_lshlrev_b32_e32 v4, 2, v3
	v_ashrrev_i32_e32 v3, 31, v2
	s_addc_u32 s1, s77, s1
	v_lshlrev_b64 v[6:7], 9, v[2:3]
	v_lshl_add_u64 v[6:7], s[0:1], 0, v[6:7]
	v_lshl_add_u64 v[6:7], v[6:7], 0, v[4:5]
	s_mov_b64 s[0:1], 0x4000
	v_lshl_add_u64 v[8:9], v[6:7], 0, s[0:1]
	s_movk_i32 s0, 0x4000
	v_add_co_u32_e32 v10, vcc, s0, v6
	s_mov_b64 s[0:1], 0x4200
	s_nop 0
	v_addc_co_u32_e32 v11, vcc, 0, v7, vcc
	v_lshl_add_u64 v[12:13], v[6:7], 0, s[0:1]
	s_mov_b64 s[0:1], 0x4400
	v_and_or_b32 v4, v20, 15, s31
	v_lshl_add_u64 v[18:19], v[6:7], 0, s[0:1]
	s_mov_b64 s[0:1], 0x4600
	v_cmp_eq_u32_e32 vcc, 0, v4
	global_store_dword v[10:11], v34, off
	global_store_dword v[10:11], v35, off offset:512
	global_store_dword v[10:11], v36, off offset:1024
	v_lshl_add_u64 v[6:7], v[6:7], 0, s[0:1]
	global_store_dword v[10:11], v37, off offset:1536
	global_store_dword v[8:9], v30, off offset:16
	global_store_dword v[12:13], v31, off offset:16
	global_store_dword v[18:19], v32, off offset:16
	global_store_dword v[6:7], v33, off offset:16
	global_store_dword v[8:9], v26, off offset:128
	global_store_dword v[12:13], v27, off offset:128
	global_store_dword v[18:19], v28, off offset:128
	global_store_dword v[6:7], v29, off offset:128
	global_store_dword v[8:9], v22, off offset:144
	global_store_dword v[12:13], v23, off offset:144
	global_store_dword v[18:19], v24, off offset:144
	global_store_dword v[6:7], v25, off offset:144
	s_and_saveexec_b64 s[0:1], vcc
	s_cbranch_execz .LBB0_373
	s_lshl_b64 s[2:3], s[16:17], 9
	v_readlane_b32 s4, v254, 26
	s_add_u32 s2, s4, s2
	v_readlane_b32 s4, v254, 27
	s_addc_u32 s3, s4, s3
	v_lshl_add_u64 v[2:3], v[2:3], 2, s[2:3]
	global_store_dwordx4 v[2:3], v[14:17], off offset:128 sc1

.LBB0_384:
	s_mov_b32 s19, s1
	s_min_u32 s1, s1, 1
	s_lshl_b32 s1, s1, 7
	s_and_b32 s20, s19, 1
	v_subrev_u32_e32 v181, s1, v180
	v_add_u32_e32 v226, s1, v137
	s_mul_i32 s1, s20, 0x9000
	s_add_i32 s21, s1, 0
	s_mul_i32 s1, s20, 0x5000
	s_waitcnt vmcnt(6)
	v_mov_b64_e32 v[120:121], v[84:85]
	s_add_i32 s26, s1, 0
	v_mov_b64_e32 v[118:119], v[82:83]
	s_add_i32 s26, s26, 0x12000
	v_add3_u32 v82, s21, v136, v175
	ds_write_b128 v82, v[30:33]
	ds_write_b128 v82, v[34:37] offset:4608
	ds_write_b128 v82, v[38:41] offset:9216
	ds_write_b128 v82, v[42:45] offset:13824
	ds_write_b128 v82, v[50:53] offset:18432
	ds_write_b128 v82, v[54:57] offset:23040
	ds_write_b128 v82, v[58:61] offset:27648
	ds_write_b128 v82, v[62:65] offset:32256
	v_lshl_add_u32 v30, v152, 1, s26
	s_lshl_b32 s1, s20, 11
	v_add3_u32 v30, v30, v178, v176
	s_add_i32 s27, s1, 0
	v_add_u32_e32 v31, 0x1000, v30
	s_add_i32 s27, s27, 0x25a00
	s_lshl_b32 s1, s20, 4
	ds_write2_b64 v31, v[66:67], v[68:69] offset0:128 offset1:132
	v_add_u32_e32 v31, 0x2800, v30
	s_waitcnt vmcnt(5)
	ds_write2_b64 v31, v[74:75], v[76:77] offset1:4
	s_add_i32 s1, s1, 0
	v_lshl_add_u32 v31, v148, 2, s27
	v_lshlrev_b32_e32 v122, 1, v134
	ds_write2_b64 v30, v[70:71], v[72:73] offset1:4
	v_add_u32_e32 v30, 0x3800, v30
	s_add_i32 s37, s1, 0x26a00
	v_add_u32_e32 v31, 64, v31
	v_add_u32_e32 v34, s21, v122
	s_waitcnt vmcnt(4)
	ds_write2_b64 v30, v[78:79], v[80:81] offset0:128 offset1:132
	s_waitcnt lgkmcnt(0)
	s_barrier
	v_mov_b32_e32 v30, s27
	ds_read2st64_b32 v[146:147], v31 offset0:2 offset1:4
	v_mov_b32_e32 v31, s37
	v_add_u32_e32 v32, v34, v3
	ds_read_b32 v227, v30 offset:1020
	ds_read_b32 v228, v31
	ds_read_b128 v[30:33], v32
	v_add_u32_e32 v34, v34, v177
	ds_read_b128 v[34:37], v34
	s_add_i32 s1, s19, 1
	s_waitcnt vmcnt(3)
	v_mov_b64_e32 v[108:109], v[88:89]
	s_waitcnt vmcnt(2)
	v_mov_b64_e32 v[104:105], v[92:93]
	s_mul_i32 s36, s20, 0x4a00
	s_cmp_lt_u32 s1, s79
	v_mov_b64_e32 v[106:107], v[86:87]
	v_mov_b64_e32 v[102:103], v[90:91]
	s_cselect_b32 s19, s1, s19
	s_add_i32 s36, s36, 0
	s_add_i32 s36, s36, 0x1c000
	v_add3_u32 v66, s21, v3, v122
	v_add3_u32 v70, s21, v177, v122
	ds_read_b128 v[38:41], v66 offset:64
	ds_read_b128 v[42:45], v70 offset:64
	s_lshl_b32 s44, s19, 7
	s_waitcnt lgkmcnt(2)
	v_mfma_f32_16x16x32_bf16 v[54:57], v[34:37], v[46:49], 0
	v_or_b32_e32 v123, s44, v150
	v_bitop3_b32 v35, s44, v156, v150 bitop3:0x36
	v_or_b32_e32 v34, 16, v123
	v_mfma_f32_16x16x32_bf16 v[50:53], v[30:33], v[46:49], 0
	v_xad_u32 v30, v123, -1, s78
	v_add_u32_e32 v35, s78, v35
	v_cndmask_b32_e64 v30, v30, v123, s[4:5]
	v_cndmask_b32_e64 v34, v35, v34, s[4:5]
	v_add_u32_e32 v30, s48, v30
	v_add_u32_e32 v34, s48, v34
	v_mad_i64_i32 v[30:31], s[56:57], v30, s86, v[144:145]
	v_mad_i64_i32 v[34:35], s[56:57], v34, s86, v[144:145]
	global_load_dwordx4 v[30:33], v[30:31], off offset:2048
	s_nop 0
	global_load_dwordx4 v[34:37], v[34:35], off offset:2048
	ds_read_b128 v[58:61], v66 offset:128
	ds_read_b128 v[62:65], v70 offset:128
	s_waitcnt lgkmcnt(3)
	v_mfma_f32_16x16x32_bf16 v[50:53], v[38:41], v[118:121], v[50:53]
	v_bitop3_b32 v39, s44, v157, v150 bitop3:0x36
	v_or_b32_e32 v38, 32, v123
	v_add_u32_e32 v39, s78, v39
	s_waitcnt lgkmcnt(2)
	v_mfma_f32_16x16x32_bf16 v[54:57], v[42:45], v[118:121], v[54:57]
	v_bitop3_b32 v43, s44, v158, v150 bitop3:0x36
	v_or_b32_e32 v42, 48, v123
	v_add_u32_e32 v43, s78, v43
	v_cndmask_b32_e64 v38, v39, v38, s[4:5]
	v_cndmask_b32_e64 v42, v43, v42, s[4:5]
	v_add_u32_e32 v38, s48, v38
	v_add_u32_e32 v42, s48, v42
	v_mad_i64_i32 v[38:39], s[56:57], v38, s86, v[144:145]
	v_mad_i64_i32 v[42:43], s[56:57], v42, s86, v[144:145]
	global_load_dwordx4 v[38:41], v[38:39], off offset:2048
	s_nop 0
	global_load_dwordx4 v[42:45], v[42:43], off offset:2048
	ds_read_b128 v[66:69], v66 offset:192
	ds_read_b128 v[70:73], v70 offset:192
	s_waitcnt lgkmcnt(3)
	v_mfma_f32_16x16x32_bf16 v[58:61], v[58:61], v[106:109], v[50:53]
	s_waitcnt lgkmcnt(2)
	v_mfma_f32_16x16x32_bf16 v[62:65], v[62:65], v[106:109], v[54:57]
	s_nop 0
	v_bitop3_b32 v51, s44, v159, v150 bitop3:0x36
	v_or_b32_e32 v50, 64, v123
	v_add_u32_e32 v51, s78, v51
	v_bitop3_b32 v55, s44, v160, v150 bitop3:0x36
	v_or_b32_e32 v54, 0x50, v123
	v_add_u32_e32 v55, s78, v55
	v_cndmask_b32_e64 v50, v51, v50, s[4:5]
	v_cndmask_b32_e64 v54, v55, v54, s[4:5]
	v_add_u32_e32 v50, s48, v50
	v_add_u32_e32 v54, s48, v54
	v_mad_i64_i32 v[50:51], s[56:57], v50, s86, v[144:145]
	v_mad_i64_i32 v[54:55], s[56:57], v54, s86, v[144:145]
	global_load_dwordx4 v[50:53], v[50:51], off offset:2048
	s_nop 0
	global_load_dwordx4 v[54:57], v[54:55], off offset:2048
	v_add_u32_e32 v74, s36, v122
	v_add_u32_e32 v90, v74, v3
	v_add_u32_e32 v74, v74, v177
	ds_read_b128 v[74:77], v74
	ds_read_b128 v[78:81], v90
	ds_read_b128 v[82:85], v90 offset:9216
	ds_read_b128 v[86:89], v90 offset:13824
	ds_read_b128 v[90:93], v90 offset:18432
	s_waitcnt lgkmcnt(6)
	v_mfma_f32_16x16x32_bf16 v[114:117], v[66:69], v[102:105], v[58:61]
	s_waitcnt lgkmcnt(5)
	v_mfma_f32_16x16x32_bf16 v[110:113], v[70:73], v[102:105], v[62:65]
	s_nop 0
	v_bitop3_b32 v59, s44, v161, v150 bitop3:0x36
	v_or_b32_e32 v58, 0x60, v123
	v_add_u32_e32 v59, s78, v59
	v_bitop3_b32 v63, s44, v162, v150 bitop3:0x36
	v_or_b32_e32 v62, 0x70, v123
	v_add_u32_e32 v63, s78, v63
	v_cndmask_b32_e64 v58, v59, v58, s[4:5]
	v_cndmask_b32_e64 v62, v63, v62, s[4:5]
	v_add_u32_e32 v58, s48, v58
	v_add_u32_e32 v62, s48, v62
	v_mad_i64_i32 v[58:59], s[56:57], v58, s86, v[144:145]
	v_mad_i64_i32 v[62:63], s[56:57], v62, s86, v[144:145]
	global_load_dwordx4 v[58:61], v[58:59], off offset:2048
	s_nop 0
	global_load_dwordx4 v[62:65], v[62:63], off offset:2048
	v_add3_u32 v218, s36, v177, v122
	v_add3_u32 v222, s36, v3, v122
	ds_read_b128 v[122:125], v218 offset:64
	ds_read_b128 v[126:129], v222 offset:64
	ds_read_b128 v[130:133], v222 offset:9280
	ds_read_b128 v[182:185], v222 offset:13888
	ds_read_b128 v[186:189], v222 offset:18496
	v_or_b32_e32 v219, s44, v149
	v_xad_u32 v66, v219, -1, s78
	s_waitcnt lgkmcnt(8)
	v_mfma_f32_16x16x32_bf16 v[78:81], v[78:81], v[46:49], 0
	v_cndmask_b32_e64 v66, v66, v219, s[4:5]
	v_add_u32_e32 v66, s48, v66
	v_mov_b64_e32 v[214:215], s[40:41]
	v_mfma_f32_16x16x32_bf16 v[74:77], v[74:77], v[46:49], 0
	v_mad_i64_i32 v[66:67], s[56:57], v66, s86, v[214:215]
	v_lshl_add_u64 v[66:67], v[66:67], 0, s[68:69]
	s_waitcnt lgkmcnt(7)
	v_mfma_f32_16x16x32_bf16 v[190:193], v[82:85], v[46:49], 0
	s_mov_b32 s19, s69
	v_lshl_add_u64 v[66:67], v[66:67], 0, s[18:19]
	v_lshl_add_u64 v[66:67], v[66:67], 0, v[4:5]
	s_waitcnt lgkmcnt(6)
	v_mfma_f32_16x16x32_bf16 v[86:89], v[86:89], v[46:49], 0
	s_waitcnt lgkmcnt(5)
	v_mfma_f32_16x16x32_bf16 v[90:93], v[90:93], v[46:49], 0
	v_bitop3_b32 v49, s44, v157, v149 bitop3:0x36
	v_or_b32_e32 v48, 32, v219
	v_add_u32_e32 v49, s78, v49
	v_cndmask_b32_e64 v48, v49, v48, s[4:5]
	v_add_u32_e32 v48, s48, v48
	v_mad_i64_i32 v[48:49], s[56:57], v48, s86, v[214:215]
	v_lshl_add_u64 v[48:49], v[48:49], 0, s[68:69]
	v_add_co_u32_e32 v46, vcc, s84, v66
	v_lshl_add_u64 v[48:49], v[48:49], 0, s[18:19]
	s_nop 0
	v_addc_co_u32_e32 v47, vcc, 0, v67, vcc
	v_lshl_add_u64 v[48:49], v[48:49], 0, v[4:5]
	v_add_co_u32_e32 v48, vcc, s84, v48
	s_nop 1
	v_addc_co_u32_e32 v49, vcc, 0, v49, vcc
	global_load_dwordx4 v[70:73], v[46:47], off
	global_load_dwordx4 v[66:69], v[48:49], off
	v_or_b32_e32 v46, s44, v151
	v_xad_u32 v47, v46, -1, s78
	v_cndmask_b32_e64 v46, v47, v46, s[4:5]
	v_add_u32_e32 v46, s48, v46
	v_mad_i64_i32 v[216:217], s[56:57], v46, s86, v[140:141]
	global_load_dwordx4 v[46:49], v[216:217], off
	global_load_dwordx4 v[82:85], v[216:217], off offset:64
	ds_read_b128 v[194:197], v218 offset:128
	ds_read_b128 v[198:201], v222 offset:128
	ds_read_b128 v[202:205], v222 offset:9344
	ds_read_b128 v[206:209], v222 offset:13952
	ds_read_b128 v[210:213], v222 offset:18560
	s_waitcnt lgkmcnt(9)
	v_mfma_f32_16x16x32_bf16 v[122:125], v[122:125], v[118:121], v[74:77]
	s_nop 2
	v_bitop3_b32 v75, s44, v159, v149 bitop3:0x36
	v_or_b32_e32 v74, 64, v219
	v_add_u32_e32 v75, s78, v75
	s_waitcnt lgkmcnt(8)
	v_mfma_f32_16x16x32_bf16 v[126:129], v[126:129], v[118:121], v[78:81]
	v_cndmask_b32_e64 v74, v75, v74, s[4:5]
	v_add_u32_e32 v74, s48, v74
	v_mad_i64_i32 v[74:75], s[56:57], v74, s86, v[214:215]
	v_bitop3_b32 v79, s44, v161, v149 bitop3:0x36
	v_or_b32_e32 v78, 0x60, v219
	v_add_u32_e32 v79, s78, v79
	v_cndmask_b32_e64 v78, v79, v78, s[4:5]
	v_lshl_add_u64 v[74:75], v[74:75], 0, s[68:69]
	v_add_u32_e32 v78, s48, v78
	v_lshl_add_u64 v[74:75], v[74:75], 0, s[18:19]
	v_mad_i64_i32 v[78:79], s[44:45], v78, s86, v[214:215]
	v_lshl_add_u64 v[74:75], v[74:75], 0, v[4:5]
	v_lshl_add_u64 v[78:79], v[78:79], 0, s[68:69]
	v_add_co_u32_e32 v74, vcc, s84, v74
	v_lshl_add_u64 v[78:79], v[78:79], 0, s[18:19]
	s_nop 0
	v_addc_co_u32_e32 v75, vcc, 0, v75, vcc
	v_lshl_add_u64 v[78:79], v[78:79], 0, v[4:5]
	v_add_co_u32_e32 v78, vcc, s84, v78
	s_waitcnt lgkmcnt(7)
	v_mfma_f32_16x16x32_bf16 v[130:133], v[130:133], v[118:121], v[190:193]
	v_addc_co_u32_e32 v79, vcc, 0, v79, vcc
	global_load_dwordx4 v[74:77], v[74:75], off
	s_waitcnt lgkmcnt(6)
	v_mfma_f32_16x16x32_bf16 v[182:185], v[182:185], v[118:121], v[86:89]
	s_waitcnt lgkmcnt(5)
	v_mfma_f32_16x16x32_bf16 v[118:121], v[186:189], v[118:121], v[90:93]
	global_load_dwordx4 v[78:81], v[78:79], off
	s_nop 0
	global_load_dwordx4 v[86:89], v[216:217], off offset:128
	global_load_dwordx4 v[90:93], v[216:217], off offset:192
	ds_read_b128 v[186:189], v218 offset:192
	ds_read_b128 v[190:193], v222 offset:192
	ds_read_b128 v[214:217], v222 offset:9408
	ds_read_b128 v[218:221], v222 offset:14016
	ds_read_b128 v[222:225], v222 offset:18624
	s_waitcnt lgkmcnt(9)
	v_mfma_f32_16x16x32_bf16 v[194:197], v[194:197], v[106:109], v[122:125]
	s_nop 2
	v_cndmask_b32_e64 v122, v226, v181, s[4:5]
	v_ashrrev_i32_e32 v123, 31, v122
	v_lshl_add_u64 v[122:123], s[16:17], 0, v[122:123]
	v_lshlrev_b64 v[122:123], 11, v[122:123]
	v_lshl_add_u64 v[122:123], v[142:143], 0, v[122:123]
	global_store_dwordx4 v[122:123], v[94:97], off sc1
	global_store_dwordx4 v[122:123], v[98:101], off offset:64 sc1
	s_waitcnt lgkmcnt(8)
	v_mfma_f32_16x16x32_bf16 v[198:201], v[198:201], v[106:109], v[126:129]
	s_waitcnt lgkmcnt(5)
	v_mfma_f32_16x16x32_bf16 v[94:97], v[210:213], v[106:109], v[118:121]
	v_mfma_f32_16x16x32_bf16 v[202:205], v[202:205], v[106:109], v[130:133]
	v_mfma_f32_16x16x32_bf16 v[182:185], v[206:209], v[106:109], v[182:185]
	v_add3_u32 v98, s26, v153, v154
	ds_read_b64_tr_b16 v[122:123], v98
	ds_read_b64_tr_b16 v[118:119], v98 offset:32
	ds_read_b64_tr_b16 v[126:127], v98 offset:64
	ds_read_b64_tr_b16 v[130:131], v98 offset:96
	ds_read_b64_tr_b16 v[124:125], v98 offset:2560
	ds_read_b64_tr_b16 v[120:121], v98 offset:2592
	ds_read_b64_tr_b16 v[128:129], v98 offset:2624
	ds_read_b64_tr_b16 v[132:133], v98 offset:2656
	v_add3_u32 v98, s21, v155, v179
	v_lshl_add_u32 v181, v2, 2, s27
	ds_read_b64_tr_b16 v[230:231], v98 offset:32
	ds_read_b64_tr_b16 v[232:233], v98 offset:4640
	ds_read_b128 v[206:209], v181 offset:1536
	ds_read_b128 v[210:213], v181 offset:1600
	ds_read_b128 v[98:101], v181
	ds_read_b128 v[106:109], v181 offset:64
	s_waitcnt lgkmcnt(14)
	v_mfma_f32_16x16x32_bf16 v[94:97], v[222:225], v[102:105], v[94:97]
	v_mfma_f32_16x16x32_bf16 v[190:193], v[190:193], v[102:105], v[198:201]
	v_mfma_f32_16x16x32_bf16 v[186:189], v[186:189], v[102:105], v[194:197]
	v_mfma_f32_16x16x32_bf16 v[194:197], v[214:217], v[102:105], v[202:205]
	v_mfma_f32_16x16x32_bf16 v[182:185], v[218:221], v[102:105], v[182:185]
	v_sub_f32_e32 v102, v228, v146
	v_mul_f32_e32 v102, 0x3fb8aa3b, v102
	v_exp_f32_e32 v198, v102
	v_sub_f32_e32 v102, v228, v227
	v_mul_f32_e32 v102, 0x3fb8aa3b, v102
	v_exp_f32_e32 v200, v102
	v_pk_mul_f32 v[102:103], v[198:199], v[190:191] op_sel_hi:[0,1]
	v_pk_mul_f32 v[190:191], v[198:199], v[194:195] op_sel_hi:[0,1]
	v_pk_mul_f32 v[194:195], v[198:199], v[94:95] op_sel_hi:[0,1]
	s_waitcnt lgkmcnt(1)
	v_fmamk_f32 v94, v146, 0xbfb8aa3b, v98
	v_fmamk_f32 v95, v146, 0xbfb8aa3b, v99
	s_waitcnt lgkmcnt(0)
	v_fmamk_f32 v98, v146, 0xbfb8aa3b, v106
	v_fmamk_f32 v99, v146, 0xbfb8aa3b, v107
	v_pk_mul_f32 v[104:105], v[198:199], v[192:193] op_sel_hi:[0,1]
	v_pk_mul_f32 v[192:193], v[198:199], v[196:197] op_sel_hi:[0,1]
	v_pk_mul_f32 v[196:197], v[198:199], v[96:97] op_sel_hi:[0,1]
	v_exp_f32_e32 v94, v94
	v_exp_f32_e32 v95, v95
	v_fmamk_f32 v96, v146, 0xbfb8aa3b, v100
	v_exp_f32_e32 v98, v98
	v_exp_f32_e32 v99, v99
	v_fmamk_f32 v100, v146, 0xbfb8aa3b, v108
	v_fmac_f32_e32 v101, 0xbfb8aa3b, v146
	v_exp_f32_e32 v100, v100
	v_fmac_f32_e32 v109, 0xbfb8aa3b, v146
	v_exp_f32_e32 v97, v101
	v_exp_f32_e32 v101, v109
	v_exp_f32_e32 v96, v96
	v_mul_f32_e32 v94, v114, v94
	v_mul_f32_e32 v95, v115, v95
	v_mul_f32_e32 v98, v110, v98
	v_mul_f32_e32 v99, v111, v99
	v_mul_f32_e32 v100, v112, v100
	v_cvt_pk_bf16_f32 v112, v94, v95
	v_cvt_pk_bf16_f32 v94, v98, s0
	v_cvt_pk_bf16_f32 v95, v99, s0
	v_mul_f32_e32 v101, v113, v101
	v_cndmask_b32_e64 v94, v94, 0, s[6:7]
	v_cndmask_b32_e64 v95, 0, v95, s[8:9]
	v_perm_b32 v114, v95, v94, s89
	v_cvt_pk_bf16_f32 v94, v100, s0
	v_cvt_pk_bf16_f32 v95, v101, s0
	v_pk_mul_f32 v[12:13], v[12:13], v[200:201] op_sel_hi:[1,0]
	v_pk_mul_f32 v[10:11], v[10:11], v[200:201] op_sel_hi:[1,0]
	v_pk_mul_f32 v[28:29], v[28:29], v[200:201] op_sel_hi:[1,0]
	v_pk_mul_f32 v[26:27], v[26:27], v[200:201] op_sel_hi:[1,0]
	v_pk_mul_f32 v[20:21], v[20:21], v[200:201] op_sel_hi:[1,0]
	v_pk_mul_f32 v[18:19], v[18:19], v[200:201] op_sel_hi:[1,0]
	v_pk_mul_f32 v[16:17], v[16:17], v[200:201] op_sel_hi:[1,0]
	v_pk_mul_f32 v[14:15], v[14:15], v[200:201] op_sel_hi:[1,0]
	v_pk_mul_f32 v[24:25], v[24:25], v[200:201] op_sel_hi:[1,0]
	v_pk_mul_f32 v[22:23], v[22:23], v[200:201] op_sel_hi:[1,0]
	v_mul_f32_e32 v96, v116, v96
	v_mul_f32_e32 v97, v117, v97
	v_cndmask_b32_e64 v94, v94, 0, s[10:11]
	v_cndmask_b32_e64 v95, v95, 0, s[12:13]
	v_pk_mul_f32 v[188:189], v[198:199], v[188:189] op_sel_hi:[0,1]
	v_pk_mul_f32 v[186:187], v[198:199], v[186:187] op_sel_hi:[0,1]
	v_pk_mul_f32 v[184:185], v[198:199], v[184:185] op_sel_hi:[0,1]
	v_pk_mul_f32 v[182:183], v[198:199], v[182:183] op_sel_hi:[0,1]
	v_cvt_pk_bf16_f32 v113, v96, v97
	v_perm_b32 v115, v95, v94, s89
	v_add3_u32 v94, s26, v168, v179
	ds_read_b64_tr_b16 v[198:199], v94
	ds_read_b64_tr_b16 v[202:203], v94 offset:32
	ds_read_b64_tr_b16 v[214:215], v94 offset:64
	ds_read_b64_tr_b16 v[218:219], v94 offset:96
	ds_read_b64_tr_b16 v[200:201], v94 offset:2560
	ds_read_b64_tr_b16 v[204:205], v94 offset:2592
	ds_read_b64_tr_b16 v[216:217], v94 offset:2624
	ds_read_b64_tr_b16 v[220:221], v94 offset:2656
	v_add3_u32 v96, s21, v169, v179
	ds_read_b64_tr_b16 v[94:95], v96 offset:32
	ds_read_b64_tr_b16 v[234:235], v96 offset:4640
	ds_read_b128 v[222:225], v181 offset:1664
	ds_read_b128 v[226:229], v181 offset:1728
	v_mfma_f32_16x16x32_bf16 v[108:111], v[122:125], v[112:115], v[102:105]
	v_and_b32_e32 v116, 0xffff0000, v232
	v_mul_f32_e32 v116, v211, v116
	v_and_b32_e32 v117, 0xffff0000, v233
	v_mfma_f32_16x16x32_bf16 v[96:99], v[118:121], v[112:115], v[186:189]
	v_mul_f32_e32 v117, v213, v117
	v_mfma_f32_16x16x32_bf16 v[104:107], v[126:129], v[112:115], v[190:193]
	v_mfma_f32_16x16x32_bf16 v[100:103], v[130:133], v[112:115], v[182:185]
	v_mfma_f32_16x16x32_bf16 v[112:115], v[6:9], v[112:115], v[194:197]
	s_nop 7
	v_lshlrev_b32_e32 v113, 16, v230
	v_and_b32_e32 v114, 0xffff0000, v230
	v_mul_f32_e32 v113, v206, v113
	v_mul_f32_e32 v114, v207, v114
	v_cvt_pk_bf16_f32 v114, v113, v114
	v_lshlrev_b32_e32 v113, 16, v231
	v_and_b32_e32 v115, 0xffff0000, v231
	v_mul_f32_e32 v113, v208, v113
	v_mul_f32_e32 v115, v209, v115
	v_cvt_pk_bf16_f32 v115, v113, v115
	v_lshlrev_b32_e32 v113, 16, v232
	v_mul_f32_e32 v113, v210, v113
	v_cvt_pk_bf16_f32 v116, v113, v116
	v_lshlrev_b32_e32 v113, 16, v233
	v_mul_f32_e32 v113, v212, v113
	v_cvt_pk_bf16_f32 v117, v113, v117
	s_nop 1
	v_mfma_f32_16x16x32_bf16 v[10:13], v[114:117], v[122:125], v[10:13]
	v_mfma_f32_16x16x32_bf16 v[26:29], v[114:117], v[118:121], v[26:29]
	v_mfma_f32_16x16x32_bf16 v[18:21], v[114:117], v[126:129], v[18:21]
	v_mfma_f32_16x16x32_bf16 v[14:17], v[114:117], v[130:133], v[14:17]
	v_mfma_f32_16x16x32_bf16 v[22:25], v[114:117], v[6:9], v[22:25]
	v_add3_u32 v113, s26, v170, v179
	ds_read_b64_tr_b16 v[114:115], v113
	ds_read_b64_tr_b16 v[118:119], v113 offset:32
	ds_read_b64_tr_b16 v[122:123], v113 offset:64
	ds_read_b64_tr_b16 v[126:127], v113 offset:96
	ds_read_b64_tr_b16 v[116:117], v113 offset:2560
	ds_read_b64_tr_b16 v[120:121], v113 offset:2592
	ds_read_b64_tr_b16 v[124:125], v113 offset:2624
	ds_read_b64_tr_b16 v[128:129], v113 offset:2656
	v_add3_u32 v113, s21, v171, v179
	ds_read_b64_tr_b16 v[210:211], v113 offset:32
	ds_read_b64_tr_b16 v[212:213], v113 offset:4640
	ds_read_b128 v[130:133], v181 offset:1792
	ds_read_b128 v[182:185], v181 offset:1856
	s_waitcnt lgkmcnt(14)
	v_lshlrev_b32_e32 v113, 16, v94
	v_and_b32_e32 v94, 0xffff0000, v94
	s_waitcnt lgkmcnt(13)
	v_mul_f32_e32 v113, v222, v113
	v_mul_f32_e32 v94, v223, v94
	v_cvt_pk_bf16_f32 v186, v113, v94
	v_lshlrev_b32_e32 v94, 16, v95
	v_and_b32_e32 v95, 0xffff0000, v95
	v_mul_f32_e32 v94, v224, v94
	v_mul_f32_e32 v95, v225, v95
	v_cvt_pk_bf16_f32 v187, v94, v95
	v_lshlrev_b32_e32 v94, 16, v234
	v_and_b32_e32 v95, 0xffff0000, v234
	s_waitcnt lgkmcnt(12)
	v_mul_f32_e32 v94, v226, v94
	v_mul_f32_e32 v95, v227, v95
	v_cvt_pk_bf16_f32 v188, v94, v95
	v_lshlrev_b32_e32 v94, 16, v235
	v_and_b32_e32 v95, 0xffff0000, v235
	v_mul_f32_e32 v94, v228, v94
	v_mul_f32_e32 v95, v229, v95
	v_cvt_pk_bf16_f32 v189, v94, v95
	s_nop 1
	v_mfma_f32_16x16x32_bf16 v[10:13], v[186:189], v[198:201], v[10:13]
	v_mfma_f32_16x16x32_bf16 v[26:29], v[186:189], v[202:205], v[26:29]
	v_mfma_f32_16x16x32_bf16 v[18:21], v[186:189], v[214:217], v[18:21]
	v_mfma_f32_16x16x32_bf16 v[14:17], v[186:189], v[218:221], v[14:17]
	v_mfma_f32_16x16x32_bf16 v[22:25], v[186:189], v[6:9], v[22:25]
	v_add3_u32 v94, s26, v172, v179
	ds_read_b64_tr_b16 v[186:187], v94
	ds_read_b64_tr_b16 v[190:191], v94 offset:32
	ds_read_b64_tr_b16 v[194:195], v94 offset:64
	ds_read_b64_tr_b16 v[198:199], v94 offset:96
	ds_read_b64_tr_b16 v[188:189], v94 offset:2560
	ds_read_b64_tr_b16 v[192:193], v94 offset:2592
	ds_read_b64_tr_b16 v[196:197], v94 offset:2624
	ds_read_b64_tr_b16 v[200:201], v94 offset:2656
	v_add3_u32 v113, s21, v173, v179
	ds_read_b64_tr_b16 v[94:95], v113 offset:32
	ds_read_b64_tr_b16 v[214:215], v113 offset:4640
	ds_read_b128 v[202:205], v181 offset:1920
	ds_read_b128 v[206:209], v181 offset:1984
	s_waitcnt lgkmcnt(14)
	v_lshlrev_b32_e32 v113, 16, v210
	s_waitcnt lgkmcnt(13)
	v_mul_f32_e32 v113, v130, v113
	v_and_b32_e32 v130, 0xffff0000, v210
	v_mul_f32_e32 v130, v131, v130
	v_cvt_pk_bf16_f32 v130, v113, v130
	v_lshlrev_b32_e32 v113, 16, v211
	v_and_b32_e32 v131, 0xffff0000, v211
	v_mul_f32_e32 v113, v132, v113
	v_mul_f32_e32 v131, v133, v131
	v_cvt_pk_bf16_f32 v131, v113, v131
	v_lshlrev_b32_e32 v113, 16, v212
	v_and_b32_e32 v132, 0xffff0000, v212
	s_waitcnt lgkmcnt(12)
	v_mul_f32_e32 v113, v182, v113
	v_mul_f32_e32 v132, v183, v132
	v_cvt_pk_bf16_f32 v132, v113, v132
	v_lshlrev_b32_e32 v113, 16, v213
	v_and_b32_e32 v133, 0xffff0000, v213
	v_mul_f32_e32 v113, v184, v113
	v_mul_f32_e32 v133, v185, v133
	v_cvt_pk_bf16_f32 v133, v113, v133
	s_nop 1
	v_mfma_f32_16x16x32_bf16 v[10:13], v[130:133], v[114:117], v[10:13]
	v_mfma_f32_16x16x32_bf16 v[26:29], v[130:133], v[118:121], v[26:29]
	v_mfma_f32_16x16x32_bf16 v[18:21], v[130:133], v[122:125], v[18:21]
	v_mfma_f32_16x16x32_bf16 v[14:17], v[130:133], v[126:129], v[14:17]
	v_mfma_f32_16x16x32_bf16 v[22:25], v[130:133], v[6:9], v[22:25]
	s_waitcnt lgkmcnt(3)
	v_lshlrev_b32_e32 v113, 16, v94
	v_and_b32_e32 v94, 0xffff0000, v94
	s_waitcnt lgkmcnt(1)
	v_mul_f32_e32 v113, v202, v113
	v_mul_f32_e32 v94, v203, v94
	v_cvt_pk_bf16_f32 v114, v113, v94
	v_lshlrev_b32_e32 v94, 16, v95
	v_and_b32_e32 v95, 0xffff0000, v95
	v_mul_f32_e32 v94, v204, v94
	v_mul_f32_e32 v95, v205, v95
	v_cvt_pk_bf16_f32 v115, v94, v95
	v_lshlrev_b32_e32 v94, 16, v214
	v_and_b32_e32 v95, 0xffff0000, v214
	s_waitcnt lgkmcnt(0)
	v_mul_f32_e32 v94, v206, v94
	v_mul_f32_e32 v95, v207, v95
	v_cvt_pk_bf16_f32 v116, v94, v95
	v_lshlrev_b32_e32 v94, 16, v215
	v_and_b32_e32 v95, 0xffff0000, v215
	v_mul_f32_e32 v94, v208, v94
	v_mul_f32_e32 v95, v209, v95
	v_cvt_pk_bf16_f32 v117, v94, v95
	s_nop 1
	v_mfma_f32_16x16x32_bf16 v[10:13], v[114:117], v[186:189], v[10:13]
	v_mfma_f32_16x16x32_bf16 v[26:29], v[114:117], v[190:193], v[26:29]
	v_mfma_f32_16x16x32_bf16 v[18:21], v[114:117], v[194:197], v[18:21]
	v_mfma_f32_16x16x32_bf16 v[14:17], v[114:117], v[198:201], v[14:17]
	v_mfma_f32_16x16x32_bf16 v[22:25], v[114:117], v[6:9], v[22:25]
	s_xor_b32 s19, s20, 1
	s_mulk_i32 s19, 0x4a00
	s_add_i32 s19, s19, 0
	v_lshlrev_b32_e32 v95, 1, v2
	v_add3_u32 v114, s19, v3, v95
	ds_bpermute_b32 v94, v174, v112
	v_cvt_pk_bf16_f32 v112, v10, v11
	v_cvt_pk_bf16_f32 v113, v12, v13
	v_add_u32_e32 v115, 0x1c020, v114
	ds_write_b64 v115, v[112:113]
	v_add_u32_e32 v115, s19, v177
	s_mov_b32 s20, 0x1c020
	v_cvt_pk_bf16_f32 v112, v26, v27
	v_cvt_pk_bf16_f32 v113, v28, v29
	v_add3_u32 v95, v115, v95, s20
	ds_write_b64 v95, v[112:113]
	v_cvt_pk_bf16_f32 v112, v18, v19
	v_cvt_pk_bf16_f32 v113, v20, v21
	v_add_u32_e32 v95, 0x1e420, v114
	ds_write_b64 v95, v[112:113]
	v_cvt_pk_bf16_f32 v112, v14, v15
	v_cvt_pk_bf16_f32 v113, v16, v17
	v_add_u32_e32 v95, 0x1f620, v114
	ds_write_b64 v95, v[112:113]
	s_and_saveexec_b64 s[20:21], s[2:3]
	s_cbranch_execz .LBB0_383
	v_lshl_add_u32 v95, v2, 1, s19
	v_cvt_pk_bf16_f32 v112, v22, v23
	v_cvt_pk_bf16_f32 v113, v24, v25
	v_add_u32_e32 v95, 0x20820, v95
	ds_write_b64 v95, v[112:113]
	s_branch .LBB0_383

.LBB0_392:
	s_add_i32 s1, s78, 0xffffff80
	v_or_b32_e32 v2, s1, v151
	v_xad_u32 v3, v2, -1, s78
	v_cndmask_b32_e64 v2, v3, v2, s[4:5]
	v_ashrrev_i32_e32 v3, 31, v2
	v_lshl_add_u64 v[2:3], s[16:17], 0, v[2:3]
	v_lshlrev_b64 v[2:3], 11, v[2:3]
	v_lshl_add_u64 v[2:3], s[42:43], 0, v[2:3]
	v_lshl_add_u64 v[2:3], v[2:3], 0, s[68:69]
	s_mov_b32 s19, s69
	v_lshl_add_u64 v[2:3], v[2:3], 0, s[18:19]
	v_lshl_add_u64 v[2:3], v[134:135], 1, v[2:3]
	s_and_b64 vcc, exec, s[46:47]
	global_store_dwordx4 v[2:3], v[94:97], off sc1
	global_store_dwordx4 v[2:3], v[98:101], off offset:64 sc1
	s_cbranch_vccz .LBB0_396
	s_waitcnt vmcnt(18)
	v_mbcnt_lo_u32_b32 v34, -1, 0
	v_mbcnt_hi_u32_b32 v34, -1, v34
	s_ashr_i32 s1, s0, 31
	v_lshlrev_b32_e32 v3, 1, v34
	v_ashrrev_i32_e32 v2, 2, v34
	v_and_b32_e32 v3, 24, v3
	v_and_b32_e32 v4, 3, v34
	s_lshl_b64 s[2:3], s[0:1], 16
	v_and_b32_e32 v2, -4, v2
	v_or3_b32 v3, v4, v3, s25
	s_add_u32 s2, s76, s2
	v_lshlrev_b32_e32 v4, 2, v3
	v_ashrrev_i32_e32 v3, 31, v2
	s_addc_u32 s3, s77, s3
	v_lshlrev_b64 v[6:7], 9, v[2:3]
	v_lshl_add_u64 v[6:7], s[2:3], 0, v[6:7]
	v_lshl_add_u64 v[6:7], v[6:7], 0, v[4:5]
	s_mov_b64 s[2:3], 0x2000
	v_lshl_add_u64 v[8:9], v[6:7], 0, s[2:3]
	s_movk_i32 s2, 0x2000
	v_add_co_u32_e32 v30, vcc, s2, v6
	s_mov_b64 s[2:3], 0x2200
	s_nop 0
	v_addc_co_u32_e32 v31, vcc, 0, v7, vcc
	v_lshl_add_u64 v[32:33], v[6:7], 0, s[2:3]
	s_mov_b64 s[2:3], 0x2400
	v_and_or_b32 v4, v34, 15, s31
	global_store_dword v[30:31], v10, off
	global_store_dword v[30:31], v11, off offset:512
	v_lshl_add_u64 v[10:11], v[6:7], 0, s[2:3]
	s_mov_b64 s[2:3], 0x2600
	v_cmp_eq_u32_e32 vcc, 0, v4
	global_store_dword v[30:31], v12, off offset:1024
	v_lshl_add_u64 v[6:7], v[6:7], 0, s[2:3]
	global_store_dword v[30:31], v13, off offset:1536
	global_store_dword v[8:9], v26, off offset:16
	global_store_dword v[32:33], v27, off offset:16
	global_store_dword v[10:11], v28, off offset:16
	global_store_dword v[6:7], v29, off offset:16
	global_store_dword v[8:9], v18, off offset:128
	global_store_dword v[32:33], v19, off offset:128
	global_store_dword v[10:11], v20, off offset:128
	global_store_dword v[6:7], v21, off offset:128
	global_store_dword v[8:9], v14, off offset:144
	global_store_dword v[32:33], v15, off offset:144
	global_store_dword v[10:11], v16, off offset:144
	global_store_dword v[6:7], v17, off offset:144
	s_and_saveexec_b64 s[2:3], vcc
	s_cbranch_execz .LBB0_395
	s_lshl_b64 s[0:1], s[0:1], 9
	v_readlane_b32 s4, v254, 26
	s_add_u32 s0, s4, s0
	v_readlane_b32 s4, v254, 27
	s_addc_u32 s1, s4, s1
	v_lshl_add_u64 v[2:3], v[2:3], 2, s[0:1]
	global_store_dwordx4 v[2:3], v[22:25], off offset:64 sc1

.LBB0_403:
	s_min_u32 s49, s93, 1
	s_lshl_b32 s36, s49, 7
	s_and_b32 s49, s93, 1
	s_mul_i32 s37, s49, 0x9000
	s_add_i32 s95, s37, 0
	s_mul_i32 s37, s49, 0x5000
	s_add_i32 s97, s37, 0
	s_lshl_b32 s37, s49, 11
	s_add_i32 s82, s37, 0
	s_lshl_b32 s37, s49, 4
	s_add_i32 s37, s37, 0
	s_mov_b32 s45, s93
	s_add_i32 s97, s97, 0x12000
	s_add_i32 s82, s82, 0x25a00
	s_add_i32 s37, s37, 0x26a00
	s_add_i32 s93, s93, 1
	v_add3_u32 v98, s95, v122, v175
	s_cmp_lt_u32 s93, s79
	s_waitcnt vmcnt(17)
	ds_write_b128 v98, v[30:33]
	s_waitcnt vmcnt(16)
	ds_write_b128 v98, v[34:37] offset:4608
	s_waitcnt vmcnt(15)
	ds_write_b128 v98, v[38:41] offset:9216
	s_waitcnt vmcnt(14)
	ds_write_b128 v98, v[42:45] offset:13824
	s_waitcnt vmcnt(13)
	ds_write_b128 v98, v[50:53] offset:18432
	s_waitcnt vmcnt(12)
	ds_write_b128 v98, v[54:57] offset:23040
	s_waitcnt vmcnt(11)
	ds_write_b128 v98, v[58:61] offset:27648
	s_waitcnt vmcnt(10)
	ds_write_b128 v98, v[62:65] offset:32256
	v_lshl_add_u32 v30, v152, 1, s97
	s_cselect_b64 s[70:71], -1, 0
	v_add3_u32 v30, v30, v123, v176
	s_and_b64 vcc, s[70:71], exec
	v_add_u32_e32 v31, 0x1000, v30
	s_cselect_b32 s38, s93, s45
	s_waitcnt vmcnt(9)
	ds_write2_b64 v30, v[70:71], v[72:73] offset1:4
	s_waitcnt vmcnt(8)
	ds_write2_b64 v31, v[66:67], v[68:69] offset0:128 offset1:132
	v_add_u32_e32 v31, 0x2800, v30
	v_add_u32_e32 v30, 0x3800, v30
	s_lshl_b32 s83, s38, 7
	s_waitcnt vmcnt(4)
	ds_write2_b64 v30, v[90:91], v[92:93] offset0:128 offset1:132
	v_add_u32_e32 v30, s83, v137
	ds_write2_b64 v31, v[78:79], v[80:81] offset1:4
	v_sub_u32_e32 v31, s57, v30
	v_cndmask_b32_e64 v30, v31, v30, s[2:3]
	v_ashrrev_i32_e32 v31, 31, v30
	v_lshlrev_b64 v[30:31], 2, v[30:31]
	v_lshl_add_u64 v[32:33], s[64:65], 0, v[30:31]
	s_waitcnt lgkmcnt(0)
	s_barrier
	v_lshl_add_u64 v[30:31], s[66:67], 0, v[30:31]
	global_load_dwordx2 v[132:133], v[32:33], off
	global_load_dwordx2 v[134:135], v[30:31], off
	v_lshl_add_u32 v31, v136, 2, s82
	v_lshlrev_b32_e32 v90, 1, v120
	v_mov_b32_e32 v30, s82
	ds_read2st64_b32 v[130:131], v31 offset0:2 offset1:4
	v_mov_b32_e32 v31, s37
	v_add3_u32 v32, s95, v90, v151
	ds_read_b32 v119, v30 offset:1020
	ds_read_b32 v240, v31
	ds_read_b128 v[30:33], v32
	v_mov_b64_e32 v[80:81], v[76:77]
	s_waitcnt vmcnt(4)
	v_mov_b64_e32 v[100:101], v[88:89]
	v_subrev_u32_e32 v117, s36, v179
	v_add_u32_e32 v241, s36, v150
	s_mul_i32 s36, s49, 0x4a00
	v_mov_b64_e32 v[78:79], v[74:75]
	v_mov_b64_e32 v[114:115], v[84:85]
	v_mov_b64_e32 v[98:99], v[86:87]
	s_add_i32 s36, s36, 0
	v_mov_b64_e32 v[112:113], v[82:83]
	s_add_i32 s36, s36, 0x1c000
	v_add3_u32 v58, s95, v151, v90
	ds_read_b128 v[38:41], v58 offset:64
	v_or_b32_e32 v91, s83, v149
	v_bitop3_b32 v35, s83, v156, v149 bitop3:0x36
	s_waitcnt lgkmcnt(1)
	v_mfma_f32_16x16x32_bf16 v[42:45], v[30:33], v[46:49], 0
	v_xad_u32 v30, v91, -1, s78
	v_or_b32_e32 v34, 16, v91
	v_add_u32_e32 v35, s78, v35
	v_cndmask_b32_e64 v30, v30, v91, s[2:3]
	v_cndmask_b32_e64 v34, v35, v34, s[2:3]
	v_add_u32_e32 v30, s48, v30
	v_add_u32_e32 v34, s48, v34
	v_mad_i64_i32 v[30:31], vcc, v30, s86, v[128:129]
	v_mad_i64_i32 v[34:35], vcc, v34, s86, v[128:129]
	global_load_dwordx4 v[30:33], v[30:31], off offset:2048
	s_nop 0
	global_load_dwordx4 v[34:37], v[34:35], off offset:2048
	ds_read_b128 v[50:53], v58 offset:128
	s_waitcnt lgkmcnt(1)
	v_mfma_f32_16x16x32_bf16 v[54:57], v[38:41], v[78:81], v[42:45]
	v_bitop3_b32 v39, s83, v157, v149 bitop3:0x36
	v_or_b32_e32 v38, 32, v91
	v_add_u32_e32 v39, s78, v39
	v_bitop3_b32 v43, s83, v158, v149 bitop3:0x36
	v_or_b32_e32 v42, 48, v91
	v_add_u32_e32 v43, s78, v43
	v_cndmask_b32_e64 v38, v39, v38, s[2:3]
	v_cndmask_b32_e64 v42, v43, v42, s[2:3]
	v_add_u32_e32 v38, s48, v38
	v_add_u32_e32 v42, s48, v42
	v_mad_i64_i32 v[38:39], vcc, v38, s86, v[128:129]
	v_mad_i64_i32 v[42:43], vcc, v42, s86, v[128:129]
	global_load_dwordx4 v[38:41], v[38:39], off offset:2048
	s_nop 0
	global_load_dwordx4 v[42:45], v[42:43], off offset:2048
	ds_read_b128 v[58:61], v58 offset:192
	s_waitcnt lgkmcnt(1)
	v_mfma_f32_16x16x32_bf16 v[62:65], v[50:53], v[112:115], v[54:57]
	v_bitop3_b32 v51, s83, v159, v149 bitop3:0x36
	v_or_b32_e32 v50, 64, v91
	v_add_u32_e32 v51, s78, v51
	v_bitop3_b32 v55, s83, v160, v149 bitop3:0x36
	v_or_b32_e32 v54, 0x50, v91
	v_add_u32_e32 v55, s78, v55
	v_cndmask_b32_e64 v50, v51, v50, s[2:3]
	v_cndmask_b32_e64 v54, v55, v54, s[2:3]
	v_add_u32_e32 v50, s48, v50
	v_add_u32_e32 v54, s48, v54
	v_mad_i64_i32 v[50:51], vcc, v50, s86, v[128:129]
	v_mad_i64_i32 v[54:55], vcc, v54, s86, v[128:129]
	global_load_dwordx4 v[50:53], v[50:51], off offset:2048
	s_nop 0
	global_load_dwordx4 v[54:57], v[54:55], off offset:2048
	v_add3_u32 v86, s36, v90, v151
	ds_read_b128 v[66:69], v86
	ds_read_b128 v[70:73], v86 offset:4608
	ds_read_b128 v[74:77], v86 offset:9216
	ds_read_b128 v[82:85], v86 offset:13824
	ds_read_b128 v[86:89], v86 offset:18432
	s_waitcnt lgkmcnt(5)
	v_mfma_f32_16x16x32_bf16 v[102:105], v[58:61], v[98:101], v[62:65]
	v_bitop3_b32 v59, s83, v161, v149 bitop3:0x36
	v_or_b32_e32 v58, 0x60, v91
	v_add_u32_e32 v59, s78, v59
	v_bitop3_b32 v63, s83, v162, v149 bitop3:0x36
	v_or_b32_e32 v62, 0x70, v91
	v_add_u32_e32 v63, s78, v63
	v_cndmask_b32_e64 v58, v59, v58, s[2:3]
	v_cndmask_b32_e64 v62, v63, v62, s[2:3]
	v_add_u32_e32 v58, s48, v58
	v_add_u32_e32 v62, s48, v62
	v_mad_i64_i32 v[58:59], vcc, v58, s86, v[128:129]
	v_mad_i64_i32 v[62:63], vcc, v62, s86, v[128:129]
	global_load_dwordx4 v[58:61], v[58:59], off offset:2048
	s_nop 0
	global_load_dwordx4 v[62:65], v[62:63], off offset:2048
	v_add3_u32 v236, s36, v151, v90
	ds_read_b128 v[90:93], v236 offset:64
	ds_read_b128 v[180:183], v236 offset:4672
	ds_read_b128 v[184:187], v236 offset:9280
	ds_read_b128 v[188:191], v236 offset:13888
	ds_read_b128 v[192:195], v236 offset:18496
	v_or_b32_e32 v230, s83, v148
	s_waitcnt lgkmcnt(9)
	v_mfma_f32_16x16x32_bf16 v[196:199], v[66:69], v[46:49], 0
	v_xad_u32 v66, v230, -1, s78
	v_cndmask_b32_e64 v66, v66, v230, s[2:3]
	v_add_u32_e32 v66, s48, v66
	v_mov_b64_e32 v[106:107], s[40:41]
	v_mad_i64_i32 v[66:67], vcc, v66, s86, v[106:107]
	s_waitcnt lgkmcnt(8)
	v_mfma_f32_16x16x32_bf16 v[200:203], v[70:73], v[46:49], 0
	v_lshl_add_u64 v[66:67], v[66:67], 0, s[68:69]
	s_mov_b32 s45, s69
	v_lshl_add_u64 v[66:67], v[66:67], 0, s[44:45]
	s_waitcnt lgkmcnt(7)
	v_mfma_f32_16x16x32_bf16 v[204:207], v[74:77], v[46:49], 0
	v_lshl_add_u64 v[66:67], v[66:67], 0, v[4:5]
	s_waitcnt lgkmcnt(6)
	v_mfma_f32_16x16x32_bf16 v[82:85], v[82:85], v[46:49], 0
	s_waitcnt lgkmcnt(5)
	v_mfma_f32_16x16x32_bf16 v[86:89], v[86:89], v[46:49], 0
	v_bitop3_b32 v49, s83, v157, v148 bitop3:0x36
	v_or_b32_e32 v48, 32, v230
	v_add_u32_e32 v49, s78, v49
	v_cndmask_b32_e64 v48, v49, v48, s[2:3]
	v_add_co_u32_e32 v46, vcc, s84, v66
	v_add_u32_e32 v48, s48, v48
	s_nop 0
	v_addc_co_u32_e32 v47, vcc, 0, v67, vcc
	v_mad_i64_i32 v[48:49], vcc, v48, s86, v[106:107]
	v_lshl_add_u64 v[48:49], v[48:49], 0, s[68:69]
	v_lshl_add_u64 v[48:49], v[48:49], 0, s[44:45]
	v_lshl_add_u64 v[48:49], v[48:49], 0, v[4:5]
	v_add_co_u32_e32 v48, vcc, s84, v48
	s_nop 1
	v_addc_co_u32_e32 v49, vcc, 0, v49, vcc
	global_load_dwordx4 v[70:73], v[46:47], off
	global_load_dwordx4 v[66:69], v[48:49], off
	v_or_b32_e32 v46, s83, v136
	v_xad_u32 v47, v46, -1, s78
	v_cndmask_b32_e64 v46, v47, v46, s[2:3]
	v_add_u32_e32 v46, s48, v46
	v_mad_i64_i32 v[228:229], vcc, v46, s86, v[124:125]
	global_load_dwordx4 v[46:49], v[228:229], off
	global_load_dwordx4 v[74:77], v[228:229], off offset:64
	ds_read_b128 v[208:211], v236 offset:128
	ds_read_b128 v[212:215], v236 offset:4736
	ds_read_b128 v[216:219], v236 offset:9344
	ds_read_b128 v[220:223], v236 offset:13952
	ds_read_b128 v[224:227], v236 offset:18560
	s_waitcnt lgkmcnt(9)
	v_mfma_f32_16x16x32_bf16 v[196:199], v[90:93], v[78:81], v[196:199]
	s_waitcnt lgkmcnt(8)
	v_mfma_f32_16x16x32_bf16 v[180:183], v[180:183], v[78:81], v[200:203]
	s_waitcnt lgkmcnt(7)
	v_mfma_f32_16x16x32_bf16 v[184:187], v[184:187], v[78:81], v[204:207]
	s_waitcnt lgkmcnt(6)
	v_mfma_f32_16x16x32_bf16 v[188:191], v[188:191], v[78:81], v[82:85]
	s_waitcnt lgkmcnt(5)
	v_mfma_f32_16x16x32_bf16 v[192:195], v[192:195], v[78:81], v[86:89]
	v_bitop3_b32 v79, s83, v159, v148 bitop3:0x36
	v_or_b32_e32 v78, 64, v230
	v_add_u32_e32 v79, s78, v79
	v_cndmask_b32_e64 v78, v79, v78, s[2:3]
	v_add_u32_e32 v78, s48, v78
	v_mad_i64_i32 v[78:79], vcc, v78, s86, v[106:107]
	v_lshl_add_u64 v[78:79], v[78:79], 0, s[68:69]
	v_bitop3_b32 v83, s83, v161, v148 bitop3:0x36
	v_lshl_add_u64 v[78:79], v[78:79], 0, s[44:45]
	v_or_b32_e32 v82, 0x60, v230
	v_add_u32_e32 v83, s78, v83
	v_lshl_add_u64 v[78:79], v[78:79], 0, v[4:5]
	v_cndmask_b32_e64 v82, v83, v82, s[2:3]
	v_add_co_u32_e32 v78, vcc, s84, v78
	v_add_u32_e32 v82, s48, v82
	s_nop 0
	v_addc_co_u32_e32 v79, vcc, 0, v79, vcc
	v_mad_i64_i32 v[82:83], vcc, v82, s86, v[106:107]
	v_lshl_add_u64 v[82:83], v[82:83], 0, s[68:69]
	v_lshl_add_u64 v[82:83], v[82:83], 0, s[44:45]
	v_lshl_add_u64 v[82:83], v[82:83], 0, v[4:5]
	v_add_co_u32_e32 v82, vcc, s84, v82
	global_load_dwordx4 v[78:81], v[78:79], off
	s_nop 0
	v_addc_co_u32_e32 v83, vcc, 0, v83, vcc
	global_load_dwordx4 v[90:93], v[82:83], off
	s_nop 0
	global_load_dwordx4 v[82:85], v[228:229], off offset:128
	global_load_dwordx4 v[86:89], v[228:229], off offset:192
	ds_read_b128 v[200:203], v236 offset:192
	ds_read_b128 v[204:207], v236 offset:4800
	ds_read_b128 v[228:231], v236 offset:9408
	ds_read_b128 v[232:235], v236 offset:14016
	ds_read_b128 v[236:239], v236 offset:18624
	v_cndmask_b32_e64 v106, v241, v117, s[2:3]
	v_ashrrev_i32_e32 v107, 31, v106
	v_lshl_add_u64 v[106:107], s[0:1], 0, v[106:107]
	v_lshlrev_b64 v[106:107], 11, v[106:107]
	v_lshl_add_u64 v[106:107], v[126:127], 0, v[106:107]
	global_store_dwordx4 v[106:107], v[108:111], off sc1
	global_store_dwordx4 v[106:107], v[94:97], off offset:64 sc1
	s_waitcnt lgkmcnt(9)
	v_mfma_f32_16x16x32_bf16 v[196:199], v[208:211], v[112:115], v[196:199]
	s_waitcnt lgkmcnt(5)
	v_mfma_f32_16x16x32_bf16 v[94:97], v[224:227], v[112:115], v[192:195]
	v_mfma_f32_16x16x32_bf16 v[180:183], v[212:215], v[112:115], v[180:183]
	v_mfma_f32_16x16x32_bf16 v[184:187], v[216:219], v[112:115], v[184:187]
	v_mfma_f32_16x16x32_bf16 v[188:191], v[220:223], v[112:115], v[188:191]
	v_add3_u32 v106, s97, v153, v154
	ds_read_b64_tr_b16 v[112:113], v106
	ds_read_b64_tr_b16 v[192:193], v106 offset:32
	ds_read_b64_tr_b16 v[208:209], v106 offset:64
	ds_read_b64_tr_b16 v[212:213], v106 offset:96
	ds_read_b64_tr_b16 v[114:115], v106 offset:2560
	ds_read_b64_tr_b16 v[194:195], v106 offset:2592
	ds_read_b64_tr_b16 v[210:211], v106 offset:2624
	ds_read_b64_tr_b16 v[214:215], v106 offset:2656
	v_add3_u32 v106, s95, v155, v178
	v_lshl_add_u32 v117, v2, 2, s82
	ds_read_b64_tr_b16 v[244:245], v106
	ds_read_b64_tr_b16 v[246:247], v106 offset:4608
	ds_read_b128 v[216:219], v117 offset:1600
	ds_read_b128 v[220:223], v117 offset:1536
	ds_read_b128 v[106:109], v117
	s_waitcnt lgkmcnt(13)
	v_mfma_f32_16x16x32_bf16 v[94:97], v[236:239], v[98:101], v[94:97]
	v_mfma_f32_16x16x32_bf16 v[196:199], v[200:203], v[98:101], v[196:199]
	v_mfma_f32_16x16x32_bf16 v[180:183], v[204:207], v[98:101], v[180:183]
	v_mfma_f32_16x16x32_bf16 v[184:187], v[228:231], v[98:101], v[184:187]
	v_mfma_f32_16x16x32_bf16 v[188:191], v[232:235], v[98:101], v[188:191]
	v_sub_f32_e32 v98, v240, v130
	v_mul_f32_e32 v98, 0x3fb8aa3b, v98
	v_exp_f32_e32 v110, v98
	v_sub_f32_e32 v98, v240, v119
	v_mul_f32_e32 v98, 0x3fb8aa3b, v98
	v_exp_f32_e32 v200, v98
	v_pk_mul_f32 v[98:99], v[110:111], v[196:197] op_sel_hi:[0,1]
	v_pk_mul_f32 v[196:197], v[110:111], v[94:95] op_sel_hi:[0,1]
	s_waitcnt lgkmcnt(0)
	v_fmamk_f32 v94, v130, 0xbfb8aa3b, v106
	v_fmamk_f32 v95, v130, 0xbfb8aa3b, v107
	v_exp_f32_e32 v94, v94
	v_exp_f32_e32 v95, v95
	v_pk_mul_f32 v[100:101], v[110:111], v[198:199] op_sel_hi:[0,1]
	v_pk_mul_f32 v[198:199], v[110:111], v[96:97] op_sel_hi:[0,1]
	v_fmamk_f32 v96, v130, 0xbfb8aa3b, v108
	v_fmac_f32_e32 v109, 0xbfb8aa3b, v130
	v_exp_f32_e32 v96, v96
	v_exp_f32_e32 v97, v109
	v_mul_f32_e32 v94, v102, v94
	v_mul_f32_e32 v95, v103, v95
	v_cvt_pk_bf16_f32 v94, v94, s0
	v_cvt_pk_bf16_f32 v95, v95, s0
	v_mul_f32_e32 v96, v104, v96
	v_mul_f32_e32 v97, v105, v97
	v_cndmask_b32_e64 v94, v94, 0, s[20:21]
	v_cndmask_b32_e64 v95, 0, v95, s[22:23]
	v_pk_mul_f32 v[20:21], v[20:21], v[200:201] op_sel_hi:[1,0]
	v_pk_mul_f32 v[18:19], v[18:19], v[200:201] op_sel_hi:[1,0]
	v_pk_mul_f32 v[24:25], v[24:25], v[200:201] op_sel_hi:[1,0]
	v_pk_mul_f32 v[22:23], v[22:23], v[200:201] op_sel_hi:[1,0]
	v_pk_mul_f32 v[16:17], v[16:17], v[200:201] op_sel_hi:[1,0]
	v_pk_mul_f32 v[14:15], v[14:15], v[200:201] op_sel_hi:[1,0]
	v_pk_mul_f32 v[12:13], v[12:13], v[200:201] op_sel_hi:[1,0]
	v_pk_mul_f32 v[10:11], v[10:11], v[200:201] op_sel_hi:[1,0]
	v_pk_mul_f32 v[8:9], v[8:9], v[200:201] op_sel_hi:[1,0]
	v_pk_mul_f32 v[6:7], v[6:7], v[200:201] op_sel_hi:[1,0]
	v_perm_b32 v200, v95, v94, s89
	v_cvt_pk_bf16_f32 v94, v96, s0
	v_cvt_pk_bf16_f32 v95, v97, s0
	v_cndmask_b32_e64 v94, v94, 0, s[24:25]
	v_cndmask_b32_e64 v95, v95, 0, s[26:27]
	v_pk_mul_f32 v[182:183], v[110:111], v[182:183] op_sel_hi:[0,1]
	v_pk_mul_f32 v[180:181], v[110:111], v[180:181] op_sel_hi:[0,1]
	v_pk_mul_f32 v[186:187], v[110:111], v[186:187] op_sel_hi:[0,1]
	v_pk_mul_f32 v[184:185], v[110:111], v[184:185] op_sel_hi:[0,1]
	v_pk_mul_f32 v[190:191], v[110:111], v[190:191] op_sel_hi:[0,1]
	v_pk_mul_f32 v[188:189], v[110:111], v[188:189] op_sel_hi:[0,1]
	v_perm_b32 v201, v95, v94, s89
	v_mov_b32_e32 v202, v5
	v_mov_b32_e32 v203, v5
	v_add3_u32 v94, s97, v168, v178
	ds_read_b64_tr_b16 v[204:205], v94
	ds_read_b64_tr_b16 v[224:225], v94 offset:32
	ds_read_b64_tr_b16 v[228:229], v94 offset:64
	ds_read_b64_tr_b16 v[232:233], v94 offset:96
	ds_read_b64_tr_b16 v[206:207], v94 offset:2560
	ds_read_b64_tr_b16 v[226:227], v94 offset:2592
	ds_read_b64_tr_b16 v[230:231], v94 offset:2624
	ds_read_b64_tr_b16 v[234:235], v94 offset:2656
	v_add3_u32 v96, s95, v169, v178
	ds_read_b64_tr_b16 v[94:95], v96
	ds_read_b64_tr_b16 v[248:249], v96 offset:4608
	ds_read_b128 v[236:239], v117 offset:1664
	ds_read_b128 v[240:243], v117 offset:1728
	v_lshlrev_b32_e32 v119, 16, v244
	v_and_b32_e32 v130, 0xffff0000, v244
	v_mfma_f32_16x16x32_bf16 v[104:107], v[192:195], v[200:203], v[180:183]
	v_mul_f32_e32 v119, v220, v119
	v_mul_f32_e32 v130, v221, v130
	v_mfma_f32_16x16x32_bf16 v[180:183], v[26:29], v[200:203], v[196:199]
	v_mfma_f32_16x16x32_bf16 v[108:111], v[112:115], v[200:203], v[98:101]
	v_mfma_f32_16x16x32_bf16 v[100:103], v[208:211], v[200:203], v[184:187]
	s_nop 5
	v_cvt_pk_bf16_f32 v182, v119, v130
	v_lshlrev_b32_e32 v119, 16, v245
	v_and_b32_e32 v130, 0xffff0000, v245
	v_mul_f32_e32 v119, v222, v119
	v_mul_f32_e32 v130, v223, v130
	v_cvt_pk_bf16_f32 v183, v119, v130
	v_lshlrev_b32_e32 v119, 16, v246
	v_and_b32_e32 v130, 0xffff0000, v246
	v_mul_f32_e32 v119, v216, v119
	v_mul_f32_e32 v130, v217, v130
	v_cvt_pk_bf16_f32 v184, v119, v130
	v_lshlrev_b32_e32 v119, 16, v247
	v_and_b32_e32 v130, 0xffff0000, v247
	v_mul_f32_e32 v119, v218, v119
	v_mul_f32_e32 v130, v219, v130
	v_cvt_pk_bf16_f32 v185, v119, v130
	v_mfma_f32_16x16x32_bf16 v[96:99], v[212:215], v[200:203], v[188:191]
	s_nop 0
	v_mfma_f32_16x16x32_bf16 v[18:21], v[182:185], v[112:115], v[18:21]
	v_mfma_f32_16x16x32_bf16 v[22:25], v[182:185], v[192:195], v[22:25]
	v_mfma_f32_16x16x32_bf16 v[14:17], v[182:185], v[208:211], v[14:17]
	v_mfma_f32_16x16x32_bf16 v[10:13], v[182:185], v[212:215], v[10:13]
	v_mfma_f32_16x16x32_bf16 v[6:9], v[182:185], v[26:29], v[6:9]
	v_add3_u32 v119, s97, v170, v178
	ds_read_b64_tr_b16 v[112:113], v119
	ds_read_b64_tr_b16 v[182:183], v119 offset:32
	ds_read_b64_tr_b16 v[186:187], v119 offset:64
	ds_read_b64_tr_b16 v[190:191], v119 offset:96
	ds_read_b64_tr_b16 v[114:115], v119 offset:2560
	ds_read_b64_tr_b16 v[184:185], v119 offset:2592
	ds_read_b64_tr_b16 v[188:189], v119 offset:2624
	ds_read_b64_tr_b16 v[192:193], v119 offset:2656
	v_add3_u32 v119, s95, v171, v178
	ds_read_b64_tr_b16 v[244:245], v119
	ds_read_b64_tr_b16 v[246:247], v119 offset:4608
	ds_read_b128 v[194:197], v117 offset:1792
	ds_read_b128 v[198:201], v117 offset:1856
	s_waitcnt lgkmcnt(14)
	v_lshlrev_b32_e32 v119, 16, v94
	v_and_b32_e32 v94, 0xffff0000, v94
	s_waitcnt lgkmcnt(13)
	v_mul_f32_e32 v119, v236, v119
	v_mul_f32_e32 v94, v237, v94
	v_cvt_pk_bf16_f32 v208, v119, v94
	v_lshlrev_b32_e32 v94, 16, v95
	v_and_b32_e32 v95, 0xffff0000, v95
	v_mul_f32_e32 v94, v238, v94
	v_mul_f32_e32 v95, v239, v95
	v_cvt_pk_bf16_f32 v209, v94, v95
	v_lshlrev_b32_e32 v94, 16, v248
	v_and_b32_e32 v95, 0xffff0000, v248
	s_waitcnt lgkmcnt(12)
	v_mul_f32_e32 v94, v240, v94
	v_mul_f32_e32 v95, v241, v95
	v_cvt_pk_bf16_f32 v210, v94, v95
	v_lshlrev_b32_e32 v94, 16, v249
	v_and_b32_e32 v95, 0xffff0000, v249
	v_mul_f32_e32 v94, v242, v94
	v_mul_f32_e32 v95, v243, v95
	v_cvt_pk_bf16_f32 v211, v94, v95
	s_nop 1
	v_mfma_f32_16x16x32_bf16 v[18:21], v[208:211], v[204:207], v[18:21]
	v_mfma_f32_16x16x32_bf16 v[22:25], v[208:211], v[224:227], v[22:25]
	v_mfma_f32_16x16x32_bf16 v[14:17], v[208:211], v[228:231], v[14:17]
	v_mfma_f32_16x16x32_bf16 v[10:13], v[208:211], v[232:235], v[10:13]
	v_mfma_f32_16x16x32_bf16 v[6:9], v[208:211], v[26:29], v[6:9]
	v_add3_u32 v94, s97, v172, v178
	ds_read_b64_tr_b16 v[202:203], v94
	ds_read_b64_tr_b16 v[206:207], v94 offset:32
	ds_read_b64_tr_b16 v[210:211], v94 offset:64
	ds_read_b64_tr_b16 v[214:215], v94 offset:96
	ds_read_b64_tr_b16 v[204:205], v94 offset:2560
	ds_read_b64_tr_b16 v[208:209], v94 offset:2592
	ds_read_b64_tr_b16 v[212:213], v94 offset:2624
	ds_read_b64_tr_b16 v[216:217], v94 offset:2656
	v_add3_u32 v119, s95, v173, v178
	ds_read_b64_tr_b16 v[94:95], v119
	ds_read_b64_tr_b16 v[226:227], v119 offset:4608
	ds_read_b128 v[218:221], v117 offset:1920
	ds_read_b128 v[222:225], v117 offset:1984
	s_waitcnt lgkmcnt(14)
	v_lshlrev_b32_e32 v117, 16, v244
	v_and_b32_e32 v119, 0xffff0000, v244
	s_waitcnt lgkmcnt(13)
	v_mul_f32_e32 v117, v194, v117
	v_mul_f32_e32 v119, v195, v119
	v_cvt_pk_bf16_f32 v194, v117, v119
	v_lshlrev_b32_e32 v117, 16, v245
	v_and_b32_e32 v119, 0xffff0000, v245
	v_mul_f32_e32 v117, v196, v117
	v_mul_f32_e32 v119, v197, v119
	v_cvt_pk_bf16_f32 v195, v117, v119
	v_lshlrev_b32_e32 v117, 16, v246
	v_and_b32_e32 v119, 0xffff0000, v246
	s_waitcnt lgkmcnt(12)
	v_mul_f32_e32 v117, v198, v117
	v_mul_f32_e32 v119, v199, v119
	v_cvt_pk_bf16_f32 v196, v117, v119
	v_lshlrev_b32_e32 v117, 16, v247
	v_and_b32_e32 v119, 0xffff0000, v247
	v_mul_f32_e32 v117, v200, v117
	v_mul_f32_e32 v119, v201, v119
	v_cvt_pk_bf16_f32 v197, v117, v119
	s_nop 1
	v_mfma_f32_16x16x32_bf16 v[18:21], v[194:197], v[112:115], v[18:21]
	v_mfma_f32_16x16x32_bf16 v[22:25], v[194:197], v[182:185], v[22:25]
	v_mfma_f32_16x16x32_bf16 v[14:17], v[194:197], v[186:189], v[14:17]
	v_mfma_f32_16x16x32_bf16 v[10:13], v[194:197], v[190:193], v[10:13]
	v_mfma_f32_16x16x32_bf16 v[6:9], v[194:197], v[26:29], v[6:9]
	s_waitcnt lgkmcnt(3)
	v_lshlrev_b32_e32 v112, 16, v94
	v_and_b32_e32 v94, 0xffff0000, v94
	s_waitcnt lgkmcnt(1)
	v_mul_f32_e32 v112, v218, v112
	v_mul_f32_e32 v94, v219, v94
	v_cvt_pk_bf16_f32 v112, v112, v94
	v_lshlrev_b32_e32 v94, 16, v95
	v_and_b32_e32 v95, 0xffff0000, v95
	v_mul_f32_e32 v94, v220, v94
	v_mul_f32_e32 v95, v221, v95
	v_cvt_pk_bf16_f32 v113, v94, v95
	v_lshlrev_b32_e32 v94, 16, v226
	v_and_b32_e32 v95, 0xffff0000, v226
	s_waitcnt lgkmcnt(0)
	v_mul_f32_e32 v94, v222, v94
	v_mul_f32_e32 v95, v223, v95
	v_cvt_pk_bf16_f32 v114, v94, v95
	v_lshlrev_b32_e32 v94, 16, v227
	v_and_b32_e32 v95, 0xffff0000, v227
	v_mul_f32_e32 v94, v224, v94
	v_mul_f32_e32 v95, v225, v95
	v_cvt_pk_bf16_f32 v115, v94, v95
	s_nop 1
	v_mfma_f32_16x16x32_bf16 v[18:21], v[112:115], v[202:205], v[18:21]
	v_mfma_f32_16x16x32_bf16 v[22:25], v[112:115], v[206:209], v[22:25]
	v_mfma_f32_16x16x32_bf16 v[14:17], v[112:115], v[210:213], v[14:17]
	v_mfma_f32_16x16x32_bf16 v[10:13], v[112:115], v[214:217], v[10:13]
	v_mfma_f32_16x16x32_bf16 v[6:9], v[112:115], v[26:29], v[6:9]
	ds_bpermute_b32 v94, v174, v180
	s_xor_b32 s45, s49, 1
	s_mul_i32 s36, s45, 0x4a00
	v_add_u32_e32 v95, s36, v177
	v_cvt_pk_bf16_f32 v112, v18, v19
	v_cvt_pk_bf16_f32 v113, v20, v21
	v_add_u32_e32 v117, v95, v151
	v_cvt_pk_bf16_f32 v114, v22, v23
	v_cvt_pk_bf16_f32 v115, v24, v25
	ds_write2st64_b64 v117, v[112:113], v[114:115] offset1:9
	v_cvt_pk_bf16_f32 v112, v14, v15
	v_cvt_pk_bf16_f32 v113, v16, v17
	v_cvt_pk_bf16_f32 v114, v10, v11
	v_cvt_pk_bf16_f32 v115, v12, v13
	ds_write2st64_b64 v117, v[112:113], v[114:115] offset0:18 offset1:27
	s_and_saveexec_b64 vcc, s[18:19]
	v_cvt_pk_bf16_f32 v112, v6, v7
	v_cvt_pk_bf16_f32 v113, v8, v9
	ds_write_b64 v95, v[112:113] offset:18432
	s_or_b64 exec, exec, vcc
	s_andn2_b64 vcc, exec, s[70:71]
	s_cbranch_vccnz .LBB0_409
	s_waitcnt vmcnt(18)
	v_cndmask_b32_e64 v95, v135, v134, s[2:3]
	v_add_f32_e32 v95, v3, v95
	v_mul_f32_e64 v112, |v95|, s88
	v_exp_f32_e32 v117, v112
	v_min_f32_e32 v112, 0, v95
	v_cndmask_b32_e64 v113, v134, v135, s[2:3]
	v_add_f32_e32 v113, v3, v113
	v_add_f32_e32 v95, 1.0, v117
	v_add_f32_e32 v114, -1.0, v95
	v_sub_f32_e32 v115, v114, v95
	v_sub_f32_e32 v114, v117, v114
	v_add_f32_e32 v115, 1.0, v115
	v_add_f32_e32 v119, v114, v115
	v_mul_f32_e64 v114, |v113|, s88
	v_exp_f32_e32 v204, v114
	v_cvt_f64_f32_e32 v[114:115], v95
	v_frexp_exp_i32_f64_e32 v134, v[114:115]
	v_frexp_mant_f32_e32 v130, v95
	v_add_f32_e32 v135, 1.0, v204
	v_add_f32_e32 v114, -1.0, v135
	v_sub_f32_e32 v115, v114, v135
	v_add_f32_e32 v115, 1.0, v115
	v_sub_f32_e32 v114, v204, v114
	v_add_f32_e32 v180, v114, v115
	v_frexp_mant_f32_e32 v181, v135
	v_cvt_f64_f32_e32 v[114:115], v135
	v_frexp_exp_i32_f64_e32 v114, v[114:115]
	v_cmp_gt_f32_e32 vcc, s80, v181
	v_min_f32_e32 v113, 0, v113
	s_nop 0
	v_subbrev_co_u32_e32 v196, vcc, 0, v114, vcc
	v_cmp_gt_f32_e32 vcc, s80, v130
	s_nop 1
	v_subbrev_co_u32_e32 v130, vcc, 0, v134, vcc
	v_sub_u32_e32 v115, 0, v130
	v_ldexp_f32 v114, v95, v115
	v_sub_u32_e32 v95, 0, v196
	v_ldexp_f32 v134, v119, v115
	v_ldexp_f32 v115, v135, v95
	v_ldexp_f32 v135, v180, v95
	v_pk_add_f32 v[180:181], v[114:115], 1.0 op_sel_hi:[1,0]
	v_pk_add_f32 v[188:189], v[114:115], -1.0 op_sel_hi:[1,0]
	v_pk_add_f32 v[182:183], v[180:181], -1.0 op_sel_hi:[1,0]
	v_pk_add_f32 v[190:191], v[188:189], 1.0 op_sel_hi:[1,0]
	v_pk_add_f32 v[182:183], v[114:115], v[182:183] neg_lo:[0,1] neg_hi:[0,1]
	v_pk_add_f32 v[114:115], v[114:115], v[190:191] neg_lo:[0,1] neg_hi:[0,1]
	v_pk_add_f32 v[182:183], v[134:135], v[182:183]
	v_pk_add_f32 v[114:115], v[134:135], v[114:115]
	v_pk_add_f32 v[184:185], v[180:181], v[182:183]
	v_pk_add_f32 v[134:135], v[188:189], v[114:115]
	v_rcp_f32_e32 v186, v184
	v_rcp_f32_e32 v187, v185
	v_pk_add_f32 v[180:181], v[184:185], v[180:181] neg_lo:[0,1] neg_hi:[0,1]
	v_pk_add_f32 v[188:189], v[134:135], v[188:189] neg_lo:[0,1] neg_hi:[0,1]
	v_pk_add_f32 v[180:181], v[182:183], v[180:181] neg_lo:[0,1] neg_hi:[0,1]
	v_pk_mul_f32 v[182:183], v[134:135], v[186:187]
	v_pk_add_f32 v[114:115], v[114:115], v[188:189] neg_lo:[0,1] neg_hi:[0,1]
	v_pk_mul_f32 v[188:189], v[184:185], v[182:183]
	v_cmp_neq_f32_e32 vcc, s81, v117
	v_pk_fma_f32 v[190:191], v[182:183], v[184:185], v[188:189] neg_lo:[0,0,1] neg_hi:[0,0,1]
	s_nop 0
	v_pk_fma_f32 v[190:191], v[182:183], v[180:181], v[190:191]
	s_nop 0
	v_pk_add_f32 v[192:193], v[188:189], v[190:191]
	s_nop 0
	v_pk_add_f32 v[194:195], v[134:135], v[192:193] neg_lo:[0,1] neg_hi:[0,1]
	v_pk_add_f32 v[188:189], v[192:193], v[188:189] neg_lo:[0,1] neg_hi:[0,1]
	v_pk_add_f32 v[134:135], v[134:135], v[194:195] neg_lo:[0,1] neg_hi:[0,1]
	s_nop 0
	v_pk_add_f32 v[134:135], v[134:135], v[192:193] neg_lo:[0,1] neg_hi:[0,1]
	s_nop 0
	v_pk_add_f32 v[114:115], v[114:115], v[134:135]
	v_pk_add_f32 v[134:135], v[188:189], v[190:191] neg_lo:[0,1] neg_hi:[0,1]
	s_nop 0
	v_pk_add_f32 v[114:115], v[134:135], v[114:115]
	s_nop 0
	v_pk_add_f32 v[134:135], v[194:195], v[114:115]
	s_nop 0
	v_pk_mul_f32 v[188:189], v[186:187], v[134:135]
	s_nop 0
	v_pk_mul_f32 v[190:191], v[184:185], v[188:189]
	s_nop 0
	v_pk_fma_f32 v[184:185], v[188:189], v[184:185], v[190:191] neg_lo:[0,0,1] neg_hi:[0,0,1]
	s_nop 0
	v_pk_fma_f32 v[180:181], v[188:189], v[180:181], v[184:185]
	v_pk_add_f32 v[184:185], v[194:195], v[134:135] neg_lo:[0,1] neg_hi:[0,1]
	s_nop 0
	v_pk_add_f32 v[114:115], v[114:115], v[184:185]
	v_pk_add_f32 v[184:185], v[190:191], v[180:181]
	s_nop 0
	v_pk_add_f32 v[192:193], v[134:135], v[184:185] neg_lo:[0,1] neg_hi:[0,1]
	v_pk_add_f32 v[190:191], v[184:185], v[190:191] neg_lo:[0,1] neg_hi:[0,1]
	v_pk_add_f32 v[134:135], v[134:135], v[192:193] neg_lo:[0,1] neg_hi:[0,1]
	s_nop 0
	v_pk_add_f32 v[134:135], v[134:135], v[184:185] neg_lo:[0,1] neg_hi:[0,1]
	s_nop 0
	v_pk_add_f32 v[114:115], v[114:115], v[134:135]
	v_pk_add_f32 v[134:135], v[190:191], v[180:181] neg_lo:[0,1] neg_hi:[0,1]
	s_nop 0
	v_pk_add_f32 v[114:115], v[134:135], v[114:115]
	v_pk_add_f32 v[134:135], v[182:183], v[188:189]
	v_pk_add_f32 v[114:115], v[192:193], v[114:115]
	v_pk_add_f32 v[180:181], v[134:135], v[182:183] neg_lo:[0,1] neg_hi:[0,1]
	v_pk_mul_f32 v[114:115], v[186:187], v[114:115]
	v_pk_add_f32 v[180:181], v[188:189], v[180:181] neg_lo:[0,1] neg_hi:[0,1]
	v_cvt_f32_i32_e32 v183, v196
	v_pk_add_f32 v[114:115], v[180:181], v[114:115]
	v_cvt_f32_i32_e32 v182, v130
	v_pk_add_f32 v[180:181], v[134:135], v[114:115]
	v_pk_mul_f32 v[188:189], v[182:183], s[94:95] op_sel_hi:[1,0]
	v_pk_mul_f32 v[184:185], v[180:181], v[180:181]
	v_pk_add_f32 v[134:135], v[180:181], v[134:135] neg_lo:[0,1] neg_hi:[0,1]
	v_pk_fma_f32 v[186:187], v[184:185], s[90:91], v[138:139] op_sel_hi:[1,0,0]
	v_pk_add_f32 v[114:115], v[114:115], v[134:135] neg_lo:[0,1] neg_hi:[0,1]
	v_ldexp_f32 v134, v180, 1
	v_pk_fma_f32 v[186:187], v[184:185], v[186:187], s[92:93] op_sel_hi:[1,1,0]
	v_ldexp_f32 v135, v181, 1
	v_pk_mul_f32 v[180:181], v[180:181], v[184:185]
	v_ldexp_f32 v193, v115, 1
	v_pk_mul_f32 v[180:181], v[180:181], v[186:187]
	v_ldexp_f32 v114, v114, 1
	v_pk_add_f32 v[184:185], v[134:135], v[180:181]
	v_mov_b32_e32 v115, v193
	v_pk_add_f32 v[134:135], v[184:185], v[134:135] neg_lo:[0,1] neg_hi:[0,1]
	v_pk_fma_f32 v[190:191], v[182:183], s[94:95], v[188:189] op_sel_hi:[1,0,1] neg_lo:[0,0,1] neg_hi:[0,0,1]
	v_pk_add_f32 v[134:135], v[180:181], v[134:135] neg_lo:[0,1] neg_hi:[0,1]
	v_pk_fma_f32 v[182:183], v[182:183], s[96:97], v[190:191] op_sel_hi:[1,0,1]
	v_pk_add_f32 v[186:187], v[114:115], v[134:135]
	v_mov_b32_e32 v181, v135
	v_mov_b32_e32 v115, v187
	v_mov_b32_e32 v135, v185
	v_pk_add_f32 v[190:191], v[188:189], v[182:183]
	v_mov_b32_e32 v180, v188
	v_mov_b32_e32 v192, v182
	v_pk_add_f32 v[114:115], v[114:115], v[134:135]
	v_pk_add_f32 v[134:135], v[184:185], v[186:187]
	v_pk_add_f32 v[180:181], v[180:181], v[192:193]
	v_mov_b32_e32 v192, v190
	v_mov_b32_e32 v193, v189
	v_mov_b32_e32 v194, v134
	v_mov_b32_e32 v195, v183
	v_mov_b32_e32 v198, v190
	v_mov_b32_e32 v199, v185
	v_mov_b32_e32 v200, v134
	v_mov_b32_e32 v201, v187
	v_pk_add_f32 v[196:197], v[192:193], v[194:195]
	v_pk_add_f32 v[198:199], v[198:199], v[200:201]
	v_pk_add_f32 v[200:201], v[190:191], v[134:135]
	v_pk_add_f32 v[192:193], v[196:197], v[192:193] neg_lo:[0,1] neg_hi:[0,1]
	v_mov_b32_e32 v196, v134
	v_mov_b32_e32 v197, v201
	v_mov_b32_e32 v202, v184
	v_mov_b32_e32 v203, v191
	v_pk_add_f32 v[196:197], v[196:197], v[202:203] neg_lo:[0,1] neg_hi:[0,1]
	v_mov_b32_e32 v202, v190
	v_mov_b32_e32 v203, v201
	v_mov_b32_e32 v189, v197
	v_pk_add_f32 v[188:189], v[202:203], v[188:189] neg_lo:[0,1] neg_hi:[0,1]
	v_pk_add_f32 v[194:195], v[194:195], v[192:193] neg_lo:[0,1] neg_hi:[0,1]
	v_mov_b32_e32 v202, v188
	v_mov_b32_e32 v203, v193
	v_mov_b32_e32 v193, v185
	v_pk_add_f32 v[202:203], v[182:183], v[202:203] neg_lo:[0,1] neg_hi:[0,1]
	v_pk_add_f32 v[192:193], v[198:199], v[192:193] neg_lo:[0,1] neg_hi:[0,1]
	v_mov_b32_e32 v183, v191
	v_pk_add_f32 v[180:181], v[180:181], v[192:193] neg_lo:[0,1] neg_hi:[0,1]
	v_pk_add_f32 v[182:183], v[182:183], v[188:189] neg_lo:[0,1] neg_hi:[0,1]
	v_pk_add_f32 v[114:115], v[114:115], v[196:197] neg_lo:[0,1] neg_hi:[0,1]
	v_pk_add_f32 v[134:135], v[134:135], v[184:185] neg_lo:[0,1] neg_hi:[0,1]
	v_pk_add_f32 v[184:185], v[114:115], v[182:183]
	v_mov_b32_e32 v115, v181
	v_pk_add_f32 v[134:135], v[186:187], v[134:135] neg_lo:[0,1] neg_hi:[0,1]
	v_pk_add_f32 v[186:187], v[194:195], v[180:181]
	v_pk_add_f32 v[114:115], v[202:203], v[114:115]
	v_mov_b32_e32 v183, v195
	v_pk_add_f32 v[114:115], v[114:115], v[182:183] neg_lo:[0,1] neg_hi:[0,1]
	v_mov_b32_e32 v180, v184
	v_mov_b32_e32 v181, v187
	v_pk_add_f32 v[180:181], v[180:181], v[114:115] neg_lo:[0,1] neg_hi:[0,1]
	v_pk_add_f32 v[114:115], v[134:135], v[114:115] neg_lo:[0,1] neg_hi:[0,1]
	v_pk_add_f32 v[180:181], v[182:183], v[180:181] neg_lo:[0,1] neg_hi:[0,1]
	v_pk_add_f32 v[134:135], v[186:187], v[184:185]
	v_pk_add_f32 v[114:115], v[114:115], v[180:181]
	v_pk_add_f32 v[180:181], v[200:201], v[134:135]
	s_nop 0
	v_pk_add_f32 v[182:183], v[180:181], v[200:201] neg_lo:[0,1] neg_hi:[0,1]
	s_nop 0
	v_pk_add_f32 v[134:135], v[134:135], v[182:183] neg_lo:[0,1] neg_hi:[0,1]
	s_nop 0
	v_pk_add_f32 v[114:115], v[114:115], v[134:135]
	s_nop 0
	v_pk_add_f32 v[114:115], v[180:181], v[114:115]
	s_nop 0
	v_cndmask_b32_e32 v95, v164, v114, vcc
	v_cmp_neq_f32_e32 vcc, s81, v204
	s_nop 1
	v_cndmask_b32_e32 v114, v164, v115, vcc
	v_cmp_ngt_f32_e32 vcc, -1.0, v204
	s_nop 1
	v_cndmask_b32_e32 v114, v165, v114, vcc
	v_cmp_ngt_f32_e32 vcc, -1.0, v117
	s_nop 1
	v_cndmask_b32_e32 v95, v165, v95, vcc
	v_cmp_neq_f32_e32 vcc, -1.0, v117
	s_nop 1
	v_cndmask_b32_e32 v95, v166, v95, vcc
	v_cmp_neq_f32_e32 vcc, -1.0, v204
	s_nop 1
	v_cndmask_b32_e32 v114, v166, v114, vcc
	v_cmp_lt_f32_e64 vcc, |v204|, s28
	s_nop 1
	v_cndmask_b32_e32 v115, v114, v204, vcc
	v_cmp_lt_f32_e64 vcc, |v117|, s28
	s_nop 1
	v_cndmask_b32_e32 v114, v95, v117, vcc
	v_pk_add_f32 v[112:113], v[112:113], v[114:115] neg_lo:[0,1] neg_hi:[0,1]
	v_cndmask_b32_e64 v117, v132, v133, s[2:3]
	v_add_f32_e32 v95, v112, v113
	ds_bpermute_b32 v113, v140, v95
	v_add_f32_e32 v119, v116, v117
	v_mov_b32_e32 v117, v112
	s_waitcnt lgkmcnt(0)
	v_add_f32_e32 v113, v95, v113
	v_cndmask_b32_e64 v113, v113, v95, s[4:5]
	ds_bpermute_b32 v114, v141, v113
	s_waitcnt lgkmcnt(0)
	v_add_f32_e32 v114, v113, v114
	v_cndmask_b32_e64 v113, v114, v113, s[6:7]
	ds_bpermute_b32 v114, v142, v113
	s_waitcnt lgkmcnt(0)
	v_add_f32_e32 v114, v113, v114
	v_cndmask_b32_e64 v113, v114, v113, s[8:9]
	ds_bpermute_b32 v114, v143, v113
	s_waitcnt lgkmcnt(0)
	v_add_f32_e32 v114, v113, v114
	v_cndmask_b32_e64 v113, v114, v113, s[10:11]
	ds_bpermute_b32 v114, v144, v113
	s_waitcnt lgkmcnt(0)
	v_add_f32_e32 v114, v113, v114
	v_cndmask_b32_e64 v113, v114, v113, s[12:13]
	ds_bpermute_b32 v115, v145, v113
	v_cndmask_b32_e64 v114, v133, v132, s[2:3]
	s_waitcnt lgkmcnt(0)
	v_add_f32_e32 v115, v113, v115
	v_cndmask_b32_e64 v113, v115, v113, s[14:15]
	v_sub_f32_e32 v115, v113, v95
	v_pk_add_f32 v[114:115], v[116:117], v[114:115]
	v_sub_f32_e32 v112, v119, v113
	v_sub_f32_e32 v95, v114, v115
	v_max_f32_e32 v114, v95, v112
	ds_bpermute_b32 v117, v140, v114
	v_mul_f32_e32 v134, 0x3fb8aa3b, v95
	v_mul_f32_e32 v135, 0x3fb8aa3b, v112
	s_waitcnt lgkmcnt(0)
	v_max_f32_e32 v117, v117, v117
	v_max_f32_e32 v117, v114, v117
	v_cndmask_b32_e64 v114, v117, v114, s[4:5]
	ds_bpermute_b32 v117, v141, v114
	s_waitcnt lgkmcnt(0)
	v_max_f32_e32 v117, v117, v117
	v_max_f32_e32 v117, v114, v117
	v_cndmask_b32_e64 v114, v117, v114, s[6:7]
	ds_bpermute_b32 v117, v142, v114
	s_waitcnt lgkmcnt(0)
	v_max_f32_e32 v117, v117, v117
	v_max_f32_e32 v117, v114, v117
	v_cndmask_b32_e64 v114, v117, v114, s[8:9]
	ds_bpermute_b32 v117, v143, v114
	s_waitcnt lgkmcnt(0)
	v_max_f32_e32 v117, v117, v117
	v_max_f32_e32 v117, v114, v117
	v_cndmask_b32_e64 v114, v117, v114, s[10:11]
	ds_bpermute_b32 v117, v144, v114
	s_waitcnt lgkmcnt(0)
	v_max_f32_e32 v117, v117, v117
	v_max_f32_e32 v117, v114, v117
	v_cndmask_b32_e64 v114, v117, v114, s[12:13]
	ds_bpermute_b32 v117, v145, v114
	v_max_f32_e32 v119, v114, v114
	s_waitcnt lgkmcnt(0)
	v_max_f32_e32 v117, v117, v117
	v_max_f32_e32 v117, v119, v117
	v_cndmask_b32_e64 v114, v117, v114, s[14:15]
	ds_bpermute_b32 v117, v140, v114
	v_max_f32_e32 v114, v114, v114
	v_lshl_add_u32 v119, s45, 11, v147
	s_waitcnt lgkmcnt(0)
	v_cndmask_b32_e64 v117, v117, v166, s[16:17]
	v_max3_f32 v132, v118, v117, v95
	v_max_f32_e32 v117, v118, v118
	v_max_f32_e32 v133, v117, v114
	ds_bpermute_b32 v114, v146, v133
	ds_bpermute_b32 v117, v146, v113
	ds_write2st64_b64 v119, v[134:135], v[132:133] offset1:1
	s_waitcnt lgkmcnt(2)
	v_sub_f32_e32 v95, v95, v114
	v_mul_f32_e32 v95, 0x3fb8aa3b, v95
	v_exp_f32_e32 v180, v95
	v_sub_f32_e32 v95, v112, v114
	v_mul_f32_e32 v95, 0x3fb8aa3b, v95
	v_exp_f32_e32 v181, v95
	v_mov_b32_e32 v112, v115
	v_pk_add_f32 v[112:113], v[112:113], v[132:133]
	ds_write2st64_b64 v119, v[112:113], v[180:181] offset0:2 offset1:3
	s_waitcnt lgkmcnt(2)
	v_add_f32_e32 v119, v114, v117
	s_and_saveexec_b64 s[70:71], s[16:17]
	s_lshl_b32 s36, s45, 4
	s_add_i32 s36, s36, 0
	s_add_i32 s36, s36, 0x26a00
	v_mov_b32_e32 v95, s36
	ds_write_b64 v95, v[118:119]
	s_or_b64 exec, exec, s[70:71]
	s_branch .LBB0_410

.LBB0_412:
	s_add_i32 s4, s78, 0xffffff80
	v_or_b32_e32 v2, s4, v136
	v_xad_u32 v3, v2, -1, s78
	v_cndmask_b32_e64 v2, v3, v2, s[2:3]
	v_ashrrev_i32_e32 v3, 31, v2
	v_lshl_add_u64 v[2:3], s[0:1], 0, v[2:3]
	v_lshlrev_b64 v[2:3], 11, v[2:3]
	v_lshl_add_u64 v[2:3], s[42:43], 0, v[2:3]
	v_lshl_add_u64 v[2:3], v[2:3], 0, s[68:69]
	s_mov_b32 s45, s69
	v_lshl_add_u64 v[2:3], v[2:3], 0, s[44:45]
	v_lshl_add_u64 v[2:3], v[120:121], 1, v[2:3]
	s_and_b64 vcc, exec, s[46:47]
	s_movk_i32 s22, 0xa0
	global_store_dwordx4 v[2:3], v[108:111], off sc1
	global_store_dwordx4 v[2:3], v[94:97], off offset:64 sc1
	s_cbranch_vccz .LBB0_274
	v_mbcnt_lo_u32_b32 v26, -1, 0
	v_mbcnt_hi_u32_b32 v26, -1, v26
	s_ashr_i32 s57, s56, 31
	v_ashrrev_i32_e32 v27, 2, v26
	v_lshlrev_b32_e32 v3, 1, v26
	s_lshl_b64 s[0:1], s[56:57], 16
	v_and_b32_e32 v2, -4, v27
	v_and_b32_e32 v4, 24, v3
	s_waitcnt vmcnt(19)
	v_and_b32_e32 v30, 3, v26
	s_add_u32 s0, s76, s0
	v_ashrrev_i32_e32 v3, 31, v2
	v_or3_b32 v4, v30, v4, s87
	v_or_b32_e32 v30, 1, v2
	s_addc_u32 s1, s77, s1
	v_lshlrev_b64 v[28:29], 9, v[2:3]
	v_ashrrev_i32_e32 v31, 31, v30
	v_lshl_add_u64 v[28:29], s[0:1], 0, v[28:29]
	v_lshlrev_b32_e32 v4, 2, v4
	v_lshlrev_b64 v[30:31], 9, v[30:31]
	v_lshl_add_u64 v[28:29], v[28:29], 0, v[4:5]
	v_lshl_add_u64 v[30:31], s[0:1], 0, v[30:31]
	global_store_dword v[28:29], v18, off
	v_lshl_add_u64 v[30:31], v[30:31], 0, v[4:5]
	v_or_b32_e32 v18, 2, v2
	global_store_dword v[30:31], v19, off
	v_ashrrev_i32_e32 v19, 31, v18
	v_lshlrev_b64 v[18:19], 9, v[18:19]
	v_lshl_add_u64 v[18:19], s[0:1], 0, v[18:19]
	v_lshl_add_u64 v[32:33], v[18:19], 0, v[4:5]
	v_or_b32_e32 v18, 3, v27
	v_ashrrev_i32_e32 v19, 31, v18
	s_waitcnt vmcnt(20)
	v_lshlrev_b64 v[34:35], 9, v[18:19]
	v_lshl_add_u64 v[34:35], s[0:1], 0, v[34:35]
	v_lshl_add_u64 v[34:35], v[34:35], 0, v[4:5]
	s_cmp_lg_u32 s31, 0
	global_store_dword v[32:33], v20, off
	global_store_dword v[34:35], v21, off
	global_store_dword v[28:29], v22, off offset:16
	global_store_dword v[30:31], v23, off offset:16
	global_store_dword v[32:33], v24, off offset:16
	global_store_dword v[34:35], v25, off offset:16
	global_store_dword v[28:29], v14, off offset:128
	global_store_dword v[30:31], v15, off offset:128
	global_store_dword v[32:33], v16, off offset:128
	global_store_dword v[34:35], v17, off offset:128
	global_store_dword v[28:29], v10, off offset:144
	global_store_dword v[30:31], v11, off offset:144
	global_store_dword v[32:33], v12, off offset:144
	global_store_dword v[34:35], v13, off offset:144
	s_cbranch_scc1 .LBB0_274
	v_and_b32_e32 v4, 15, v26
	v_cmp_eq_u32_e32 vcc, 0, v4
	s_and_saveexec_b64 s[0:1], vcc
	s_cbranch_execz .LBB0_416
	s_lshl_b64 s[2:3], s[56:57], 9
	v_readlane_b32 s4, v254, 26
	s_add_u32 s2, s4, s2
	v_readlane_b32 s4, v254, 27
	s_addc_u32 s3, s4, s3
	v_lshl_add_u64 v[2:3], v[2:3], 2, s[2:3]
	v_lshl_add_u64 v[10:11], v[18:19], 2, s[2:3]
	global_store_dwordx3 v[2:3], v[6:8], off
	global_store_dword v[10:11], v9, off

.LBB0_423:
	s_min_u32 s18, s20, 1
	s_lshl_b32 s26, s18, 7
	s_and_b32 s18, s20, 1
	s_mov_b32 s19, s20
	s_mul_i32 s20, s18, 0x5000
	s_add_i32 s25, s20, 0
	s_lshl_b32 s20, s18, 11
	s_add_i32 s20, s20, 0
	s_add_i32 s36, s20, 0x25a00
	s_lshl_b32 s20, s18, 4
	s_add_i32 s20, s20, 0
	s_add_i32 s25, s25, 0x12000
	s_add_i32 s37, s20, 0x26a00
	s_add_i32 s20, s19, 1
	s_waitcnt vmcnt(4)
	v_mov_b64_e32 v[56:57], v[16:17]
	s_mul_i32 s27, s18, 0x9000
	s_cmp_lt_u32 s20, s79
	v_mov_b64_e32 v[54:55], v[14:15]
	s_cselect_b32 s38, s20, s19
	v_lshl_add_u32 v15, v94, 2, s36
	s_add_i32 s19, s27, 0
	v_lshlrev_b32_e32 v172, 1, v2
	v_add_u32_e32 v15, 64, v15
	v_add_u32_e32 v70, s19, v172
	s_waitcnt vmcnt(3)
	v_mov_b64_e32 v[60:61], v[20:21]
	s_waitcnt vmcnt(2)
	v_mov_b64_e32 v[112:113], v[24:25]
	s_waitcnt lgkmcnt(0)
	s_barrier
	v_mov_b32_e32 v14, s36
	ds_read2st64_b32 v[88:89], v15 offset0:3 offset1:5
	v_mov_b32_e32 v15, s37
	v_add_u32_e32 v66, v70, v4
	v_mov_b64_e32 v[58:59], v[18:19]
	v_mov_b64_e32 v[110:111], v[22:23]
	ds_read_b32 v204, v14 offset:1020
	ds_read_b32 v205, v15
	ds_read_b128 v[14:17], v66
	ds_read_b128 v[18:21], v66 offset:4608
	ds_read_b128 v[22:25], v66 offset:9216
	ds_read_b128 v[62:65], v66 offset:13824
	ds_read_b128 v[66:69], v66 offset:18432
	v_add_u32_e32 v70, v70, v105
	ds_read_b128 v[70:73], v70
	v_subrev_u32_e32 v109, s26, v108
	v_add_u32_e32 v188, s26, v106
	s_mul_i32 s26, s18, 0x4a00
	s_add_i32 s26, s26, 0
	s_add_i32 s26, s26, 0x1c000
	v_add3_u32 v152, s19, v4, v172
	ds_read_b128 v[74:77], v152 offset:64
	ds_read_b128 v[78:81], v152 offset:4672
	ds_read_b128 v[90:93], v152 offset:9280
	ds_read_b128 v[114:117], v152 offset:13888
	v_add3_u32 v153, s19, v105, v172
	ds_read_b128 v[118:121], v152 offset:18496
	ds_read_b128 v[122:125], v153 offset:64
	s_waitcnt lgkmcnt(11)
	v_mfma_f32_16x16x32_bf16 v[14:17], v[14:17], v[10:13], 0
	s_waitcnt lgkmcnt(10)
	v_mfma_f32_16x16x32_bf16 v[18:21], v[18:21], v[10:13], 0
	s_waitcnt lgkmcnt(9)
	v_mfma_f32_16x16x32_bf16 v[22:25], v[22:25], v[10:13], 0
	s_waitcnt lgkmcnt(8)
	v_mfma_f32_16x16x32_bf16 v[62:65], v[62:65], v[10:13], 0
	s_waitcnt lgkmcnt(7)
	v_mfma_f32_16x16x32_bf16 v[66:69], v[66:69], v[10:13], 0
	s_waitcnt lgkmcnt(6)
	v_mfma_f32_16x16x32_bf16 v[70:73], v[70:73], v[10:13], 0
	ds_read_b128 v[126:129], v152 offset:128
	ds_read_b128 v[130:133], v152 offset:4736
	ds_read_b128 v[134:137], v152 offset:9344
	ds_read_b128 v[140:143], v152 offset:13952
	ds_read_b128 v[144:147], v152 offset:18560
	ds_read_b128 v[148:151], v153 offset:128
	s_waitcnt lgkmcnt(11)
	v_mfma_f32_16x16x32_bf16 v[14:17], v[74:77], v[54:57], v[14:17]
	s_waitcnt lgkmcnt(10)
	v_mfma_f32_16x16x32_bf16 v[18:21], v[78:81], v[54:57], v[18:21]
	s_waitcnt lgkmcnt(9)
	v_mfma_f32_16x16x32_bf16 v[22:25], v[90:93], v[54:57], v[22:25]
	s_waitcnt lgkmcnt(8)
	v_mfma_f32_16x16x32_bf16 v[62:65], v[114:117], v[54:57], v[62:65]
	s_waitcnt lgkmcnt(7)
	v_mfma_f32_16x16x32_bf16 v[66:69], v[118:121], v[54:57], v[66:69]
	s_waitcnt lgkmcnt(6)
	v_mfma_f32_16x16x32_bf16 v[70:73], v[122:125], v[54:57], v[70:73]
	ds_read_b128 v[74:77], v152 offset:192
	ds_read_b128 v[78:81], v152 offset:4800
	ds_read_b128 v[90:93], v152 offset:9408
	ds_read_b128 v[114:117], v152 offset:14016
	ds_read_b128 v[118:121], v152 offset:18624
	ds_read_b128 v[122:125], v153 offset:192
	s_waitcnt lgkmcnt(11)
	v_mfma_f32_16x16x32_bf16 v[14:17], v[126:129], v[58:61], v[14:17]
	s_waitcnt lgkmcnt(10)
	v_mfma_f32_16x16x32_bf16 v[18:21], v[130:133], v[58:61], v[18:21]
	s_waitcnt lgkmcnt(9)
	v_mfma_f32_16x16x32_bf16 v[22:25], v[134:137], v[58:61], v[22:25]
	s_waitcnt lgkmcnt(8)
	v_mfma_f32_16x16x32_bf16 v[62:65], v[140:143], v[58:61], v[62:65]
	s_waitcnt lgkmcnt(7)
	v_mfma_f32_16x16x32_bf16 v[66:69], v[144:147], v[58:61], v[66:69]
	s_waitcnt lgkmcnt(6)
	v_mfma_f32_16x16x32_bf16 v[70:73], v[148:151], v[58:61], v[70:73]
	v_add3_u32 v144, s26, v172, v4
	ds_read_b128 v[126:129], v144
	ds_read_b128 v[130:133], v144 offset:4608
	ds_read_b128 v[134:137], v144 offset:9216
	ds_read_b128 v[140:143], v144 offset:13824
	ds_read_b128 v[144:147], v144 offset:18432
	s_waitcnt lgkmcnt(10)
	v_mfma_f32_16x16x32_bf16 v[148:151], v[74:77], v[110:113], v[14:17]
	s_waitcnt lgkmcnt(9)
	v_mfma_f32_16x16x32_bf16 v[152:155], v[78:81], v[110:113], v[18:21]
	s_waitcnt lgkmcnt(8)
	v_mfma_f32_16x16x32_bf16 v[168:171], v[90:93], v[110:113], v[22:25]
	s_waitcnt lgkmcnt(7)
	v_mfma_f32_16x16x32_bf16 v[78:81], v[114:117], v[110:113], v[62:65]
	s_waitcnt lgkmcnt(6)
	v_mfma_f32_16x16x32_bf16 v[74:77], v[118:121], v[110:113], v[66:69]
	s_waitcnt lgkmcnt(5)
	v_mfma_f32_16x16x32_bf16 v[70:73], v[122:125], v[110:113], v[70:73]
	v_add3_u32 v184, s26, v4, v172
	ds_read_b128 v[18:21], v184 offset:64
	ds_read_b128 v[22:25], v184 offset:4672
	ds_read_b128 v[62:65], v184 offset:9280
	ds_read_b128 v[66:69], v184 offset:13888
	ds_read_b128 v[90:93], v184 offset:18496
	v_lshl_or_b32 v14, s38, 7, v83
	v_xad_u32 v15, v14, -1, s78
	v_cndmask_b32_e64 v14, v15, v14, s[4:5]
	v_add_u32_e32 v14, s48, v14
	v_mad_i64_i32 v[180:181], s[26:27], v14, s86, v[84:85]
	s_waitcnt lgkmcnt(9)
	v_mfma_f32_16x16x32_bf16 v[114:117], v[126:129], v[10:13], 0
	s_waitcnt lgkmcnt(8)
	v_mfma_f32_16x16x32_bf16 v[118:121], v[130:133], v[10:13], 0
	s_waitcnt lgkmcnt(7)
	v_mfma_f32_16x16x32_bf16 v[122:125], v[134:137], v[10:13], 0
	s_waitcnt lgkmcnt(6)
	v_mfma_f32_16x16x32_bf16 v[126:129], v[140:143], v[10:13], 0
	s_waitcnt lgkmcnt(5)
	v_mfma_f32_16x16x32_bf16 v[130:133], v[144:147], v[10:13], 0
	global_load_dwordx4 v[10:13], v[180:181], off
	global_load_dwordx4 v[14:17], v[180:181], off offset:64
	ds_read_b128 v[134:137], v184 offset:128
	ds_read_b128 v[140:143], v184 offset:4736
	ds_read_b128 v[144:147], v184 offset:9344
	ds_read_b128 v[172:175], v184 offset:13952
	ds_read_b128 v[176:179], v184 offset:18560
	s_waitcnt lgkmcnt(9)
	v_mfma_f32_16x16x32_bf16 v[114:117], v[18:21], v[54:57], v[114:117]
	s_waitcnt lgkmcnt(8)
	v_mfma_f32_16x16x32_bf16 v[118:121], v[22:25], v[54:57], v[118:121]
	global_load_dwordx4 v[18:21], v[180:181], off offset:128
	global_load_dwordx4 v[22:25], v[180:181], off offset:192
	s_waitcnt lgkmcnt(7)
	v_mfma_f32_16x16x32_bf16 v[62:65], v[62:65], v[54:57], v[122:125]
	s_waitcnt lgkmcnt(6)
	v_mfma_f32_16x16x32_bf16 v[66:69], v[66:69], v[54:57], v[126:129]
	s_waitcnt lgkmcnt(5)
	v_mfma_f32_16x16x32_bf16 v[54:57], v[90:93], v[54:57], v[130:133]
	ds_read_b128 v[122:125], v184 offset:192
	ds_read_b128 v[126:129], v184 offset:4800
	s_nop 0
	ds_read_b128 v[130:133], v184 offset:9408
	ds_read_b128 v[180:183], v184 offset:14016
	ds_read_b128 v[184:187], v184 offset:18624
	s_waitcnt lgkmcnt(9)
	v_mfma_f32_16x16x32_bf16 v[114:117], v[134:137], v[58:61], v[114:117]
	s_waitcnt lgkmcnt(7)
	v_mfma_f32_16x16x32_bf16 v[134:137], v[144:147], v[58:61], v[62:65]
	s_nop 2
	v_cndmask_b32_e64 v62, v188, v109, s[4:5]
	v_ashrrev_i32_e32 v63, 31, v62
	v_lshl_add_u64 v[62:63], s[0:1], 0, v[62:63]
	v_lshlrev_b64 v[62:63], 11, v[62:63]
	v_lshl_add_u64 v[62:63], v[86:87], 0, v[62:63]
	v_mfma_f32_16x16x32_bf16 v[118:121], v[140:143], v[58:61], v[118:121]
	global_store_dwordx4 v[62:63], v[50:53], off sc1
	global_store_dwordx4 v[62:63], v[46:49], off offset:64 sc1
	s_waitcnt lgkmcnt(6)
	v_mfma_f32_16x16x32_bf16 v[140:143], v[172:175], v[58:61], v[66:69]
	s_waitcnt lgkmcnt(5)
	v_mfma_f32_16x16x32_bf16 v[144:147], v[176:179], v[58:61], v[54:57]
	v_add3_u32 v60, s25, v95, v96
	v_add3_u32 v62, s19, v97, v107
	v_lshl_add_u32 v109, v82, 2, s36
	ds_read_b64_tr_b16 v[50:51], v60
	ds_read_b64_tr_b16 v[46:47], v60 offset:32
	ds_read_b64_tr_b16 v[54:55], v60 offset:64
	ds_read_b64_tr_b16 v[58:59], v60 offset:96
	ds_read_b64_tr_b16 v[52:53], v60 offset:2560
	ds_read_b64_tr_b16 v[48:49], v60 offset:2592
	ds_read_b64_tr_b16 v[56:57], v60 offset:2624
	ds_read_b64_tr_b16 v[60:61], v60 offset:2656
	ds_read_b64_tr_b16 v[92:93], v62 offset:192
	ds_read_b64_tr_b16 v[90:91], v62 offset:4800
	ds_read_b128 v[66:69], v109 offset:1536
	ds_read_b128 v[62:65], v109 offset:1600
	ds_read_b128 v[172:175], v109
	ds_read_b128 v[176:179], v109 offset:64
	ds_read_b128 v[188:191], v109 offset:128
	ds_read_b128 v[192:195], v109 offset:192
	ds_read_b128 v[196:199], v109 offset:256
	ds_read_b128 v[200:203], v109 offset:320
	s_waitcnt lgkmcnt(14)
	v_mfma_f32_16x16x32_bf16 v[114:117], v[122:125], v[110:113], v[114:117]
	v_mfma_f32_16x16x32_bf16 v[118:121], v[126:129], v[110:113], v[118:121]
	v_mfma_f32_16x16x32_bf16 v[122:125], v[130:133], v[110:113], v[134:137]
	v_mfma_f32_16x16x32_bf16 v[126:129], v[180:183], v[110:113], v[140:143]
	v_mfma_f32_16x16x32_bf16 v[110:113], v[184:187], v[110:113], v[144:147]
	s_waitcnt lgkmcnt(2)
	s_nop 1
	v_fmamk_f32 v144, v88, 0xbfb8aa3b, v192
	v_fmamk_f32 v145, v88, 0xbfb8aa3b, v193
	v_exp_f32_e32 v144, v144
	v_exp_f32_e32 v145, v145
	v_fmamk_f32 v146, v88, 0xbfb8aa3b, v194
	v_exp_f32_e32 v146, v146
	v_fmac_f32_e32 v195, 0xbfb8aa3b, v88
	v_sub_f32_e32 v130, v205, v88
	v_exp_f32_e32 v147, v195
	v_mul_f32_e32 v130, 0x3fb8aa3b, v130
	v_sub_f32_e32 v131, v205, v204
	v_mul_f32_e32 v78, v78, v144
	v_mul_f32_e32 v79, v79, v145
	s_waitcnt lgkmcnt(1)
	v_fmamk_f32 v144, v88, 0xbfb8aa3b, v196
	v_fmamk_f32 v145, v88, 0xbfb8aa3b, v197
	v_exp_f32_e32 v130, v130
	v_mul_f32_e32 v131, 0x3fb8aa3b, v131
	v_exp_f32_e32 v144, v144
	v_exp_f32_e32 v145, v145
	v_exp_f32_e32 v132, v131
	v_mul_f32_e32 v80, v80, v146
	v_fmamk_f32 v146, v88, 0xbfb8aa3b, v198
	v_fmac_f32_e32 v199, 0xbfb8aa3b, v88
	v_mul_f32_e32 v81, v81, v147
	v_exp_f32_e32 v146, v146
	v_exp_f32_e32 v147, v199
	v_pk_mul_f32 v[116:117], v[130:131], v[116:117] op_sel_hi:[0,1]
	v_pk_mul_f32 v[114:115], v[130:131], v[114:115] op_sel_hi:[0,1]
	v_pk_mul_f32 v[120:121], v[130:131], v[120:121] op_sel_hi:[0,1]
	v_pk_mul_f32 v[118:119], v[130:131], v[118:119] op_sel_hi:[0,1]
	v_pk_mul_f32 v[124:125], v[130:131], v[124:125] op_sel_hi:[0,1]
	v_pk_mul_f32 v[122:123], v[130:131], v[122:123] op_sel_hi:[0,1]
	v_pk_mul_f32 v[128:129], v[130:131], v[128:129] op_sel_hi:[0,1]
	v_pk_mul_f32 v[126:127], v[130:131], v[126:127] op_sel_hi:[0,1]
	v_pk_mul_f32 v[112:113], v[130:131], v[112:113] op_sel_hi:[0,1]
	v_pk_mul_f32 v[110:111], v[130:131], v[110:111] op_sel_hi:[0,1]
	v_fmamk_f32 v130, v88, 0xbfb8aa3b, v172
	v_mul_f32_e32 v144, v74, v144
	v_mul_f32_e32 v145, v75, v145
	s_waitcnt lgkmcnt(0)
	v_fmamk_f32 v74, v88, 0xbfb8aa3b, v200
	v_fmamk_f32 v75, v88, 0xbfb8aa3b, v201
	v_pk_mul_f32 v[44:45], v[44:45], v[132:133] op_sel_hi:[1,0]
	v_pk_mul_f32 v[42:43], v[42:43], v[132:133] op_sel_hi:[1,0]
	v_pk_mul_f32 v[40:41], v[40:41], v[132:133] op_sel_hi:[1,0]
	v_pk_mul_f32 v[38:39], v[38:39], v[132:133] op_sel_hi:[1,0]
	v_pk_mul_f32 v[36:37], v[36:37], v[132:133] op_sel_hi:[1,0]
	v_pk_mul_f32 v[34:35], v[34:35], v[132:133] op_sel_hi:[1,0]
	v_pk_mul_f32 v[32:33], v[32:33], v[132:133] op_sel_hi:[1,0]
	v_pk_mul_f32 v[30:31], v[30:31], v[132:133] op_sel_hi:[1,0]
	v_pk_mul_f32 v[28:29], v[28:29], v[132:133] op_sel_hi:[1,0]
	v_pk_mul_f32 v[26:27], v[26:27], v[132:133] op_sel_hi:[1,0]
	v_exp_f32_e32 v130, v130
	v_fmamk_f32 v132, v88, 0xbfb8aa3b, v174
	v_exp_f32_e32 v74, v74
	v_exp_f32_e32 v75, v75
	v_fmac_f32_e32 v203, 0xbfb8aa3b, v88
	v_fmamk_f32 v131, v88, 0xbfb8aa3b, v173
	v_exp_f32_e32 v132, v132
	v_mul_f32_e32 v146, v76, v146
	v_mul_f32_e32 v147, v77, v147
	v_fmamk_f32 v76, v88, 0xbfb8aa3b, v202
	v_exp_f32_e32 v77, v203
	v_exp_f32_e32 v131, v131
	v_exp_f32_e32 v76, v76
	v_fmac_f32_e32 v175, 0xbfb8aa3b, v88
	v_fmamk_f32 v134, v88, 0xbfb8aa3b, v176
	v_fmamk_f32 v135, v88, 0xbfb8aa3b, v177
	v_fmamk_f32 v136, v88, 0xbfb8aa3b, v178
	v_fmac_f32_e32 v179, 0xbfb8aa3b, v88
	v_fmamk_f32 v140, v88, 0xbfb8aa3b, v188
	v_fmamk_f32 v141, v88, 0xbfb8aa3b, v189
	v_fmamk_f32 v142, v88, 0xbfb8aa3b, v190
	v_fmac_f32_e32 v191, 0xbfb8aa3b, v88
	v_exp_f32_e32 v133, v175
	v_mul_f32_e32 v130, v148, v130
	v_exp_f32_e32 v134, v134
	v_exp_f32_e32 v135, v135
	v_exp_f32_e32 v136, v136
	v_exp_f32_e32 v137, v179
	v_exp_f32_e32 v140, v140
	v_exp_f32_e32 v141, v141
	v_exp_f32_e32 v142, v142
	v_exp_f32_e32 v143, v191
	v_mul_f32_e32 v88, v70, v74
	v_mul_f32_e32 v148, v71, v75
	v_mul_f32_e32 v132, v150, v132
	v_mul_f32_e32 v150, v73, v77
	v_cvt_pk_bf16_f32 v77, v80, v81
	v_cvt_pk_bf16_f32 v80, v88, s0
	v_cvt_pk_bf16_f32 v81, v148, s0
	v_mul_f32_e32 v131, v149, v131
	v_mul_f32_e32 v149, v72, v76
	v_cndmask_b32_e64 v80, v80, 0, s[6:7]
	v_cndmask_b32_e64 v81, 0, v81, s[8:9]
	v_perm_b32 v80, v81, v80, s89
	v_cvt_pk_bf16_f32 v81, v149, s0
	v_cvt_pk_bf16_f32 v88, v150, s0
	v_mul_f32_e32 v133, v151, v133
	v_mul_f32_e32 v134, v152, v134
	v_mul_f32_e32 v135, v153, v135
	v_mul_f32_e32 v136, v154, v136
	v_mul_f32_e32 v137, v155, v137
	v_mul_f32_e32 v140, v168, v140
	v_mul_f32_e32 v141, v169, v141
	v_mul_f32_e32 v142, v170, v142
	v_mul_f32_e32 v143, v171, v143
	v_cndmask_b32_e64 v81, v81, 0, s[10:11]
	v_cndmask_b32_e64 v88, v88, 0, s[12:13]
	v_cvt_pk_bf16_f32 v70, v130, v131
	v_cvt_pk_bf16_f32 v71, v132, v133
	v_cvt_pk_bf16_f32 v72, v134, v135
	v_cvt_pk_bf16_f32 v73, v136, v137
	v_cvt_pk_bf16_f32 v74, v140, v141
	v_cvt_pk_bf16_f32 v75, v142, v143
	v_cvt_pk_bf16_f32 v76, v78, v79
	v_cvt_pk_bf16_f32 v78, v144, v145
	v_cvt_pk_bf16_f32 v79, v146, v147
	v_perm_b32 v81, v88, v81, s89
	v_add3_u32 v88, s25, v98, v107
	ds_read_b64_tr_b16 v[130:131], v88
	ds_read_b64_tr_b16 v[134:135], v88 offset:32
	ds_read_b64_tr_b16 v[140:141], v88 offset:64
	ds_read_b64_tr_b16 v[144:145], v88 offset:96
	ds_read_b64_tr_b16 v[132:133], v88 offset:2560
	ds_read_b64_tr_b16 v[136:137], v88 offset:2592
	ds_read_b64_tr_b16 v[142:143], v88 offset:2624
	ds_read_b64_tr_b16 v[146:147], v88 offset:2656
	v_add3_u32 v88, s19, v99, v107
	ds_read_b64_tr_b16 v[176:177], v88 offset:192
	ds_read_b64_tr_b16 v[178:179], v88 offset:4800
	ds_read_b128 v[148:151], v109 offset:1664
	ds_read_b128 v[152:155], v109 offset:1728
	v_lshlrev_b32_e32 v88, 16, v92
	v_mul_f32_e32 v66, v66, v88
	v_and_b32_e32 v88, 0xffff0000, v92
	v_mul_f32_e32 v67, v67, v88
	v_cvt_pk_bf16_f32 v66, v66, v67
	v_lshlrev_b32_e32 v67, 16, v93
	v_mul_f32_e32 v67, v68, v67
	v_and_b32_e32 v68, 0xffff0000, v93
	v_mul_f32_e32 v68, v69, v68
	v_cvt_pk_bf16_f32 v67, v67, v68
	v_lshlrev_b32_e32 v68, 16, v90
	v_mul_f32_e32 v62, v62, v68
	v_and_b32_e32 v68, 0xffff0000, v90
	v_mul_f32_e32 v63, v63, v68
	v_cvt_pk_bf16_f32 v68, v62, v63
	v_lshlrev_b32_e32 v62, 16, v91
	v_and_b32_e32 v63, 0xffff0000, v91
	v_mul_f32_e32 v62, v64, v62
	v_mul_f32_e32 v63, v65, v63
	v_cvt_pk_bf16_f32 v69, v62, v63
	v_mfma_f32_16x16x32_bf16 v[114:117], v[50:53], v[70:73], v[114:117]
	s_nop 0
	v_mfma_f32_16x16x32_bf16 v[42:45], v[66:69], v[50:53], v[42:45]
	v_mfma_f32_16x16x32_bf16 v[38:41], v[66:69], v[46:49], v[38:41]
	v_mfma_f32_16x16x32_bf16 v[34:37], v[66:69], v[54:57], v[34:37]
	v_mfma_f32_16x16x32_bf16 v[30:33], v[66:69], v[58:61], v[30:33]
	v_mfma_f32_16x16x32_bf16 v[26:29], v[66:69], v[6:9], v[26:29]
	v_mfma_f32_16x16x32_bf16 v[118:121], v[46:49], v[70:73], v[118:121]
	v_mfma_f32_16x16x32_bf16 v[122:125], v[54:57], v[70:73], v[122:125]
	v_mfma_f32_16x16x32_bf16 v[126:129], v[58:61], v[70:73], v[126:129]
	v_mfma_f32_16x16x32_bf16 v[70:73], v[6:9], v[70:73], v[110:113]
	v_add3_u32 v46, s25, v100, v107
	ds_read_b64_tr_b16 v[62:63], v46
	ds_read_b64_tr_b16 v[66:67], v46 offset:32
	ds_read_b64_tr_b16 v[90:91], v46 offset:64
	ds_read_b64_tr_b16 v[110:111], v46 offset:96
	ds_read_b64_tr_b16 v[64:65], v46 offset:2560
	ds_read_b64_tr_b16 v[68:69], v46 offset:2592
	ds_read_b64_tr_b16 v[92:93], v46 offset:2624
	ds_read_b64_tr_b16 v[112:113], v46 offset:2656
	v_add3_u32 v46, s19, v101, v107
	ds_read_b64_tr_b16 v[180:181], v46 offset:192
	ds_read_b64_tr_b16 v[182:183], v46 offset:4800
	ds_read_b128 v[168:171], v109 offset:1792
	ds_read_b128 v[172:175], v109 offset:1856
	s_waitcnt lgkmcnt(14)
	v_lshlrev_b32_e32 v50, 16, v176
	v_and_b32_e32 v51, 0xffff0000, v176
	s_waitcnt lgkmcnt(13)
	v_mul_f32_e32 v50, v148, v50
	v_mul_f32_e32 v51, v149, v51
	v_cvt_pk_bf16_f32 v50, v50, v51
	v_lshlrev_b32_e32 v51, 16, v177
	v_and_b32_e32 v52, 0xffff0000, v177
	v_mul_f32_e32 v51, v150, v51
	v_mul_f32_e32 v52, v151, v52
	v_cvt_pk_bf16_f32 v51, v51, v52
	v_lshlrev_b32_e32 v52, 16, v178
	v_and_b32_e32 v53, 0xffff0000, v178
	s_waitcnt lgkmcnt(12)
	v_mul_f32_e32 v52, v152, v52
	v_mul_f32_e32 v53, v153, v53
	v_cvt_pk_bf16_f32 v52, v52, v53
	v_lshlrev_b32_e32 v53, 16, v179
	v_and_b32_e32 v58, 0xffff0000, v179
	v_mul_f32_e32 v53, v154, v53
	v_mul_f32_e32 v58, v155, v58
	v_cvt_pk_bf16_f32 v53, v53, v58
	v_mfma_f32_16x16x32_bf16 v[46:49], v[130:133], v[74:77], v[114:117]
	v_mfma_f32_16x16x32_bf16 v[54:57], v[134:137], v[74:77], v[118:121]
	v_mfma_f32_16x16x32_bf16 v[42:45], v[50:53], v[130:133], v[42:45]
	v_mfma_f32_16x16x32_bf16 v[38:41], v[50:53], v[134:137], v[38:41]
	v_mfma_f32_16x16x32_bf16 v[34:37], v[50:53], v[140:143], v[34:37]
	v_mfma_f32_16x16x32_bf16 v[30:33], v[50:53], v[144:147], v[30:33]
	v_mfma_f32_16x16x32_bf16 v[26:29], v[50:53], v[6:9], v[26:29]
	v_mfma_f32_16x16x32_bf16 v[114:117], v[140:143], v[74:77], v[122:125]
	v_mfma_f32_16x16x32_bf16 v[118:121], v[144:147], v[74:77], v[126:129]
	v_mfma_f32_16x16x32_bf16 v[70:73], v[6:9], v[74:77], v[70:73]
	v_add3_u32 v50, s25, v102, v107
	ds_read_b64_tr_b16 v[74:75], v50
	ds_read_b64_tr_b16 v[122:123], v50 offset:32
	ds_read_b64_tr_b16 v[126:127], v50 offset:64
	ds_read_b64_tr_b16 v[130:131], v50 offset:96
	ds_read_b64_tr_b16 v[76:77], v50 offset:2560
	ds_read_b64_tr_b16 v[124:125], v50 offset:2592
	ds_read_b64_tr_b16 v[128:129], v50 offset:2624
	ds_read_b64_tr_b16 v[132:133], v50 offset:2656
	v_add3_u32 v50, s19, v103, v107
	ds_read_b64_tr_b16 v[144:145], v50 offset:192
	ds_read_b64_tr_b16 v[146:147], v50 offset:4800
	ds_read_b128 v[134:137], v109 offset:1920
	ds_read_b128 v[140:143], v109 offset:1984
	v_mfma_f32_16x16x32_bf16 v[70:73], v[6:9], v[78:81], v[70:73]
	s_waitcnt lgkmcnt(14)
	v_mfma_f32_16x16x32_bf16 v[50:53], v[62:65], v[78:81], v[46:49]
	v_mfma_f32_16x16x32_bf16 v[58:61], v[66:69], v[78:81], v[54:57]
	s_nop 4
	v_lshlrev_b32_e32 v71, 16, v180
	v_and_b32_e32 v72, 0xffff0000, v180
	s_waitcnt lgkmcnt(13)
	v_mul_f32_e32 v71, v168, v71
	v_mul_f32_e32 v72, v169, v72
	v_mfma_f32_16x16x32_bf16 v[46:49], v[90:93], v[78:81], v[114:117]
	v_mfma_f32_16x16x32_bf16 v[54:57], v[110:113], v[78:81], v[118:121]
	v_cvt_pk_bf16_f32 v78, v71, v72
	v_lshlrev_b32_e32 v71, 16, v181
	v_and_b32_e32 v72, 0xffff0000, v181
	v_mul_f32_e32 v71, v170, v71
	v_mul_f32_e32 v72, v171, v72
	v_cvt_pk_bf16_f32 v79, v71, v72
	v_lshlrev_b32_e32 v71, 16, v182
	v_and_b32_e32 v72, 0xffff0000, v182
	s_waitcnt lgkmcnt(12)
	v_mul_f32_e32 v71, v172, v71
	v_mul_f32_e32 v72, v173, v72
	v_cvt_pk_bf16_f32 v80, v71, v72
	v_lshlrev_b32_e32 v71, 16, v183
	v_and_b32_e32 v72, 0xffff0000, v183
	v_mul_f32_e32 v71, v174, v71
	v_mul_f32_e32 v72, v175, v72
	v_cvt_pk_bf16_f32 v81, v71, v72
	s_nop 1
	v_mfma_f32_16x16x32_bf16 v[42:45], v[78:81], v[62:65], v[42:45]
	v_mfma_f32_16x16x32_bf16 v[38:41], v[78:81], v[66:69], v[38:41]
	v_mfma_f32_16x16x32_bf16 v[34:37], v[78:81], v[90:93], v[34:37]
	v_mfma_f32_16x16x32_bf16 v[30:33], v[78:81], v[110:113], v[30:33]
	v_mfma_f32_16x16x32_bf16 v[26:29], v[78:81], v[6:9], v[26:29]
	s_waitcnt lgkmcnt(3)
	v_lshlrev_b32_e32 v62, 16, v144
	v_and_b32_e32 v63, 0xffff0000, v144
	s_waitcnt lgkmcnt(1)
	v_mul_f32_e32 v62, v134, v62
	v_mul_f32_e32 v63, v135, v63
	v_cvt_pk_bf16_f32 v62, v62, v63
	v_lshlrev_b32_e32 v63, 16, v145
	v_and_b32_e32 v64, 0xffff0000, v145
	v_mul_f32_e32 v63, v136, v63
	v_mul_f32_e32 v64, v137, v64
	v_cvt_pk_bf16_f32 v63, v63, v64
	v_lshlrev_b32_e32 v64, 16, v146
	v_and_b32_e32 v65, 0xffff0000, v146
	s_waitcnt lgkmcnt(0)
	v_mul_f32_e32 v64, v140, v64
	v_mul_f32_e32 v65, v141, v65
	v_cvt_pk_bf16_f32 v64, v64, v65
	v_lshlrev_b32_e32 v65, 16, v147
	v_and_b32_e32 v66, 0xffff0000, v147
	v_mul_f32_e32 v65, v142, v65
	v_mul_f32_e32 v66, v143, v66
	v_cvt_pk_bf16_f32 v65, v65, v66
	s_nop 1
	v_mfma_f32_16x16x32_bf16 v[42:45], v[62:65], v[74:77], v[42:45]
	v_mfma_f32_16x16x32_bf16 v[38:41], v[62:65], v[122:125], v[38:41]
	v_mfma_f32_16x16x32_bf16 v[34:37], v[62:65], v[126:129], v[34:37]
	v_mfma_f32_16x16x32_bf16 v[30:33], v[62:65], v[130:133], v[30:33]
	v_mfma_f32_16x16x32_bf16 v[26:29], v[62:65], v[6:9], v[26:29]
	s_xor_b32 s18, s18, 1
	s_mulk_i32 s18, 0x4a00
	s_add_i32 s25, s18, 0
	v_lshlrev_b32_e32 v63, 1, v82
	ds_bpermute_b32 v62, v104, v70
	v_add3_u32 v63, s25, v4, v63
	v_cvt_pk_bf16_f32 v64, v42, v43
	v_cvt_pk_bf16_f32 v65, v44, v45
	v_add_u32_e32 v66, 0x1c0c0, v63
	ds_write_b64 v66, v[64:65]
	v_cvt_pk_bf16_f32 v64, v38, v39
	v_cvt_pk_bf16_f32 v65, v40, v41
	v_add_u32_e32 v66, 0x1d2c0, v63
	ds_write_b64 v66, v[64:65]
	v_cvt_pk_bf16_f32 v64, v34, v35
	v_cvt_pk_bf16_f32 v65, v36, v37
	v_add_u32_e32 v66, 0x1e4c0, v63
	ds_write_b64 v66, v[64:65]
	v_cvt_pk_bf16_f32 v64, v30, v31
	v_cvt_pk_bf16_f32 v65, v32, v33
	v_add_u32_e32 v63, 0x1f6c0, v63
	ds_write_b64 v63, v[64:65]
	s_and_saveexec_b64 s[18:19], s[2:3]
	s_cbranch_execz .LBB0_422
	v_lshl_add_u32 v63, v82, 1, s25
	v_cvt_pk_bf16_f32 v64, v26, v27
	v_cvt_pk_bf16_f32 v65, v28, v29
	v_add_u32_e32 v63, 0x208c0, v63
	ds_write_b64 v63, v[64:65]
	s_branch .LBB0_422
.LBB0_425:
	s_add_i32 s2, s78, 0xffffff80
	v_or_b32_e32 v4, s2, v83
	v_xad_u32 v6, v4, -1, s78
	v_cndmask_b32_e64 v6, v6, v4, s[4:5]
	v_ashrrev_i32_e32 v7, 31, v6
	v_lshl_add_u64 v[6:7], s[0:1], 0, v[6:7]
	v_lshlrev_b64 v[6:7], 11, v[6:7]
	v_lshl_add_u64 v[6:7], s[42:43], 0, v[6:7]
	s_lshl_b32 s68, s17, 1
	v_lshl_add_u64 v[6:7], v[6:7], 0, s[68:69]
	s_lshl_b32 s68, s21, 1
	v_lshl_add_u64 v[6:7], v[6:7], 0, s[68:69]
	v_lshl_add_u64 v[2:3], v[2:3], 1, v[6:7]
	s_and_b64 vcc, exec, s[46:47]
	global_store_dwordx4 v[2:3], v[50:53], off sc1
	global_store_dwordx4 v[2:3], v[46:49], off offset:64 sc1
	s_cbranch_vccz .LBB0_429
	s_waitcnt vmcnt(6)
	v_mbcnt_lo_u32_b32 v16, -1, 0
	v_mbcnt_hi_u32_b32 v16, -1, v16
	s_ashr_i32 s17, s16, 31
	v_lshlrev_b32_e32 v3, 1, v16
	v_ashrrev_i32_e32 v2, 2, v16
	v_and_b32_e32 v3, 24, v3
	v_and_b32_e32 v4, 3, v16
	s_lshl_b64 s[0:1], s[16:17], 16
	v_and_b32_e32 v2, -4, v2
	v_or3_b32 v3, v4, v3, s21
	s_add_u32 s0, s76, s0
	v_lshlrev_b32_e32 v4, 2, v3
	v_ashrrev_i32_e32 v3, 31, v2
	s_addc_u32 s1, s77, s1
	v_lshlrev_b64 v[6:7], 9, v[2:3]
	v_lshl_add_u64 v[6:7], s[0:1], 0, v[6:7]
	v_lshl_add_u64 v[6:7], v[6:7], 0, v[4:5]
	s_mov_b64 s[0:1], 0xc000
	v_lshl_add_u64 v[8:9], v[6:7], 0, s[0:1]
	s_mov_b32 s0, 0xc000
	v_add_co_u32_e32 v10, vcc, s0, v6
	s_mov_b64 s[0:1], 0xc200
	s_nop 0
	v_addc_co_u32_e32 v11, vcc, 0, v7, vcc
	v_lshl_add_u64 v[12:13], v[6:7], 0, s[0:1]
	s_mov_b64 s[0:1], 0xc400
	v_and_or_b32 v4, v16, 15, s31
	v_lshl_add_u64 v[14:15], v[6:7], 0, s[0:1]
	s_mov_b64 s[0:1], 0xc600
	v_cmp_eq_u32_e32 vcc, 0, v4
	global_store_dword v[10:11], v42, off
	global_store_dword v[10:11], v43, off offset:512
	global_store_dword v[10:11], v44, off offset:1024
	v_lshl_add_u64 v[6:7], v[6:7], 0, s[0:1]
	global_store_dword v[10:11], v45, off offset:1536
	global_store_dword v[8:9], v38, off offset:16
	global_store_dword v[12:13], v39, off offset:16
	global_store_dword v[14:15], v40, off offset:16
	global_store_dword v[6:7], v41, off offset:16
	global_store_dword v[8:9], v34, off offset:128
	global_store_dword v[12:13], v35, off offset:128
	global_store_dword v[14:15], v36, off offset:128
	global_store_dword v[6:7], v37, off offset:128
	global_store_dword v[8:9], v30, off offset:144
	global_store_dword v[12:13], v31, off offset:144
	global_store_dword v[14:15], v32, off offset:144
	global_store_dword v[6:7], v33, off offset:144
	s_and_saveexec_b64 s[0:1], vcc
	s_cbranch_execz .LBB0_428
	s_lshl_b64 s[2:3], s[16:17], 9
	v_readlane_b32 s4, v254, 26
	s_add_u32 s2, s4, s2
	v_readlane_b32 s4, v254, 27
	s_addc_u32 s3, s4, s3
	v_lshl_add_u64 v[2:3], v[2:3], 2, s[2:3]
	global_store_dwordx4 v[2:3], v[26:29], off offset:384 sc1
